# GEMM core without per-phase s_setprio flips
# speedup vs baseline: 1.0282x; 1.0084x over previous
.Lg8_p2_loop:
	ds_read_b128 v[160:163], v199 offset:0
	ds_read_b128 v[164:167], v201 offset:0
	ds_read_b128 v[172:175], v199 offset:2048
	ds_read_b128 v[176:179], v201 offset:2048
	ds_read_b128 v[128:131], v170 offset:0
	ds_read_b128 v[132:135], v197 offset:0
	ds_read_b128 v[136:139], v170 offset:2048
	ds_read_b128 v[140:143], v197 offset:2048
	ds_read_b128 v[144:147], v170 offset:4096
	ds_read_b128 v[148:151], v197 offset:4096
	ds_read_b128 v[152:155], v170 offset:6144
	ds_read_b128 v[156:159], v197 offset:6144
	s_add_u32 m0, s99, 0x14000
	s_nop 0
	global_load_lds_dwordx4 v205, s[58:59]
	s_add_u32 m0, s99, 0x16000
	s_nop 0
	global_load_lds_dwordx4 v206, s[58:59]
	s_waitcnt lgkmcnt(8)
	s_barrier
	s_waitcnt lgkmcnt(0)
	v_mfma_f32_16x16x32_bf16 v[112:115], v[128:131], v[160:163], v[112:115]
	v_mfma_f32_16x16x32_bf16 v[112:115], v[132:135], v[164:167], v[112:115]
	v_mfma_f32_16x16x32_bf16 v[116:119], v[128:131], v[172:175], v[116:119]
	v_mfma_f32_16x16x32_bf16 v[116:119], v[132:135], v[176:179], v[116:119]
	v_mfma_f32_16x16x32_bf16 v[120:123], v[136:139], v[160:163], v[120:123]
	v_mfma_f32_16x16x32_bf16 v[120:123], v[140:143], v[164:167], v[120:123]
	v_mfma_f32_16x16x32_bf16 v[124:127], v[136:139], v[172:175], v[124:127]
	v_mfma_f32_16x16x32_bf16 v[124:127], v[140:143], v[176:179], v[124:127]
	v_mfma_f32_16x16x32_bf16 v[80:83], v[144:147], v[160:163], v[80:83]
	v_mfma_f32_16x16x32_bf16 v[80:83], v[148:151], v[164:167], v[80:83]
	v_mfma_f32_16x16x32_bf16 v[84:87], v[144:147], v[172:175], v[84:87]
	v_mfma_f32_16x16x32_bf16 v[84:87], v[148:151], v[176:179], v[84:87]
	v_mfma_f32_16x16x32_bf16 v[88:91], v[152:155], v[160:163], v[88:91]
	v_mfma_f32_16x16x32_bf16 v[88:91], v[156:159], v[164:167], v[88:91]
	v_mfma_f32_16x16x32_bf16 v[92:95], v[152:155], v[172:175], v[92:95]
	v_mfma_f32_16x16x32_bf16 v[92:95], v[156:159], v[176:179], v[92:95]
	s_barrier
	ds_read_b128 v[180:183], v199 offset:16384
	ds_read_b128 v[184:187], v201 offset:16384
	ds_read_b128 v[188:191], v199 offset:18432
	ds_read_b128 v[192:195], v201 offset:18432
	s_add_u32 s56, s56, 0x80
	s_addc_u32 s57, s57, 0
	s_add_u32 m0, s99, 0x8000
	s_nop 0
	global_load_lds_dwordx4 v207, s[56:57]
	s_add_u32 m0, s99, 0xa000
	s_nop 0
	global_load_lds_dwordx4 v229, s[56:57]
	s_barrier
	s_waitcnt lgkmcnt(0)
	v_mfma_f32_16x16x32_bf16 v[48:51], v[128:131], v[180:183], v[48:51]
	v_mfma_f32_16x16x32_bf16 v[48:51], v[132:135], v[184:187], v[48:51]
	v_mfma_f32_16x16x32_bf16 v[52:55], v[128:131], v[188:191], v[52:55]
	v_mfma_f32_16x16x32_bf16 v[52:55], v[132:135], v[192:195], v[52:55]
	v_mfma_f32_16x16x32_bf16 v[56:59], v[136:139], v[180:183], v[56:59]
	v_mfma_f32_16x16x32_bf16 v[56:59], v[140:143], v[184:187], v[56:59]
	v_mfma_f32_16x16x32_bf16 v[60:63], v[136:139], v[188:191], v[60:63]
	v_mfma_f32_16x16x32_bf16 v[60:63], v[140:143], v[192:195], v[60:63]
	v_mfma_f32_16x16x32_bf16 v[16:19], v[144:147], v[180:183], v[16:19]
	v_mfma_f32_16x16x32_bf16 v[16:19], v[148:151], v[184:187], v[16:19]
	v_mfma_f32_16x16x32_bf16 v[20:23], v[144:147], v[188:191], v[20:23]
	v_mfma_f32_16x16x32_bf16 v[20:23], v[148:151], v[192:195], v[20:23]
	v_mfma_f32_16x16x32_bf16 v[24:27], v[152:155], v[180:183], v[24:27]
	v_mfma_f32_16x16x32_bf16 v[24:27], v[156:159], v[184:187], v[24:27]
	v_mfma_f32_16x16x32_bf16 v[28:31], v[152:155], v[188:191], v[28:31]
	v_mfma_f32_16x16x32_bf16 v[28:31], v[156:159], v[192:195], v[28:31]
	s_barrier
	ds_read_b128 v[128:131], v170 offset:16384
	ds_read_b128 v[132:135], v197 offset:16384
	ds_read_b128 v[136:139], v170 offset:18432
	ds_read_b128 v[140:143], v197 offset:18432
	ds_read_b128 v[144:147], v170 offset:20480
	ds_read_b128 v[148:151], v197 offset:20480
	ds_read_b128 v[152:155], v170 offset:22528
	ds_read_b128 v[156:159], v197 offset:22528
	s_add_u32 s58, s58, 0x80
	s_addc_u32 s59, s59, 0
	s_add_u32 m0, s99, 0x0
	s_nop 0
	global_load_lds_dwordx4 v203, s[58:59]
	s_add_u32 m0, s99, 0x2000
	s_nop 0
	global_load_lds_dwordx4 v204, s[58:59]
	s_barrier
	s_waitcnt lgkmcnt(0)
	v_mfma_f32_16x16x32_bf16 v[96:99], v[128:131], v[160:163], v[96:99]
	v_mfma_f32_16x16x32_bf16 v[96:99], v[132:135], v[164:167], v[96:99]
	v_mfma_f32_16x16x32_bf16 v[100:103], v[128:131], v[172:175], v[100:103]
	v_mfma_f32_16x16x32_bf16 v[100:103], v[132:135], v[176:179], v[100:103]
	v_mfma_f32_16x16x32_bf16 v[104:107], v[136:139], v[160:163], v[104:107]
	v_mfma_f32_16x16x32_bf16 v[104:107], v[140:143], v[164:167], v[104:107]
	v_mfma_f32_16x16x32_bf16 v[108:111], v[136:139], v[172:175], v[108:111]
	v_mfma_f32_16x16x32_bf16 v[108:111], v[140:143], v[176:179], v[108:111]
	v_mfma_f32_16x16x32_bf16 v[64:67], v[144:147], v[160:163], v[64:67]
	v_mfma_f32_16x16x32_bf16 v[64:67], v[148:151], v[164:167], v[64:67]
	v_mfma_f32_16x16x32_bf16 v[68:71], v[144:147], v[172:175], v[68:71]
	v_mfma_f32_16x16x32_bf16 v[68:71], v[148:151], v[176:179], v[68:71]
	v_mfma_f32_16x16x32_bf16 v[72:75], v[152:155], v[160:163], v[72:75]
	v_mfma_f32_16x16x32_bf16 v[72:75], v[156:159], v[164:167], v[72:75]
	v_mfma_f32_16x16x32_bf16 v[76:79], v[152:155], v[172:175], v[76:79]
	v_mfma_f32_16x16x32_bf16 v[76:79], v[156:159], v[176:179], v[76:79]
	s_barrier
	s_add_u32 m0, s99, 0xc000
	s_nop 0
	global_load_lds_dwordx4 v230, s[56:57]
	s_add_u32 m0, s99, 0xe000
	s_nop 0
	global_load_lds_dwordx4 v231, s[56:57]
	s_waitcnt vmcnt(6)
	s_barrier
	v_mfma_f32_16x16x32_bf16 v[32:35], v[128:131], v[180:183], v[32:35]
	v_mfma_f32_16x16x32_bf16 v[32:35], v[132:135], v[184:187], v[32:35]
	v_mfma_f32_16x16x32_bf16 v[36:39], v[128:131], v[188:191], v[36:39]
	v_mfma_f32_16x16x32_bf16 v[36:39], v[132:135], v[192:195], v[36:39]
	v_mfma_f32_16x16x32_bf16 v[40:43], v[136:139], v[180:183], v[40:43]
	v_mfma_f32_16x16x32_bf16 v[40:43], v[140:143], v[184:187], v[40:43]
	v_mfma_f32_16x16x32_bf16 v[44:47], v[136:139], v[188:191], v[44:47]
	v_mfma_f32_16x16x32_bf16 v[44:47], v[140:143], v[192:195], v[44:47]
	v_mfma_f32_16x16x32_bf16 v[0:3], v[144:147], v[180:183], v[0:3]
	v_mfma_f32_16x16x32_bf16 v[0:3], v[148:151], v[184:187], v[0:3]
	v_mfma_f32_16x16x32_bf16 v[4:7], v[144:147], v[188:191], v[4:7]
	v_mfma_f32_16x16x32_bf16 v[4:7], v[148:151], v[192:195], v[4:7]
	v_mfma_f32_16x16x32_bf16 v[8:11], v[152:155], v[180:183], v[8:11]
	v_mfma_f32_16x16x32_bf16 v[8:11], v[156:159], v[184:187], v[8:11]
	v_mfma_f32_16x16x32_bf16 v[12:15], v[152:155], v[188:191], v[12:15]
	v_mfma_f32_16x16x32_bf16 v[12:15], v[156:159], v[192:195], v[12:15]
	s_barrier
	ds_read_b128 v[160:163], v200 offset:0
	ds_read_b128 v[164:167], v202 offset:0
	ds_read_b128 v[172:175], v200 offset:2048
	ds_read_b128 v[176:179], v202 offset:2048
	ds_read_b128 v[128:131], v196 offset:0
	ds_read_b128 v[132:135], v198 offset:0
	ds_read_b128 v[136:139], v196 offset:2048
	ds_read_b128 v[140:143], v198 offset:2048
	ds_read_b128 v[144:147], v196 offset:4096
	ds_read_b128 v[148:151], v198 offset:4096
	ds_read_b128 v[152:155], v196 offset:6144
	ds_read_b128 v[156:159], v198 offset:6144
	s_add_u32 m0, s99, 0x4000
	s_nop 0
	global_load_lds_dwordx4 v205, s[58:59]
	s_add_u32 m0, s99, 0x6000
	s_nop 0
	global_load_lds_dwordx4 v206, s[58:59]
	s_waitcnt lgkmcnt(8)
	s_barrier
	s_waitcnt lgkmcnt(0)
	v_mfma_f32_16x16x32_bf16 v[112:115], v[128:131], v[160:163], v[112:115]
	v_mfma_f32_16x16x32_bf16 v[112:115], v[132:135], v[164:167], v[112:115]
	v_mfma_f32_16x16x32_bf16 v[116:119], v[128:131], v[172:175], v[116:119]
	v_mfma_f32_16x16x32_bf16 v[116:119], v[132:135], v[176:179], v[116:119]
	v_mfma_f32_16x16x32_bf16 v[120:123], v[136:139], v[160:163], v[120:123]
	v_mfma_f32_16x16x32_bf16 v[120:123], v[140:143], v[164:167], v[120:123]
	v_mfma_f32_16x16x32_bf16 v[124:127], v[136:139], v[172:175], v[124:127]
	v_mfma_f32_16x16x32_bf16 v[124:127], v[140:143], v[176:179], v[124:127]
	v_mfma_f32_16x16x32_bf16 v[80:83], v[144:147], v[160:163], v[80:83]
	v_mfma_f32_16x16x32_bf16 v[80:83], v[148:151], v[164:167], v[80:83]
	v_mfma_f32_16x16x32_bf16 v[84:87], v[144:147], v[172:175], v[84:87]
	v_mfma_f32_16x16x32_bf16 v[84:87], v[148:151], v[176:179], v[84:87]
	v_mfma_f32_16x16x32_bf16 v[88:91], v[152:155], v[160:163], v[88:91]
	v_mfma_f32_16x16x32_bf16 v[88:91], v[156:159], v[164:167], v[88:91]
	v_mfma_f32_16x16x32_bf16 v[92:95], v[152:155], v[172:175], v[92:95]
	v_mfma_f32_16x16x32_bf16 v[92:95], v[156:159], v[176:179], v[92:95]
	s_barrier
	ds_read_b128 v[180:183], v200 offset:16384
	ds_read_b128 v[184:187], v202 offset:16384
	ds_read_b128 v[188:191], v200 offset:18432
	ds_read_b128 v[192:195], v202 offset:18432
	s_add_u32 s56, s56, 0x80
	s_addc_u32 s57, s57, 0
	s_add_u32 m0, s99, 0x18000
	s_nop 0
	global_load_lds_dwordx4 v207, s[56:57]
	s_add_u32 m0, s99, 0x1a000
	s_nop 0
	global_load_lds_dwordx4 v229, s[56:57]
	s_barrier
	s_waitcnt lgkmcnt(0)
	v_mfma_f32_16x16x32_bf16 v[48:51], v[128:131], v[180:183], v[48:51]
	v_mfma_f32_16x16x32_bf16 v[48:51], v[132:135], v[184:187], v[48:51]
	v_mfma_f32_16x16x32_bf16 v[52:55], v[128:131], v[188:191], v[52:55]
	v_mfma_f32_16x16x32_bf16 v[52:55], v[132:135], v[192:195], v[52:55]
	v_mfma_f32_16x16x32_bf16 v[56:59], v[136:139], v[180:183], v[56:59]
	v_mfma_f32_16x16x32_bf16 v[56:59], v[140:143], v[184:187], v[56:59]
	v_mfma_f32_16x16x32_bf16 v[60:63], v[136:139], v[188:191], v[60:63]
	v_mfma_f32_16x16x32_bf16 v[60:63], v[140:143], v[192:195], v[60:63]
	v_mfma_f32_16x16x32_bf16 v[16:19], v[144:147], v[180:183], v[16:19]
	v_mfma_f32_16x16x32_bf16 v[16:19], v[148:151], v[184:187], v[16:19]
	v_mfma_f32_16x16x32_bf16 v[20:23], v[144:147], v[188:191], v[20:23]
	v_mfma_f32_16x16x32_bf16 v[20:23], v[148:151], v[192:195], v[20:23]
	v_mfma_f32_16x16x32_bf16 v[24:27], v[152:155], v[180:183], v[24:27]
	v_mfma_f32_16x16x32_bf16 v[24:27], v[156:159], v[184:187], v[24:27]
	v_mfma_f32_16x16x32_bf16 v[28:31], v[152:155], v[188:191], v[28:31]
	v_mfma_f32_16x16x32_bf16 v[28:31], v[156:159], v[192:195], v[28:31]
	s_barrier
	ds_read_b128 v[128:131], v196 offset:16384
	ds_read_b128 v[132:135], v198 offset:16384
	ds_read_b128 v[136:139], v196 offset:18432
	ds_read_b128 v[140:143], v198 offset:18432
	ds_read_b128 v[144:147], v196 offset:20480
	ds_read_b128 v[148:151], v198 offset:20480
	ds_read_b128 v[152:155], v196 offset:22528
	ds_read_b128 v[156:159], v198 offset:22528
	s_add_u32 s58, s58, 0x80
	s_addc_u32 s59, s59, 0
	s_add_u32 m0, s99, 0x10000
	s_nop 0
	global_load_lds_dwordx4 v203, s[58:59]
	s_add_u32 m0, s99, 0x12000
	s_nop 0
	global_load_lds_dwordx4 v204, s[58:59]
	s_barrier
	s_waitcnt lgkmcnt(0)
	v_mfma_f32_16x16x32_bf16 v[96:99], v[128:131], v[160:163], v[96:99]
	v_mfma_f32_16x16x32_bf16 v[96:99], v[132:135], v[164:167], v[96:99]
	v_mfma_f32_16x16x32_bf16 v[100:103], v[128:131], v[172:175], v[100:103]
	v_mfma_f32_16x16x32_bf16 v[100:103], v[132:135], v[176:179], v[100:103]
	v_mfma_f32_16x16x32_bf16 v[104:107], v[136:139], v[160:163], v[104:107]
	v_mfma_f32_16x16x32_bf16 v[104:107], v[140:143], v[164:167], v[104:107]
	v_mfma_f32_16x16x32_bf16 v[108:111], v[136:139], v[172:175], v[108:111]
	v_mfma_f32_16x16x32_bf16 v[108:111], v[140:143], v[176:179], v[108:111]
	v_mfma_f32_16x16x32_bf16 v[64:67], v[144:147], v[160:163], v[64:67]
	v_mfma_f32_16x16x32_bf16 v[64:67], v[148:151], v[164:167], v[64:67]
	v_mfma_f32_16x16x32_bf16 v[68:71], v[144:147], v[172:175], v[68:71]
	v_mfma_f32_16x16x32_bf16 v[68:71], v[148:151], v[176:179], v[68:71]
	v_mfma_f32_16x16x32_bf16 v[72:75], v[152:155], v[160:163], v[72:75]
	v_mfma_f32_16x16x32_bf16 v[72:75], v[156:159], v[164:167], v[72:75]
	v_mfma_f32_16x16x32_bf16 v[76:79], v[152:155], v[172:175], v[76:79]
	v_mfma_f32_16x16x32_bf16 v[76:79], v[156:159], v[176:179], v[76:79]
	s_barrier
	s_add_u32 m0, s99, 0x1c000
	s_nop 0
	global_load_lds_dwordx4 v230, s[56:57]
	s_add_u32 m0, s99, 0x1e000
	s_nop 0
	global_load_lds_dwordx4 v231, s[56:57]
	s_waitcnt vmcnt(6)
	s_barrier
	v_mfma_f32_16x16x32_bf16 v[32:35], v[128:131], v[180:183], v[32:35]
	v_mfma_f32_16x16x32_bf16 v[32:35], v[132:135], v[184:187], v[32:35]
	v_mfma_f32_16x16x32_bf16 v[36:39], v[128:131], v[188:191], v[36:39]
	v_mfma_f32_16x16x32_bf16 v[36:39], v[132:135], v[192:195], v[36:39]
	v_mfma_f32_16x16x32_bf16 v[40:43], v[136:139], v[180:183], v[40:43]
	v_mfma_f32_16x16x32_bf16 v[40:43], v[140:143], v[184:187], v[40:43]
	v_mfma_f32_16x16x32_bf16 v[44:47], v[136:139], v[188:191], v[44:47]
	v_mfma_f32_16x16x32_bf16 v[44:47], v[140:143], v[192:195], v[44:47]
	v_mfma_f32_16x16x32_bf16 v[0:3], v[144:147], v[180:183], v[0:3]
	v_mfma_f32_16x16x32_bf16 v[0:3], v[148:151], v[184:187], v[0:3]
	v_mfma_f32_16x16x32_bf16 v[4:7], v[144:147], v[188:191], v[4:7]
	v_mfma_f32_16x16x32_bf16 v[4:7], v[148:151], v[192:195], v[4:7]
	v_mfma_f32_16x16x32_bf16 v[8:11], v[152:155], v[180:183], v[8:11]
	v_mfma_f32_16x16x32_bf16 v[8:11], v[156:159], v[184:187], v[8:11]
	v_mfma_f32_16x16x32_bf16 v[12:15], v[152:155], v[188:191], v[12:15]
	v_mfma_f32_16x16x32_bf16 v[12:15], v[156:159], v[192:195], v[12:15]
	s_barrier
	s_sub_u32 s101, s101, 1
	s_cmp_lg_u32 s101, 0
	s_cbranch_scc1 .Lg8_p2_loop
	ds_read_b128 v[160:163], v199 offset:0
	ds_read_b128 v[164:167], v201 offset:0
	ds_read_b128 v[172:175], v199 offset:2048
	ds_read_b128 v[176:179], v201 offset:2048
	ds_read_b128 v[128:131], v170 offset:0
	ds_read_b128 v[132:135], v197 offset:0
	ds_read_b128 v[136:139], v170 offset:2048
	ds_read_b128 v[140:143], v197 offset:2048
	ds_read_b128 v[144:147], v170 offset:4096
	ds_read_b128 v[148:151], v197 offset:4096
	ds_read_b128 v[152:155], v170 offset:6144
	ds_read_b128 v[156:159], v197 offset:6144
	s_add_u32 m0, s99, 0x14000
	s_nop 0
	global_load_lds_dwordx4 v205, s[58:59]
	s_add_u32 m0, s99, 0x16000
	s_nop 0
	global_load_lds_dwordx4 v206, s[58:59]
	s_barrier
	s_waitcnt lgkmcnt(0)
	v_mfma_f32_16x16x32_bf16 v[112:115], v[128:131], v[160:163], v[112:115]
	v_mfma_f32_16x16x32_bf16 v[112:115], v[132:135], v[164:167], v[112:115]
	v_mfma_f32_16x16x32_bf16 v[116:119], v[128:131], v[172:175], v[116:119]
	v_mfma_f32_16x16x32_bf16 v[116:119], v[132:135], v[176:179], v[116:119]
	v_mfma_f32_16x16x32_bf16 v[120:123], v[136:139], v[160:163], v[120:123]
	v_mfma_f32_16x16x32_bf16 v[120:123], v[140:143], v[164:167], v[120:123]
	v_mfma_f32_16x16x32_bf16 v[124:127], v[136:139], v[172:175], v[124:127]
	v_mfma_f32_16x16x32_bf16 v[124:127], v[140:143], v[176:179], v[124:127]
	v_mfma_f32_16x16x32_bf16 v[80:83], v[144:147], v[160:163], v[80:83]
	v_mfma_f32_16x16x32_bf16 v[80:83], v[148:151], v[164:167], v[80:83]
	v_mfma_f32_16x16x32_bf16 v[84:87], v[144:147], v[172:175], v[84:87]
	v_mfma_f32_16x16x32_bf16 v[84:87], v[148:151], v[176:179], v[84:87]
	v_mfma_f32_16x16x32_bf16 v[88:91], v[152:155], v[160:163], v[88:91]
	v_mfma_f32_16x16x32_bf16 v[88:91], v[156:159], v[164:167], v[88:91]
	v_mfma_f32_16x16x32_bf16 v[92:95], v[152:155], v[172:175], v[92:95]
	v_mfma_f32_16x16x32_bf16 v[92:95], v[156:159], v[176:179], v[92:95]
	s_barrier
	ds_read_b128 v[180:183], v199 offset:16384
	ds_read_b128 v[184:187], v201 offset:16384
	ds_read_b128 v[188:191], v199 offset:18432
	ds_read_b128 v[192:195], v201 offset:18432
	s_barrier
	s_waitcnt lgkmcnt(0)
	v_mfma_f32_16x16x32_bf16 v[48:51], v[128:131], v[180:183], v[48:51]
	v_mfma_f32_16x16x32_bf16 v[48:51], v[132:135], v[184:187], v[48:51]
	v_mfma_f32_16x16x32_bf16 v[52:55], v[128:131], v[188:191], v[52:55]
	v_mfma_f32_16x16x32_bf16 v[52:55], v[132:135], v[192:195], v[52:55]
	v_mfma_f32_16x16x32_bf16 v[56:59], v[136:139], v[180:183], v[56:59]
	v_mfma_f32_16x16x32_bf16 v[56:59], v[140:143], v[184:187], v[56:59]
	v_mfma_f32_16x16x32_bf16 v[60:63], v[136:139], v[188:191], v[60:63]
	v_mfma_f32_16x16x32_bf16 v[60:63], v[140:143], v[192:195], v[60:63]
	v_mfma_f32_16x16x32_bf16 v[16:19], v[144:147], v[180:183], v[16:19]
	v_mfma_f32_16x16x32_bf16 v[16:19], v[148:151], v[184:187], v[16:19]
	v_mfma_f32_16x16x32_bf16 v[20:23], v[144:147], v[188:191], v[20:23]
	v_mfma_f32_16x16x32_bf16 v[20:23], v[148:151], v[192:195], v[20:23]
	v_mfma_f32_16x16x32_bf16 v[24:27], v[152:155], v[180:183], v[24:27]
	v_mfma_f32_16x16x32_bf16 v[24:27], v[156:159], v[184:187], v[24:27]
	v_mfma_f32_16x16x32_bf16 v[28:31], v[152:155], v[188:191], v[28:31]
	v_mfma_f32_16x16x32_bf16 v[28:31], v[156:159], v[192:195], v[28:31]
	s_barrier
	ds_read_b128 v[128:131], v170 offset:16384
	ds_read_b128 v[132:135], v197 offset:16384
	ds_read_b128 v[136:139], v170 offset:18432
	ds_read_b128 v[140:143], v197 offset:18432
	ds_read_b128 v[144:147], v170 offset:20480
	ds_read_b128 v[148:151], v197 offset:20480
	ds_read_b128 v[152:155], v170 offset:22528
	ds_read_b128 v[156:159], v197 offset:22528
	s_waitcnt vmcnt(4)
	s_barrier
	s_waitcnt lgkmcnt(0)
	v_mfma_f32_16x16x32_bf16 v[96:99], v[128:131], v[160:163], v[96:99]
	v_mfma_f32_16x16x32_bf16 v[96:99], v[132:135], v[164:167], v[96:99]
	v_mfma_f32_16x16x32_bf16 v[100:103], v[128:131], v[172:175], v[100:103]
	v_mfma_f32_16x16x32_bf16 v[100:103], v[132:135], v[176:179], v[100:103]
	v_mfma_f32_16x16x32_bf16 v[104:107], v[136:139], v[160:163], v[104:107]
	v_mfma_f32_16x16x32_bf16 v[104:107], v[140:143], v[164:167], v[104:107]
	v_mfma_f32_16x16x32_bf16 v[108:111], v[136:139], v[172:175], v[108:111]
	v_mfma_f32_16x16x32_bf16 v[108:111], v[140:143], v[176:179], v[108:111]
	v_mfma_f32_16x16x32_bf16 v[64:67], v[144:147], v[160:163], v[64:67]
	v_mfma_f32_16x16x32_bf16 v[64:67], v[148:151], v[164:167], v[64:67]
	v_mfma_f32_16x16x32_bf16 v[68:71], v[144:147], v[172:175], v[68:71]
	v_mfma_f32_16x16x32_bf16 v[68:71], v[148:151], v[176:179], v[68:71]
	v_mfma_f32_16x16x32_bf16 v[72:75], v[152:155], v[160:163], v[72:75]
	v_mfma_f32_16x16x32_bf16 v[72:75], v[156:159], v[164:167], v[72:75]
	v_mfma_f32_16x16x32_bf16 v[76:79], v[152:155], v[172:175], v[76:79]
	v_mfma_f32_16x16x32_bf16 v[76:79], v[156:159], v[176:179], v[76:79]
	v_mfma_f32_16x16x32_bf16 v[32:35], v[128:131], v[180:183], v[32:35]
	v_mfma_f32_16x16x32_bf16 v[32:35], v[132:135], v[184:187], v[32:35]
	v_mfma_f32_16x16x32_bf16 v[36:39], v[128:131], v[188:191], v[36:39]
	v_mfma_f32_16x16x32_bf16 v[36:39], v[132:135], v[192:195], v[36:39]
	v_mfma_f32_16x16x32_bf16 v[40:43], v[136:139], v[180:183], v[40:43]
	v_mfma_f32_16x16x32_bf16 v[40:43], v[140:143], v[184:187], v[40:43]
	v_mfma_f32_16x16x32_bf16 v[44:47], v[136:139], v[188:191], v[44:47]
	v_mfma_f32_16x16x32_bf16 v[44:47], v[140:143], v[192:195], v[44:47]
	v_mfma_f32_16x16x32_bf16 v[0:3], v[144:147], v[180:183], v[0:3]
	v_mfma_f32_16x16x32_bf16 v[0:3], v[148:151], v[184:187], v[0:3]
	v_mfma_f32_16x16x32_bf16 v[4:7], v[144:147], v[188:191], v[4:7]
	v_mfma_f32_16x16x32_bf16 v[4:7], v[148:151], v[192:195], v[4:7]
	v_mfma_f32_16x16x32_bf16 v[8:11], v[152:155], v[180:183], v[8:11]
	v_mfma_f32_16x16x32_bf16 v[8:11], v[156:159], v[184:187], v[8:11]
	v_mfma_f32_16x16x32_bf16 v[12:15], v[152:155], v[188:191], v[12:15]
	v_mfma_f32_16x16x32_bf16 v[12:15], v[156:159], v[192:195], v[12:15]
	s_barrier
	ds_read_b128 v[160:163], v200 offset:0
	ds_read_b128 v[164:167], v202 offset:0
	ds_read_b128 v[172:175], v200 offset:2048
	ds_read_b128 v[176:179], v202 offset:2048
	ds_read_b128 v[128:131], v196 offset:0
	ds_read_b128 v[132:135], v198 offset:0
	ds_read_b128 v[136:139], v196 offset:2048
	ds_read_b128 v[140:143], v198 offset:2048
	ds_read_b128 v[144:147], v196 offset:4096
	ds_read_b128 v[148:151], v198 offset:4096
	ds_read_b128 v[152:155], v196 offset:6144
	ds_read_b128 v[156:159], v198 offset:6144
	s_waitcnt vmcnt(2)
	s_barrier
	s_waitcnt lgkmcnt(0)
	v_mfma_f32_16x16x32_bf16 v[112:115], v[128:131], v[160:163], v[112:115]
	v_mfma_f32_16x16x32_bf16 v[112:115], v[132:135], v[164:167], v[112:115]
	v_mfma_f32_16x16x32_bf16 v[116:119], v[128:131], v[172:175], v[116:119]
	v_mfma_f32_16x16x32_bf16 v[116:119], v[132:135], v[176:179], v[116:119]
	v_mfma_f32_16x16x32_bf16 v[120:123], v[136:139], v[160:163], v[120:123]
	v_mfma_f32_16x16x32_bf16 v[120:123], v[140:143], v[164:167], v[120:123]
	v_mfma_f32_16x16x32_bf16 v[124:127], v[136:139], v[172:175], v[124:127]
	v_mfma_f32_16x16x32_bf16 v[124:127], v[140:143], v[176:179], v[124:127]
	v_mfma_f32_16x16x32_bf16 v[80:83], v[144:147], v[160:163], v[80:83]
	v_mfma_f32_16x16x32_bf16 v[80:83], v[148:151], v[164:167], v[80:83]
	v_mfma_f32_16x16x32_bf16 v[84:87], v[144:147], v[172:175], v[84:87]
	v_mfma_f32_16x16x32_bf16 v[84:87], v[148:151], v[176:179], v[84:87]
	v_mfma_f32_16x16x32_bf16 v[88:91], v[152:155], v[160:163], v[88:91]
	v_mfma_f32_16x16x32_bf16 v[88:91], v[156:159], v[164:167], v[88:91]
	v_mfma_f32_16x16x32_bf16 v[92:95], v[152:155], v[172:175], v[92:95]
	v_mfma_f32_16x16x32_bf16 v[92:95], v[156:159], v[176:179], v[92:95]
	s_barrier
	ds_read_b128 v[180:183], v200 offset:16384
	ds_read_b128 v[184:187], v202 offset:16384
	ds_read_b128 v[188:191], v200 offset:18432
	ds_read_b128 v[192:195], v202 offset:18432
	s_waitcnt vmcnt(0)
	s_barrier
	s_waitcnt lgkmcnt(0)
	v_mfma_f32_16x16x32_bf16 v[48:51], v[128:131], v[180:183], v[48:51]
	v_mfma_f32_16x16x32_bf16 v[48:51], v[132:135], v[184:187], v[48:51]
	v_mfma_f32_16x16x32_bf16 v[52:55], v[128:131], v[188:191], v[52:55]
	v_mfma_f32_16x16x32_bf16 v[52:55], v[132:135], v[192:195], v[52:55]
	v_mfma_f32_16x16x32_bf16 v[56:59], v[136:139], v[180:183], v[56:59]
	v_mfma_f32_16x16x32_bf16 v[56:59], v[140:143], v[184:187], v[56:59]
	v_mfma_f32_16x16x32_bf16 v[60:63], v[136:139], v[188:191], v[60:63]
	v_mfma_f32_16x16x32_bf16 v[60:63], v[140:143], v[192:195], v[60:63]
	v_mfma_f32_16x16x32_bf16 v[16:19], v[144:147], v[180:183], v[16:19]
	v_mfma_f32_16x16x32_bf16 v[16:19], v[148:151], v[184:187], v[16:19]
	v_mfma_f32_16x16x32_bf16 v[20:23], v[144:147], v[188:191], v[20:23]
	v_mfma_f32_16x16x32_bf16 v[20:23], v[148:151], v[192:195], v[20:23]
	v_mfma_f32_16x16x32_bf16 v[24:27], v[152:155], v[180:183], v[24:27]
	v_mfma_f32_16x16x32_bf16 v[24:27], v[156:159], v[184:187], v[24:27]
	v_mfma_f32_16x16x32_bf16 v[28:31], v[152:155], v[188:191], v[28:31]
	v_mfma_f32_16x16x32_bf16 v[28:31], v[156:159], v[192:195], v[28:31]
	s_barrier
	ds_read_b128 v[128:131], v196 offset:16384
	ds_read_b128 v[132:135], v198 offset:16384
	ds_read_b128 v[136:139], v196 offset:18432
	ds_read_b128 v[140:143], v198 offset:18432
	ds_read_b128 v[144:147], v196 offset:20480
	ds_read_b128 v[148:151], v198 offset:20480
	ds_read_b128 v[152:155], v196 offset:22528
	ds_read_b128 v[156:159], v198 offset:22528
	s_barrier
	s_waitcnt lgkmcnt(0)
	v_mfma_f32_16x16x32_bf16 v[96:99], v[128:131], v[160:163], v[96:99]
	v_mfma_f32_16x16x32_bf16 v[96:99], v[132:135], v[164:167], v[96:99]
	v_mfma_f32_16x16x32_bf16 v[100:103], v[128:131], v[172:175], v[100:103]
	v_mfma_f32_16x16x32_bf16 v[100:103], v[132:135], v[176:179], v[100:103]
	v_mfma_f32_16x16x32_bf16 v[104:107], v[136:139], v[160:163], v[104:107]
	v_mfma_f32_16x16x32_bf16 v[104:107], v[140:143], v[164:167], v[104:107]
	v_mfma_f32_16x16x32_bf16 v[108:111], v[136:139], v[172:175], v[108:111]
	v_mfma_f32_16x16x32_bf16 v[108:111], v[140:143], v[176:179], v[108:111]
	v_mfma_f32_16x16x32_bf16 v[64:67], v[144:147], v[160:163], v[64:67]
	v_mfma_f32_16x16x32_bf16 v[64:67], v[148:151], v[164:167], v[64:67]
	v_mfma_f32_16x16x32_bf16 v[68:71], v[144:147], v[172:175], v[68:71]
	v_mfma_f32_16x16x32_bf16 v[68:71], v[148:151], v[176:179], v[68:71]
	v_mfma_f32_16x16x32_bf16 v[72:75], v[152:155], v[160:163], v[72:75]
	v_mfma_f32_16x16x32_bf16 v[72:75], v[156:159], v[164:167], v[72:75]
	v_mfma_f32_16x16x32_bf16 v[76:79], v[152:155], v[172:175], v[76:79]
	v_mfma_f32_16x16x32_bf16 v[76:79], v[156:159], v[176:179], v[76:79]
	v_mfma_f32_16x16x32_bf16 v[32:35], v[128:131], v[180:183], v[32:35]
	v_mfma_f32_16x16x32_bf16 v[32:35], v[132:135], v[184:187], v[32:35]
	v_mfma_f32_16x16x32_bf16 v[36:39], v[128:131], v[188:191], v[36:39]
	v_mfma_f32_16x16x32_bf16 v[36:39], v[132:135], v[192:195], v[36:39]
	v_mfma_f32_16x16x32_bf16 v[40:43], v[136:139], v[180:183], v[40:43]
	v_mfma_f32_16x16x32_bf16 v[40:43], v[140:143], v[184:187], v[40:43]
	v_mfma_f32_16x16x32_bf16 v[44:47], v[136:139], v[188:191], v[44:47]
	v_mfma_f32_16x16x32_bf16 v[44:47], v[140:143], v[192:195], v[44:47]
	v_mfma_f32_16x16x32_bf16 v[0:3], v[144:147], v[180:183], v[0:3]
	v_mfma_f32_16x16x32_bf16 v[0:3], v[148:151], v[184:187], v[0:3]
	v_mfma_f32_16x16x32_bf16 v[4:7], v[144:147], v[188:191], v[4:7]
	v_mfma_f32_16x16x32_bf16 v[4:7], v[148:151], v[192:195], v[4:7]
	v_mfma_f32_16x16x32_bf16 v[8:11], v[152:155], v[180:183], v[8:11]
	v_mfma_f32_16x16x32_bf16 v[8:11], v[156:159], v[184:187], v[8:11]
	v_mfma_f32_16x16x32_bf16 v[12:15], v[152:155], v[188:191], v[12:15]
	v_mfma_f32_16x16x32_bf16 v[12:15], v[156:159], v[192:195], v[12:15]
	s_barrier
	s_cmp_lg_u32 s100, 0
	s_cbranch_scc1 .Lg8_p2_gb1
	s_barrier

.Lg8_p4_loop:
	ds_read_b128 v[160:163], v197 offset:0
	ds_read_b128 v[164:167], v199 offset:0
	ds_read_b128 v[168:171], v197 offset:2048
	ds_read_b128 v[172:175], v199 offset:2048
	ds_read_b128 v[128:131], v184 offset:0
	ds_read_b128 v[132:135], v187 offset:0
	ds_read_b128 v[136:139], v184 offset:2048
	ds_read_b128 v[140:143], v187 offset:2048
	ds_read_b128 v[144:147], v184 offset:4096
	ds_read_b128 v[148:151], v187 offset:4096
	ds_read_b128 v[152:155], v184 offset:6144
	ds_read_b128 v[156:159], v187 offset:6144
	s_add_u32 m0, s99, 0x14000
	s_nop 0
	global_load_lds_dwordx4 v203, s[46:47]
	s_add_u32 m0, s99, 0x16000
	s_nop 0
	global_load_lds_dwordx4 v204, s[46:47]
	s_waitcnt lgkmcnt(8)
	s_barrier
	s_waitcnt lgkmcnt(0)
	v_mfma_f32_16x16x32_bf16 v[112:115], v[128:131], v[160:163], v[112:115]
	v_mfma_f32_16x16x32_bf16 v[112:115], v[132:135], v[164:167], v[112:115]
	v_mfma_f32_16x16x32_bf16 v[116:119], v[128:131], v[168:171], v[116:119]
	v_mfma_f32_16x16x32_bf16 v[116:119], v[132:135], v[172:175], v[116:119]
	v_mfma_f32_16x16x32_bf16 v[120:123], v[136:139], v[160:163], v[120:123]
	v_mfma_f32_16x16x32_bf16 v[120:123], v[140:143], v[164:167], v[120:123]
	v_mfma_f32_16x16x32_bf16 v[124:127], v[136:139], v[168:171], v[124:127]
	v_mfma_f32_16x16x32_bf16 v[124:127], v[140:143], v[172:175], v[124:127]
	v_mfma_f32_16x16x32_bf16 v[96:99], v[144:147], v[160:163], v[96:99]
	v_mfma_f32_16x16x32_bf16 v[96:99], v[148:151], v[164:167], v[96:99]
	v_mfma_f32_16x16x32_bf16 v[100:103], v[144:147], v[168:171], v[100:103]
	v_mfma_f32_16x16x32_bf16 v[100:103], v[148:151], v[172:175], v[100:103]
	v_mfma_f32_16x16x32_bf16 v[104:107], v[152:155], v[160:163], v[104:107]
	v_mfma_f32_16x16x32_bf16 v[104:107], v[156:159], v[164:167], v[104:107]
	v_mfma_f32_16x16x32_bf16 v[108:111], v[152:155], v[168:171], v[108:111]
	v_mfma_f32_16x16x32_bf16 v[108:111], v[156:159], v[172:175], v[108:111]
	s_barrier
	ds_read_b128 v[176:179], v197 offset:16384
	ds_read_b128 v[180:183], v199 offset:16384
	ds_read_b128 v[188:191], v197 offset:18432
	ds_read_b128 v[192:195], v199 offset:18432
	s_add_u32 s44, s44, 0x80
	s_addc_u32 s45, s45, 0
	s_add_u32 m0, s99, 0x8000
	s_nop 0
	global_load_lds_dwordx4 v205, s[44:45]
	s_add_u32 m0, s99, 0xa000
	s_nop 0
	global_load_lds_dwordx4 v206, s[44:45]
	s_barrier
	s_waitcnt lgkmcnt(0)
	v_mfma_f32_16x16x32_bf16 v[48:51], v[128:131], v[176:179], v[48:51]
	v_mfma_f32_16x16x32_bf16 v[48:51], v[132:135], v[180:183], v[48:51]
	v_mfma_f32_16x16x32_bf16 v[52:55], v[128:131], v[188:191], v[52:55]
	v_mfma_f32_16x16x32_bf16 v[52:55], v[132:135], v[192:195], v[52:55]
	v_mfma_f32_16x16x32_bf16 v[56:59], v[136:139], v[176:179], v[56:59]
	v_mfma_f32_16x16x32_bf16 v[56:59], v[140:143], v[180:183], v[56:59]
	v_mfma_f32_16x16x32_bf16 v[60:63], v[136:139], v[188:191], v[60:63]
	v_mfma_f32_16x16x32_bf16 v[60:63], v[140:143], v[192:195], v[60:63]
	v_mfma_f32_16x16x32_bf16 v[32:35], v[144:147], v[176:179], v[32:35]
	v_mfma_f32_16x16x32_bf16 v[32:35], v[148:151], v[180:183], v[32:35]
	v_mfma_f32_16x16x32_bf16 v[36:39], v[144:147], v[188:191], v[36:39]
	v_mfma_f32_16x16x32_bf16 v[36:39], v[148:151], v[192:195], v[36:39]
	v_mfma_f32_16x16x32_bf16 v[40:43], v[152:155], v[176:179], v[40:43]
	v_mfma_f32_16x16x32_bf16 v[40:43], v[156:159], v[180:183], v[40:43]
	v_mfma_f32_16x16x32_bf16 v[44:47], v[152:155], v[188:191], v[44:47]
	v_mfma_f32_16x16x32_bf16 v[44:47], v[156:159], v[192:195], v[44:47]
	s_barrier
	ds_read_b128 v[128:131], v184 offset:16384
	ds_read_b128 v[132:135], v187 offset:16384
	ds_read_b128 v[136:139], v184 offset:18432
	ds_read_b128 v[140:143], v187 offset:18432
	ds_read_b128 v[144:147], v184 offset:20480
	ds_read_b128 v[148:151], v187 offset:20480
	ds_read_b128 v[152:155], v184 offset:22528
	ds_read_b128 v[156:159], v187 offset:22528
	s_add_u32 s46, s46, 0x80
	s_addc_u32 s47, s47, 0
	s_add_u32 m0, s99, 0x0
	s_nop 0
	global_load_lds_dwordx4 v201, s[46:47]
	s_add_u32 m0, s99, 0x2000
	s_nop 0
	global_load_lds_dwordx4 v202, s[46:47]
	s_barrier
	s_waitcnt lgkmcnt(0)
	v_mfma_f32_16x16x32_bf16 v[64:67], v[128:131], v[160:163], v[64:67]
	v_mfma_f32_16x16x32_bf16 v[64:67], v[132:135], v[164:167], v[64:67]
	v_mfma_f32_16x16x32_bf16 v[68:71], v[128:131], v[168:171], v[68:71]
	v_mfma_f32_16x16x32_bf16 v[68:71], v[132:135], v[172:175], v[68:71]
	v_mfma_f32_16x16x32_bf16 v[72:75], v[136:139], v[160:163], v[72:75]
	v_mfma_f32_16x16x32_bf16 v[72:75], v[140:143], v[164:167], v[72:75]
	v_mfma_f32_16x16x32_bf16 v[76:79], v[136:139], v[168:171], v[76:79]
	v_mfma_f32_16x16x32_bf16 v[76:79], v[140:143], v[172:175], v[76:79]
	v_mfma_f32_16x16x32_bf16 v[80:83], v[144:147], v[160:163], v[80:83]
	v_mfma_f32_16x16x32_bf16 v[80:83], v[148:151], v[164:167], v[80:83]
	v_mfma_f32_16x16x32_bf16 v[84:87], v[144:147], v[168:171], v[84:87]
	v_mfma_f32_16x16x32_bf16 v[84:87], v[148:151], v[172:175], v[84:87]
	v_mfma_f32_16x16x32_bf16 v[88:91], v[152:155], v[160:163], v[88:91]
	v_mfma_f32_16x16x32_bf16 v[88:91], v[156:159], v[164:167], v[88:91]
	v_mfma_f32_16x16x32_bf16 v[92:95], v[152:155], v[168:171], v[92:95]
	v_mfma_f32_16x16x32_bf16 v[92:95], v[156:159], v[172:175], v[92:95]
	s_barrier
	s_add_u32 m0, s99, 0xc000
	s_nop 0
	global_load_lds_dwordx4 v210, s[44:45]
	s_add_u32 m0, s99, 0xe000
	s_nop 0
	global_load_lds_dwordx4 v211, s[44:45]
	s_waitcnt vmcnt(6)
	s_barrier
	v_mfma_f32_16x16x32_bf16 v[16:19], v[128:131], v[176:179], v[16:19]
	v_mfma_f32_16x16x32_bf16 v[16:19], v[132:135], v[180:183], v[16:19]
	v_mfma_f32_16x16x32_bf16 v[20:23], v[128:131], v[188:191], v[20:23]
	v_mfma_f32_16x16x32_bf16 v[20:23], v[132:135], v[192:195], v[20:23]
	v_mfma_f32_16x16x32_bf16 v[24:27], v[136:139], v[176:179], v[24:27]
	v_mfma_f32_16x16x32_bf16 v[24:27], v[140:143], v[180:183], v[24:27]
	v_mfma_f32_16x16x32_bf16 v[28:31], v[136:139], v[188:191], v[28:31]
	v_mfma_f32_16x16x32_bf16 v[28:31], v[140:143], v[192:195], v[28:31]
	v_mfma_f32_16x16x32_bf16 v[0:3], v[144:147], v[176:179], v[0:3]
	v_mfma_f32_16x16x32_bf16 v[0:3], v[148:151], v[180:183], v[0:3]
	v_mfma_f32_16x16x32_bf16 v[4:7], v[144:147], v[188:191], v[4:7]
	v_mfma_f32_16x16x32_bf16 v[4:7], v[148:151], v[192:195], v[4:7]
	v_mfma_f32_16x16x32_bf16 v[8:11], v[152:155], v[176:179], v[8:11]
	v_mfma_f32_16x16x32_bf16 v[8:11], v[156:159], v[180:183], v[8:11]
	v_mfma_f32_16x16x32_bf16 v[12:15], v[152:155], v[188:191], v[12:15]
	v_mfma_f32_16x16x32_bf16 v[12:15], v[156:159], v[192:195], v[12:15]
	s_barrier
	ds_read_b128 v[160:163], v198 offset:0
	ds_read_b128 v[164:167], v200 offset:0
	ds_read_b128 v[168:171], v198 offset:2048
	ds_read_b128 v[172:175], v200 offset:2048
	ds_read_b128 v[128:131], v186 offset:0
	ds_read_b128 v[132:135], v196 offset:0
	ds_read_b128 v[136:139], v186 offset:2048
	ds_read_b128 v[140:143], v196 offset:2048
	ds_read_b128 v[144:147], v186 offset:4096
	ds_read_b128 v[148:151], v196 offset:4096
	ds_read_b128 v[152:155], v186 offset:6144
	ds_read_b128 v[156:159], v196 offset:6144
	s_add_u32 m0, s99, 0x4000
	s_nop 0
	global_load_lds_dwordx4 v203, s[46:47]
	s_add_u32 m0, s99, 0x6000
	s_nop 0
	global_load_lds_dwordx4 v204, s[46:47]
	s_waitcnt lgkmcnt(8)
	s_barrier
	s_waitcnt lgkmcnt(0)
	v_mfma_f32_16x16x32_bf16 v[112:115], v[128:131], v[160:163], v[112:115]
	v_mfma_f32_16x16x32_bf16 v[112:115], v[132:135], v[164:167], v[112:115]
	v_mfma_f32_16x16x32_bf16 v[116:119], v[128:131], v[168:171], v[116:119]
	v_mfma_f32_16x16x32_bf16 v[116:119], v[132:135], v[172:175], v[116:119]
	v_mfma_f32_16x16x32_bf16 v[120:123], v[136:139], v[160:163], v[120:123]
	v_mfma_f32_16x16x32_bf16 v[120:123], v[140:143], v[164:167], v[120:123]
	v_mfma_f32_16x16x32_bf16 v[124:127], v[136:139], v[168:171], v[124:127]
	v_mfma_f32_16x16x32_bf16 v[124:127], v[140:143], v[172:175], v[124:127]
	v_mfma_f32_16x16x32_bf16 v[96:99], v[144:147], v[160:163], v[96:99]
	v_mfma_f32_16x16x32_bf16 v[96:99], v[148:151], v[164:167], v[96:99]
	v_mfma_f32_16x16x32_bf16 v[100:103], v[144:147], v[168:171], v[100:103]
	v_mfma_f32_16x16x32_bf16 v[100:103], v[148:151], v[172:175], v[100:103]
	v_mfma_f32_16x16x32_bf16 v[104:107], v[152:155], v[160:163], v[104:107]
	v_mfma_f32_16x16x32_bf16 v[104:107], v[156:159], v[164:167], v[104:107]
	v_mfma_f32_16x16x32_bf16 v[108:111], v[152:155], v[168:171], v[108:111]
	v_mfma_f32_16x16x32_bf16 v[108:111], v[156:159], v[172:175], v[108:111]
	s_barrier
	ds_read_b128 v[176:179], v198 offset:16384
	ds_read_b128 v[180:183], v200 offset:16384
	ds_read_b128 v[188:191], v198 offset:18432
	ds_read_b128 v[192:195], v200 offset:18432
	s_add_u32 s44, s44, 0x80
	s_addc_u32 s45, s45, 0
	s_add_u32 m0, s99, 0x18000
	s_nop 0
	global_load_lds_dwordx4 v205, s[44:45]
	s_add_u32 m0, s99, 0x1a000
	s_nop 0
	global_load_lds_dwordx4 v206, s[44:45]
	s_barrier
	s_waitcnt lgkmcnt(0)
	v_mfma_f32_16x16x32_bf16 v[48:51], v[128:131], v[176:179], v[48:51]
	v_mfma_f32_16x16x32_bf16 v[48:51], v[132:135], v[180:183], v[48:51]
	v_mfma_f32_16x16x32_bf16 v[52:55], v[128:131], v[188:191], v[52:55]
	v_mfma_f32_16x16x32_bf16 v[52:55], v[132:135], v[192:195], v[52:55]
	v_mfma_f32_16x16x32_bf16 v[56:59], v[136:139], v[176:179], v[56:59]
	v_mfma_f32_16x16x32_bf16 v[56:59], v[140:143], v[180:183], v[56:59]
	v_mfma_f32_16x16x32_bf16 v[60:63], v[136:139], v[188:191], v[60:63]
	v_mfma_f32_16x16x32_bf16 v[60:63], v[140:143], v[192:195], v[60:63]
	v_mfma_f32_16x16x32_bf16 v[32:35], v[144:147], v[176:179], v[32:35]
	v_mfma_f32_16x16x32_bf16 v[32:35], v[148:151], v[180:183], v[32:35]
	v_mfma_f32_16x16x32_bf16 v[36:39], v[144:147], v[188:191], v[36:39]
	v_mfma_f32_16x16x32_bf16 v[36:39], v[148:151], v[192:195], v[36:39]
	v_mfma_f32_16x16x32_bf16 v[40:43], v[152:155], v[176:179], v[40:43]
	v_mfma_f32_16x16x32_bf16 v[40:43], v[156:159], v[180:183], v[40:43]
	v_mfma_f32_16x16x32_bf16 v[44:47], v[152:155], v[188:191], v[44:47]
	v_mfma_f32_16x16x32_bf16 v[44:47], v[156:159], v[192:195], v[44:47]
	s_barrier
	ds_read_b128 v[128:131], v186 offset:16384
	ds_read_b128 v[132:135], v196 offset:16384
	ds_read_b128 v[136:139], v186 offset:18432
	ds_read_b128 v[140:143], v196 offset:18432
	ds_read_b128 v[144:147], v186 offset:20480
	ds_read_b128 v[148:151], v196 offset:20480
	ds_read_b128 v[152:155], v186 offset:22528
	ds_read_b128 v[156:159], v196 offset:22528
	s_add_u32 s46, s46, 0x80
	s_addc_u32 s47, s47, 0
	s_add_u32 m0, s99, 0x10000
	s_nop 0
	global_load_lds_dwordx4 v201, s[46:47]
	s_add_u32 m0, s99, 0x12000
	s_nop 0
	global_load_lds_dwordx4 v202, s[46:47]
	s_barrier
	s_waitcnt lgkmcnt(0)
	v_mfma_f32_16x16x32_bf16 v[64:67], v[128:131], v[160:163], v[64:67]
	v_mfma_f32_16x16x32_bf16 v[64:67], v[132:135], v[164:167], v[64:67]
	v_mfma_f32_16x16x32_bf16 v[68:71], v[128:131], v[168:171], v[68:71]
	v_mfma_f32_16x16x32_bf16 v[68:71], v[132:135], v[172:175], v[68:71]
	v_mfma_f32_16x16x32_bf16 v[72:75], v[136:139], v[160:163], v[72:75]
	v_mfma_f32_16x16x32_bf16 v[72:75], v[140:143], v[164:167], v[72:75]
	v_mfma_f32_16x16x32_bf16 v[76:79], v[136:139], v[168:171], v[76:79]
	v_mfma_f32_16x16x32_bf16 v[76:79], v[140:143], v[172:175], v[76:79]
	v_mfma_f32_16x16x32_bf16 v[80:83], v[144:147], v[160:163], v[80:83]
	v_mfma_f32_16x16x32_bf16 v[80:83], v[148:151], v[164:167], v[80:83]
	v_mfma_f32_16x16x32_bf16 v[84:87], v[144:147], v[168:171], v[84:87]
	v_mfma_f32_16x16x32_bf16 v[84:87], v[148:151], v[172:175], v[84:87]
	v_mfma_f32_16x16x32_bf16 v[88:91], v[152:155], v[160:163], v[88:91]
	v_mfma_f32_16x16x32_bf16 v[88:91], v[156:159], v[164:167], v[88:91]
	v_mfma_f32_16x16x32_bf16 v[92:95], v[152:155], v[168:171], v[92:95]
	v_mfma_f32_16x16x32_bf16 v[92:95], v[156:159], v[172:175], v[92:95]
	s_barrier
	s_add_u32 m0, s99, 0x1c000
	s_nop 0
	global_load_lds_dwordx4 v210, s[44:45]
	s_add_u32 m0, s99, 0x1e000
	s_nop 0
	global_load_lds_dwordx4 v211, s[44:45]
	s_waitcnt vmcnt(6)
	s_barrier
	v_mfma_f32_16x16x32_bf16 v[16:19], v[128:131], v[176:179], v[16:19]
	v_mfma_f32_16x16x32_bf16 v[16:19], v[132:135], v[180:183], v[16:19]
	v_mfma_f32_16x16x32_bf16 v[20:23], v[128:131], v[188:191], v[20:23]
	v_mfma_f32_16x16x32_bf16 v[20:23], v[132:135], v[192:195], v[20:23]
	v_mfma_f32_16x16x32_bf16 v[24:27], v[136:139], v[176:179], v[24:27]
	v_mfma_f32_16x16x32_bf16 v[24:27], v[140:143], v[180:183], v[24:27]
	v_mfma_f32_16x16x32_bf16 v[28:31], v[136:139], v[188:191], v[28:31]
	v_mfma_f32_16x16x32_bf16 v[28:31], v[140:143], v[192:195], v[28:31]
	v_mfma_f32_16x16x32_bf16 v[0:3], v[144:147], v[176:179], v[0:3]
	v_mfma_f32_16x16x32_bf16 v[0:3], v[148:151], v[180:183], v[0:3]
	v_mfma_f32_16x16x32_bf16 v[4:7], v[144:147], v[188:191], v[4:7]
	v_mfma_f32_16x16x32_bf16 v[4:7], v[148:151], v[192:195], v[4:7]
	v_mfma_f32_16x16x32_bf16 v[8:11], v[152:155], v[176:179], v[8:11]
	v_mfma_f32_16x16x32_bf16 v[8:11], v[156:159], v[180:183], v[8:11]
	v_mfma_f32_16x16x32_bf16 v[12:15], v[152:155], v[188:191], v[12:15]
	v_mfma_f32_16x16x32_bf16 v[12:15], v[156:159], v[192:195], v[12:15]
	s_barrier
	s_sub_u32 s101, s101, 1
	s_cmp_lg_u32 s101, 0
	s_cbranch_scc1 .Lg8_p4_loop
	ds_read_b128 v[160:163], v197 offset:0
	ds_read_b128 v[164:167], v199 offset:0
	ds_read_b128 v[168:171], v197 offset:2048
	ds_read_b128 v[172:175], v199 offset:2048
	ds_read_b128 v[128:131], v184 offset:0
	ds_read_b128 v[132:135], v187 offset:0
	ds_read_b128 v[136:139], v184 offset:2048
	ds_read_b128 v[140:143], v187 offset:2048
	ds_read_b128 v[144:147], v184 offset:4096
	ds_read_b128 v[148:151], v187 offset:4096
	ds_read_b128 v[152:155], v184 offset:6144
	ds_read_b128 v[156:159], v187 offset:6144
	s_add_u32 m0, s99, 0x14000
	s_nop 0
	global_load_lds_dwordx4 v203, s[46:47]
	s_add_u32 m0, s99, 0x16000
	s_nop 0
	global_load_lds_dwordx4 v204, s[46:47]
	s_barrier
	s_waitcnt lgkmcnt(0)
	v_mfma_f32_16x16x32_bf16 v[112:115], v[128:131], v[160:163], v[112:115]
	v_mfma_f32_16x16x32_bf16 v[112:115], v[132:135], v[164:167], v[112:115]
	v_mfma_f32_16x16x32_bf16 v[116:119], v[128:131], v[168:171], v[116:119]
	v_mfma_f32_16x16x32_bf16 v[116:119], v[132:135], v[172:175], v[116:119]
	v_mfma_f32_16x16x32_bf16 v[120:123], v[136:139], v[160:163], v[120:123]
	v_mfma_f32_16x16x32_bf16 v[120:123], v[140:143], v[164:167], v[120:123]
	v_mfma_f32_16x16x32_bf16 v[124:127], v[136:139], v[168:171], v[124:127]
	v_mfma_f32_16x16x32_bf16 v[124:127], v[140:143], v[172:175], v[124:127]
	v_mfma_f32_16x16x32_bf16 v[96:99], v[144:147], v[160:163], v[96:99]
	v_mfma_f32_16x16x32_bf16 v[96:99], v[148:151], v[164:167], v[96:99]
	v_mfma_f32_16x16x32_bf16 v[100:103], v[144:147], v[168:171], v[100:103]
	v_mfma_f32_16x16x32_bf16 v[100:103], v[148:151], v[172:175], v[100:103]
	v_mfma_f32_16x16x32_bf16 v[104:107], v[152:155], v[160:163], v[104:107]
	v_mfma_f32_16x16x32_bf16 v[104:107], v[156:159], v[164:167], v[104:107]
	v_mfma_f32_16x16x32_bf16 v[108:111], v[152:155], v[168:171], v[108:111]
	v_mfma_f32_16x16x32_bf16 v[108:111], v[156:159], v[172:175], v[108:111]
	s_barrier
	ds_read_b128 v[176:179], v197 offset:16384
	ds_read_b128 v[180:183], v199 offset:16384
	ds_read_b128 v[188:191], v197 offset:18432
	ds_read_b128 v[192:195], v199 offset:18432
	s_barrier
	s_waitcnt lgkmcnt(0)
	v_mfma_f32_16x16x32_bf16 v[48:51], v[128:131], v[176:179], v[48:51]
	v_mfma_f32_16x16x32_bf16 v[48:51], v[132:135], v[180:183], v[48:51]
	v_mfma_f32_16x16x32_bf16 v[52:55], v[128:131], v[188:191], v[52:55]
	v_mfma_f32_16x16x32_bf16 v[52:55], v[132:135], v[192:195], v[52:55]
	v_mfma_f32_16x16x32_bf16 v[56:59], v[136:139], v[176:179], v[56:59]
	v_mfma_f32_16x16x32_bf16 v[56:59], v[140:143], v[180:183], v[56:59]
	v_mfma_f32_16x16x32_bf16 v[60:63], v[136:139], v[188:191], v[60:63]
	v_mfma_f32_16x16x32_bf16 v[60:63], v[140:143], v[192:195], v[60:63]
	v_mfma_f32_16x16x32_bf16 v[32:35], v[144:147], v[176:179], v[32:35]
	v_mfma_f32_16x16x32_bf16 v[32:35], v[148:151], v[180:183], v[32:35]
	v_mfma_f32_16x16x32_bf16 v[36:39], v[144:147], v[188:191], v[36:39]
	v_mfma_f32_16x16x32_bf16 v[36:39], v[148:151], v[192:195], v[36:39]
	v_mfma_f32_16x16x32_bf16 v[40:43], v[152:155], v[176:179], v[40:43]
	v_mfma_f32_16x16x32_bf16 v[40:43], v[156:159], v[180:183], v[40:43]
	v_mfma_f32_16x16x32_bf16 v[44:47], v[152:155], v[188:191], v[44:47]
	v_mfma_f32_16x16x32_bf16 v[44:47], v[156:159], v[192:195], v[44:47]
	s_barrier
	ds_read_b128 v[128:131], v184 offset:16384
	ds_read_b128 v[132:135], v187 offset:16384
	ds_read_b128 v[136:139], v184 offset:18432
	ds_read_b128 v[140:143], v187 offset:18432
	ds_read_b128 v[144:147], v184 offset:20480
	ds_read_b128 v[148:151], v187 offset:20480
	ds_read_b128 v[152:155], v184 offset:22528
	ds_read_b128 v[156:159], v187 offset:22528
	s_waitcnt vmcnt(4)
	s_barrier
	s_waitcnt lgkmcnt(0)
	v_mfma_f32_16x16x32_bf16 v[64:67], v[128:131], v[160:163], v[64:67]
	v_mfma_f32_16x16x32_bf16 v[64:67], v[132:135], v[164:167], v[64:67]
	v_mfma_f32_16x16x32_bf16 v[68:71], v[128:131], v[168:171], v[68:71]
	v_mfma_f32_16x16x32_bf16 v[68:71], v[132:135], v[172:175], v[68:71]
	v_mfma_f32_16x16x32_bf16 v[72:75], v[136:139], v[160:163], v[72:75]
	v_mfma_f32_16x16x32_bf16 v[72:75], v[140:143], v[164:167], v[72:75]
	v_mfma_f32_16x16x32_bf16 v[76:79], v[136:139], v[168:171], v[76:79]
	v_mfma_f32_16x16x32_bf16 v[76:79], v[140:143], v[172:175], v[76:79]
	v_mfma_f32_16x16x32_bf16 v[80:83], v[144:147], v[160:163], v[80:83]
	v_mfma_f32_16x16x32_bf16 v[80:83], v[148:151], v[164:167], v[80:83]
	v_mfma_f32_16x16x32_bf16 v[84:87], v[144:147], v[168:171], v[84:87]
	v_mfma_f32_16x16x32_bf16 v[84:87], v[148:151], v[172:175], v[84:87]
	v_mfma_f32_16x16x32_bf16 v[88:91], v[152:155], v[160:163], v[88:91]
	v_mfma_f32_16x16x32_bf16 v[88:91], v[156:159], v[164:167], v[88:91]
	v_mfma_f32_16x16x32_bf16 v[92:95], v[152:155], v[168:171], v[92:95]
	v_mfma_f32_16x16x32_bf16 v[92:95], v[156:159], v[172:175], v[92:95]
	v_mfma_f32_16x16x32_bf16 v[16:19], v[128:131], v[176:179], v[16:19]
	v_mfma_f32_16x16x32_bf16 v[16:19], v[132:135], v[180:183], v[16:19]
	v_mfma_f32_16x16x32_bf16 v[20:23], v[128:131], v[188:191], v[20:23]
	v_mfma_f32_16x16x32_bf16 v[20:23], v[132:135], v[192:195], v[20:23]
	v_mfma_f32_16x16x32_bf16 v[24:27], v[136:139], v[176:179], v[24:27]
	v_mfma_f32_16x16x32_bf16 v[24:27], v[140:143], v[180:183], v[24:27]
	v_mfma_f32_16x16x32_bf16 v[28:31], v[136:139], v[188:191], v[28:31]
	v_mfma_f32_16x16x32_bf16 v[28:31], v[140:143], v[192:195], v[28:31]
	v_mfma_f32_16x16x32_bf16 v[0:3], v[144:147], v[176:179], v[0:3]
	v_mfma_f32_16x16x32_bf16 v[0:3], v[148:151], v[180:183], v[0:3]
	v_mfma_f32_16x16x32_bf16 v[4:7], v[144:147], v[188:191], v[4:7]
	v_mfma_f32_16x16x32_bf16 v[4:7], v[148:151], v[192:195], v[4:7]
	v_mfma_f32_16x16x32_bf16 v[8:11], v[152:155], v[176:179], v[8:11]
	v_mfma_f32_16x16x32_bf16 v[8:11], v[156:159], v[180:183], v[8:11]
	v_mfma_f32_16x16x32_bf16 v[12:15], v[152:155], v[188:191], v[12:15]
	v_mfma_f32_16x16x32_bf16 v[12:15], v[156:159], v[192:195], v[12:15]
	s_barrier
	ds_read_b128 v[160:163], v198 offset:0
	ds_read_b128 v[164:167], v200 offset:0
	ds_read_b128 v[168:171], v198 offset:2048
	ds_read_b128 v[172:175], v200 offset:2048
	ds_read_b128 v[128:131], v186 offset:0
	ds_read_b128 v[132:135], v196 offset:0
	ds_read_b128 v[136:139], v186 offset:2048
	ds_read_b128 v[140:143], v196 offset:2048
	ds_read_b128 v[144:147], v186 offset:4096
	ds_read_b128 v[148:151], v196 offset:4096
	ds_read_b128 v[152:155], v186 offset:6144
	ds_read_b128 v[156:159], v196 offset:6144
	s_waitcnt vmcnt(2)
	s_barrier
	s_waitcnt lgkmcnt(0)
	v_mfma_f32_16x16x32_bf16 v[112:115], v[128:131], v[160:163], v[112:115]
	v_mfma_f32_16x16x32_bf16 v[112:115], v[132:135], v[164:167], v[112:115]
	v_mfma_f32_16x16x32_bf16 v[116:119], v[128:131], v[168:171], v[116:119]
	v_mfma_f32_16x16x32_bf16 v[116:119], v[132:135], v[172:175], v[116:119]
	v_mfma_f32_16x16x32_bf16 v[120:123], v[136:139], v[160:163], v[120:123]
	v_mfma_f32_16x16x32_bf16 v[120:123], v[140:143], v[164:167], v[120:123]
	v_mfma_f32_16x16x32_bf16 v[124:127], v[136:139], v[168:171], v[124:127]
	v_mfma_f32_16x16x32_bf16 v[124:127], v[140:143], v[172:175], v[124:127]
	v_mfma_f32_16x16x32_bf16 v[96:99], v[144:147], v[160:163], v[96:99]
	v_mfma_f32_16x16x32_bf16 v[96:99], v[148:151], v[164:167], v[96:99]
	v_mfma_f32_16x16x32_bf16 v[100:103], v[144:147], v[168:171], v[100:103]
	v_mfma_f32_16x16x32_bf16 v[100:103], v[148:151], v[172:175], v[100:103]
	v_mfma_f32_16x16x32_bf16 v[104:107], v[152:155], v[160:163], v[104:107]
	v_mfma_f32_16x16x32_bf16 v[104:107], v[156:159], v[164:167], v[104:107]
	v_mfma_f32_16x16x32_bf16 v[108:111], v[152:155], v[168:171], v[108:111]
	v_mfma_f32_16x16x32_bf16 v[108:111], v[156:159], v[172:175], v[108:111]
	s_barrier
	ds_read_b128 v[176:179], v198 offset:16384
	ds_read_b128 v[180:183], v200 offset:16384
	ds_read_b128 v[188:191], v198 offset:18432
	ds_read_b128 v[192:195], v200 offset:18432
	s_waitcnt vmcnt(0)
	s_barrier
	s_waitcnt lgkmcnt(0)
	v_mfma_f32_16x16x32_bf16 v[48:51], v[128:131], v[176:179], v[48:51]
	v_mfma_f32_16x16x32_bf16 v[48:51], v[132:135], v[180:183], v[48:51]
	v_mfma_f32_16x16x32_bf16 v[52:55], v[128:131], v[188:191], v[52:55]
	v_mfma_f32_16x16x32_bf16 v[52:55], v[132:135], v[192:195], v[52:55]
	v_mfma_f32_16x16x32_bf16 v[56:59], v[136:139], v[176:179], v[56:59]
	v_mfma_f32_16x16x32_bf16 v[56:59], v[140:143], v[180:183], v[56:59]
	v_mfma_f32_16x16x32_bf16 v[60:63], v[136:139], v[188:191], v[60:63]
	v_mfma_f32_16x16x32_bf16 v[60:63], v[140:143], v[192:195], v[60:63]
	v_mfma_f32_16x16x32_bf16 v[32:35], v[144:147], v[176:179], v[32:35]
	v_mfma_f32_16x16x32_bf16 v[32:35], v[148:151], v[180:183], v[32:35]
	v_mfma_f32_16x16x32_bf16 v[36:39], v[144:147], v[188:191], v[36:39]
	v_mfma_f32_16x16x32_bf16 v[36:39], v[148:151], v[192:195], v[36:39]
	v_mfma_f32_16x16x32_bf16 v[40:43], v[152:155], v[176:179], v[40:43]
	v_mfma_f32_16x16x32_bf16 v[40:43], v[156:159], v[180:183], v[40:43]
	v_mfma_f32_16x16x32_bf16 v[44:47], v[152:155], v[188:191], v[44:47]
	v_mfma_f32_16x16x32_bf16 v[44:47], v[156:159], v[192:195], v[44:47]
	s_barrier
	ds_read_b128 v[128:131], v186 offset:16384
	ds_read_b128 v[132:135], v196 offset:16384
	ds_read_b128 v[136:139], v186 offset:18432
	ds_read_b128 v[140:143], v196 offset:18432
	ds_read_b128 v[144:147], v186 offset:20480
	ds_read_b128 v[148:151], v196 offset:20480
	ds_read_b128 v[152:155], v186 offset:22528
	ds_read_b128 v[156:159], v196 offset:22528
	s_barrier
	s_waitcnt lgkmcnt(0)
	v_mfma_f32_16x16x32_bf16 v[64:67], v[128:131], v[160:163], v[64:67]
	v_mfma_f32_16x16x32_bf16 v[64:67], v[132:135], v[164:167], v[64:67]
	v_mfma_f32_16x16x32_bf16 v[68:71], v[128:131], v[168:171], v[68:71]
	v_mfma_f32_16x16x32_bf16 v[68:71], v[132:135], v[172:175], v[68:71]
	v_mfma_f32_16x16x32_bf16 v[72:75], v[136:139], v[160:163], v[72:75]
	v_mfma_f32_16x16x32_bf16 v[72:75], v[140:143], v[164:167], v[72:75]
	v_mfma_f32_16x16x32_bf16 v[76:79], v[136:139], v[168:171], v[76:79]
	v_mfma_f32_16x16x32_bf16 v[76:79], v[140:143], v[172:175], v[76:79]
	v_mfma_f32_16x16x32_bf16 v[80:83], v[144:147], v[160:163], v[80:83]
	v_mfma_f32_16x16x32_bf16 v[80:83], v[148:151], v[164:167], v[80:83]
	v_mfma_f32_16x16x32_bf16 v[84:87], v[144:147], v[168:171], v[84:87]
	v_mfma_f32_16x16x32_bf16 v[84:87], v[148:151], v[172:175], v[84:87]
	v_mfma_f32_16x16x32_bf16 v[88:91], v[152:155], v[160:163], v[88:91]
	v_mfma_f32_16x16x32_bf16 v[88:91], v[156:159], v[164:167], v[88:91]
	v_mfma_f32_16x16x32_bf16 v[92:95], v[152:155], v[168:171], v[92:95]
	v_mfma_f32_16x16x32_bf16 v[92:95], v[156:159], v[172:175], v[92:95]
	v_mfma_f32_16x16x32_bf16 v[16:19], v[128:131], v[176:179], v[16:19]
	v_mfma_f32_16x16x32_bf16 v[16:19], v[132:135], v[180:183], v[16:19]
	v_mfma_f32_16x16x32_bf16 v[20:23], v[128:131], v[188:191], v[20:23]
	v_mfma_f32_16x16x32_bf16 v[20:23], v[132:135], v[192:195], v[20:23]
	v_mfma_f32_16x16x32_bf16 v[24:27], v[136:139], v[176:179], v[24:27]
	v_mfma_f32_16x16x32_bf16 v[24:27], v[140:143], v[180:183], v[24:27]
	v_mfma_f32_16x16x32_bf16 v[28:31], v[136:139], v[188:191], v[28:31]
	v_mfma_f32_16x16x32_bf16 v[28:31], v[140:143], v[192:195], v[28:31]
	v_mfma_f32_16x16x32_bf16 v[0:3], v[144:147], v[176:179], v[0:3]
	v_mfma_f32_16x16x32_bf16 v[0:3], v[148:151], v[180:183], v[0:3]
	v_mfma_f32_16x16x32_bf16 v[4:7], v[144:147], v[188:191], v[4:7]
	v_mfma_f32_16x16x32_bf16 v[4:7], v[148:151], v[192:195], v[4:7]
	v_mfma_f32_16x16x32_bf16 v[8:11], v[152:155], v[176:179], v[8:11]
	v_mfma_f32_16x16x32_bf16 v[8:11], v[156:159], v[180:183], v[8:11]
	v_mfma_f32_16x16x32_bf16 v[12:15], v[152:155], v[188:191], v[12:15]
	v_mfma_f32_16x16x32_bf16 v[12:15], v[156:159], v[192:195], v[12:15]
	s_barrier
	s_cmp_lg_u32 s100, 0
	s_cbranch_scc1 .Lg8_p4_gb1
	s_barrier

.Lg8_p6g_loop:
	ds_read_b128 v[160:163], v197 offset:0
	ds_read_b128 v[164:167], v199 offset:0
	ds_read_b128 v[172:175], v197 offset:2048
	ds_read_b128 v[176:179], v199 offset:2048
	ds_read_b128 v[128:131], v168 offset:0
	ds_read_b128 v[132:135], v171 offset:0
	ds_read_b128 v[136:139], v168 offset:2048
	ds_read_b128 v[140:143], v171 offset:2048
	ds_read_b128 v[144:147], v168 offset:4096
	ds_read_b128 v[148:151], v171 offset:4096
	ds_read_b128 v[152:155], v168 offset:6144
	ds_read_b128 v[156:159], v171 offset:6144
	s_add_u32 m0, s99, 0x14000
	s_nop 0
	global_load_lds_dwordx4 v203, s[58:59]
	s_add_u32 m0, s99, 0x16000
	s_nop 0
	global_load_lds_dwordx4 v204, s[58:59]
	s_waitcnt lgkmcnt(8)
	s_barrier
	s_waitcnt lgkmcnt(0)
	v_mfma_f32_16x16x32_bf16 v[112:115], v[128:131], v[160:163], v[112:115]
	v_mfma_f32_16x16x32_bf16 v[112:115], v[132:135], v[164:167], v[112:115]
	v_mfma_f32_16x16x32_bf16 v[116:119], v[128:131], v[172:175], v[116:119]
	v_mfma_f32_16x16x32_bf16 v[116:119], v[132:135], v[176:179], v[116:119]
	v_mfma_f32_16x16x32_bf16 v[120:123], v[136:139], v[160:163], v[120:123]
	v_mfma_f32_16x16x32_bf16 v[120:123], v[140:143], v[164:167], v[120:123]
	v_mfma_f32_16x16x32_bf16 v[124:127], v[136:139], v[172:175], v[124:127]
	v_mfma_f32_16x16x32_bf16 v[124:127], v[140:143], v[176:179], v[124:127]
	v_mfma_f32_16x16x32_bf16 v[96:99], v[144:147], v[160:163], v[96:99]
	v_mfma_f32_16x16x32_bf16 v[96:99], v[148:151], v[164:167], v[96:99]
	v_mfma_f32_16x16x32_bf16 v[100:103], v[144:147], v[172:175], v[100:103]
	v_mfma_f32_16x16x32_bf16 v[100:103], v[148:151], v[176:179], v[100:103]
	v_mfma_f32_16x16x32_bf16 v[104:107], v[152:155], v[160:163], v[104:107]
	v_mfma_f32_16x16x32_bf16 v[104:107], v[156:159], v[164:167], v[104:107]
	v_mfma_f32_16x16x32_bf16 v[108:111], v[152:155], v[172:175], v[108:111]
	v_mfma_f32_16x16x32_bf16 v[108:111], v[156:159], v[176:179], v[108:111]
	s_barrier
	ds_read_b128 v[180:183], v197 offset:16384
	ds_read_b128 v[184:187], v199 offset:16384
	ds_read_b128 v[188:191], v197 offset:18432
	ds_read_b128 v[192:195], v199 offset:18432
	s_add_u32 s56, s56, 0x80
	s_addc_u32 s57, s57, 0
	s_add_u32 m0, s99, 0x8000
	s_nop 0
	global_load_lds_dwordx4 v205, s[56:57]
	s_add_u32 m0, s99, 0xa000
	s_nop 0
	global_load_lds_dwordx4 v206, s[56:57]
	s_barrier
	s_waitcnt lgkmcnt(0)
	v_mfma_f32_16x16x32_bf16 v[48:51], v[128:131], v[180:183], v[48:51]
	v_mfma_f32_16x16x32_bf16 v[48:51], v[132:135], v[184:187], v[48:51]
	v_mfma_f32_16x16x32_bf16 v[52:55], v[128:131], v[188:191], v[52:55]
	v_mfma_f32_16x16x32_bf16 v[52:55], v[132:135], v[192:195], v[52:55]
	v_mfma_f32_16x16x32_bf16 v[56:59], v[136:139], v[180:183], v[56:59]
	v_mfma_f32_16x16x32_bf16 v[56:59], v[140:143], v[184:187], v[56:59]
	v_mfma_f32_16x16x32_bf16 v[60:63], v[136:139], v[188:191], v[60:63]
	v_mfma_f32_16x16x32_bf16 v[60:63], v[140:143], v[192:195], v[60:63]
	v_mfma_f32_16x16x32_bf16 v[32:35], v[144:147], v[180:183], v[32:35]
	v_mfma_f32_16x16x32_bf16 v[32:35], v[148:151], v[184:187], v[32:35]
	v_mfma_f32_16x16x32_bf16 v[36:39], v[144:147], v[188:191], v[36:39]
	v_mfma_f32_16x16x32_bf16 v[36:39], v[148:151], v[192:195], v[36:39]
	v_mfma_f32_16x16x32_bf16 v[40:43], v[152:155], v[180:183], v[40:43]
	v_mfma_f32_16x16x32_bf16 v[40:43], v[156:159], v[184:187], v[40:43]
	v_mfma_f32_16x16x32_bf16 v[44:47], v[152:155], v[188:191], v[44:47]
	v_mfma_f32_16x16x32_bf16 v[44:47], v[156:159], v[192:195], v[44:47]
	s_barrier
	ds_read_b128 v[128:131], v168 offset:16384
	ds_read_b128 v[132:135], v171 offset:16384
	ds_read_b128 v[136:139], v168 offset:18432
	ds_read_b128 v[140:143], v171 offset:18432
	ds_read_b128 v[144:147], v168 offset:20480
	ds_read_b128 v[148:151], v171 offset:20480
	ds_read_b128 v[152:155], v168 offset:22528
	ds_read_b128 v[156:159], v171 offset:22528
	s_add_u32 s58, s58, 0x80
	s_addc_u32 s59, s59, 0
	s_add_u32 m0, s99, 0x0
	s_nop 0
	global_load_lds_dwordx4 v201, s[58:59]
	s_add_u32 m0, s99, 0x2000
	s_nop 0
	global_load_lds_dwordx4 v202, s[58:59]
	s_barrier
	s_waitcnt lgkmcnt(0)
	v_mfma_f32_16x16x32_bf16 v[80:83], v[128:131], v[160:163], v[80:83]
	v_mfma_f32_16x16x32_bf16 v[80:83], v[132:135], v[164:167], v[80:83]
	v_mfma_f32_16x16x32_bf16 v[84:87], v[128:131], v[172:175], v[84:87]
	v_mfma_f32_16x16x32_bf16 v[84:87], v[132:135], v[176:179], v[84:87]
	v_mfma_f32_16x16x32_bf16 v[88:91], v[136:139], v[160:163], v[88:91]
	v_mfma_f32_16x16x32_bf16 v[88:91], v[140:143], v[164:167], v[88:91]
	v_mfma_f32_16x16x32_bf16 v[92:95], v[136:139], v[172:175], v[92:95]
	v_mfma_f32_16x16x32_bf16 v[92:95], v[140:143], v[176:179], v[92:95]
	v_mfma_f32_16x16x32_bf16 v[64:67], v[144:147], v[160:163], v[64:67]
	v_mfma_f32_16x16x32_bf16 v[64:67], v[148:151], v[164:167], v[64:67]
	v_mfma_f32_16x16x32_bf16 v[68:71], v[144:147], v[172:175], v[68:71]
	v_mfma_f32_16x16x32_bf16 v[68:71], v[148:151], v[176:179], v[68:71]
	v_mfma_f32_16x16x32_bf16 v[72:75], v[152:155], v[160:163], v[72:75]
	v_mfma_f32_16x16x32_bf16 v[72:75], v[156:159], v[164:167], v[72:75]
	v_mfma_f32_16x16x32_bf16 v[76:79], v[152:155], v[172:175], v[76:79]
	v_mfma_f32_16x16x32_bf16 v[76:79], v[156:159], v[176:179], v[76:79]
	s_barrier
	s_add_u32 m0, s99, 0xc000
	s_nop 0
	global_load_lds_dwordx4 v210, s[56:57]
	s_add_u32 m0, s99, 0xe000
	s_nop 0
	global_load_lds_dwordx4 v211, s[56:57]
	s_waitcnt vmcnt(6)
	s_barrier
	v_mfma_f32_16x16x32_bf16 v[16:19], v[128:131], v[180:183], v[16:19]
	v_mfma_f32_16x16x32_bf16 v[16:19], v[132:135], v[184:187], v[16:19]
	v_mfma_f32_16x16x32_bf16 v[20:23], v[128:131], v[188:191], v[20:23]
	v_mfma_f32_16x16x32_bf16 v[20:23], v[132:135], v[192:195], v[20:23]
	v_mfma_f32_16x16x32_bf16 v[24:27], v[136:139], v[180:183], v[24:27]
	v_mfma_f32_16x16x32_bf16 v[24:27], v[140:143], v[184:187], v[24:27]
	v_mfma_f32_16x16x32_bf16 v[28:31], v[136:139], v[188:191], v[28:31]
	v_mfma_f32_16x16x32_bf16 v[28:31], v[140:143], v[192:195], v[28:31]
	v_mfma_f32_16x16x32_bf16 v[0:3], v[144:147], v[180:183], v[0:3]
	v_mfma_f32_16x16x32_bf16 v[0:3], v[148:151], v[184:187], v[0:3]
	v_mfma_f32_16x16x32_bf16 v[4:7], v[144:147], v[188:191], v[4:7]
	v_mfma_f32_16x16x32_bf16 v[4:7], v[148:151], v[192:195], v[4:7]
	v_mfma_f32_16x16x32_bf16 v[8:11], v[152:155], v[180:183], v[8:11]
	v_mfma_f32_16x16x32_bf16 v[8:11], v[156:159], v[184:187], v[8:11]
	v_mfma_f32_16x16x32_bf16 v[12:15], v[152:155], v[188:191], v[12:15]
	v_mfma_f32_16x16x32_bf16 v[12:15], v[156:159], v[192:195], v[12:15]
	s_barrier
	ds_read_b128 v[160:163], v198 offset:0
	ds_read_b128 v[164:167], v200 offset:0
	ds_read_b128 v[172:175], v198 offset:2048
	ds_read_b128 v[176:179], v200 offset:2048
	ds_read_b128 v[128:131], v170 offset:0
	ds_read_b128 v[132:135], v196 offset:0
	ds_read_b128 v[136:139], v170 offset:2048
	ds_read_b128 v[140:143], v196 offset:2048
	ds_read_b128 v[144:147], v170 offset:4096
	ds_read_b128 v[148:151], v196 offset:4096
	ds_read_b128 v[152:155], v170 offset:6144
	ds_read_b128 v[156:159], v196 offset:6144
	s_add_u32 m0, s99, 0x4000
	s_nop 0
	global_load_lds_dwordx4 v203, s[58:59]
	s_add_u32 m0, s99, 0x6000
	s_nop 0
	global_load_lds_dwordx4 v204, s[58:59]
	s_waitcnt lgkmcnt(8)
	s_barrier
	s_waitcnt lgkmcnt(0)
	v_mfma_f32_16x16x32_bf16 v[112:115], v[128:131], v[160:163], v[112:115]
	v_mfma_f32_16x16x32_bf16 v[112:115], v[132:135], v[164:167], v[112:115]
	v_mfma_f32_16x16x32_bf16 v[116:119], v[128:131], v[172:175], v[116:119]
	v_mfma_f32_16x16x32_bf16 v[116:119], v[132:135], v[176:179], v[116:119]
	v_mfma_f32_16x16x32_bf16 v[120:123], v[136:139], v[160:163], v[120:123]
	v_mfma_f32_16x16x32_bf16 v[120:123], v[140:143], v[164:167], v[120:123]
	v_mfma_f32_16x16x32_bf16 v[124:127], v[136:139], v[172:175], v[124:127]
	v_mfma_f32_16x16x32_bf16 v[124:127], v[140:143], v[176:179], v[124:127]
	v_mfma_f32_16x16x32_bf16 v[96:99], v[144:147], v[160:163], v[96:99]
	v_mfma_f32_16x16x32_bf16 v[96:99], v[148:151], v[164:167], v[96:99]
	v_mfma_f32_16x16x32_bf16 v[100:103], v[144:147], v[172:175], v[100:103]
	v_mfma_f32_16x16x32_bf16 v[100:103], v[148:151], v[176:179], v[100:103]
	v_mfma_f32_16x16x32_bf16 v[104:107], v[152:155], v[160:163], v[104:107]
	v_mfma_f32_16x16x32_bf16 v[104:107], v[156:159], v[164:167], v[104:107]
	v_mfma_f32_16x16x32_bf16 v[108:111], v[152:155], v[172:175], v[108:111]
	v_mfma_f32_16x16x32_bf16 v[108:111], v[156:159], v[176:179], v[108:111]
	s_barrier
	ds_read_b128 v[180:183], v198 offset:16384
	ds_read_b128 v[184:187], v200 offset:16384
	ds_read_b128 v[188:191], v198 offset:18432
	ds_read_b128 v[192:195], v200 offset:18432
	s_add_u32 s56, s56, 0x80
	s_addc_u32 s57, s57, 0
	s_add_u32 m0, s99, 0x18000
	s_nop 0
	global_load_lds_dwordx4 v205, s[56:57]
	s_add_u32 m0, s99, 0x1a000
	s_nop 0
	global_load_lds_dwordx4 v206, s[56:57]
	s_barrier
	s_waitcnt lgkmcnt(0)
	v_mfma_f32_16x16x32_bf16 v[48:51], v[128:131], v[180:183], v[48:51]
	v_mfma_f32_16x16x32_bf16 v[48:51], v[132:135], v[184:187], v[48:51]
	v_mfma_f32_16x16x32_bf16 v[52:55], v[128:131], v[188:191], v[52:55]
	v_mfma_f32_16x16x32_bf16 v[52:55], v[132:135], v[192:195], v[52:55]
	v_mfma_f32_16x16x32_bf16 v[56:59], v[136:139], v[180:183], v[56:59]
	v_mfma_f32_16x16x32_bf16 v[56:59], v[140:143], v[184:187], v[56:59]
	v_mfma_f32_16x16x32_bf16 v[60:63], v[136:139], v[188:191], v[60:63]
	v_mfma_f32_16x16x32_bf16 v[60:63], v[140:143], v[192:195], v[60:63]
	v_mfma_f32_16x16x32_bf16 v[32:35], v[144:147], v[180:183], v[32:35]
	v_mfma_f32_16x16x32_bf16 v[32:35], v[148:151], v[184:187], v[32:35]
	v_mfma_f32_16x16x32_bf16 v[36:39], v[144:147], v[188:191], v[36:39]
	v_mfma_f32_16x16x32_bf16 v[36:39], v[148:151], v[192:195], v[36:39]
	v_mfma_f32_16x16x32_bf16 v[40:43], v[152:155], v[180:183], v[40:43]
	v_mfma_f32_16x16x32_bf16 v[40:43], v[156:159], v[184:187], v[40:43]
	v_mfma_f32_16x16x32_bf16 v[44:47], v[152:155], v[188:191], v[44:47]
	v_mfma_f32_16x16x32_bf16 v[44:47], v[156:159], v[192:195], v[44:47]
	s_barrier
	ds_read_b128 v[128:131], v170 offset:16384
	ds_read_b128 v[132:135], v196 offset:16384
	ds_read_b128 v[136:139], v170 offset:18432
	ds_read_b128 v[140:143], v196 offset:18432
	ds_read_b128 v[144:147], v170 offset:20480
	ds_read_b128 v[148:151], v196 offset:20480
	ds_read_b128 v[152:155], v170 offset:22528
	ds_read_b128 v[156:159], v196 offset:22528
	s_add_u32 s58, s58, 0x80
	s_addc_u32 s59, s59, 0
	s_add_u32 m0, s99, 0x10000
	s_nop 0
	global_load_lds_dwordx4 v201, s[58:59]
	s_add_u32 m0, s99, 0x12000
	s_nop 0
	global_load_lds_dwordx4 v202, s[58:59]
	s_barrier
	s_waitcnt lgkmcnt(0)
	v_mfma_f32_16x16x32_bf16 v[80:83], v[128:131], v[160:163], v[80:83]
	v_mfma_f32_16x16x32_bf16 v[80:83], v[132:135], v[164:167], v[80:83]
	v_mfma_f32_16x16x32_bf16 v[84:87], v[128:131], v[172:175], v[84:87]
	v_mfma_f32_16x16x32_bf16 v[84:87], v[132:135], v[176:179], v[84:87]
	v_mfma_f32_16x16x32_bf16 v[88:91], v[136:139], v[160:163], v[88:91]
	v_mfma_f32_16x16x32_bf16 v[88:91], v[140:143], v[164:167], v[88:91]
	v_mfma_f32_16x16x32_bf16 v[92:95], v[136:139], v[172:175], v[92:95]
	v_mfma_f32_16x16x32_bf16 v[92:95], v[140:143], v[176:179], v[92:95]
	v_mfma_f32_16x16x32_bf16 v[64:67], v[144:147], v[160:163], v[64:67]
	v_mfma_f32_16x16x32_bf16 v[64:67], v[148:151], v[164:167], v[64:67]
	v_mfma_f32_16x16x32_bf16 v[68:71], v[144:147], v[172:175], v[68:71]
	v_mfma_f32_16x16x32_bf16 v[68:71], v[148:151], v[176:179], v[68:71]
	v_mfma_f32_16x16x32_bf16 v[72:75], v[152:155], v[160:163], v[72:75]
	v_mfma_f32_16x16x32_bf16 v[72:75], v[156:159], v[164:167], v[72:75]
	v_mfma_f32_16x16x32_bf16 v[76:79], v[152:155], v[172:175], v[76:79]
	v_mfma_f32_16x16x32_bf16 v[76:79], v[156:159], v[176:179], v[76:79]
	s_barrier
	s_add_u32 m0, s99, 0x1c000
	s_nop 0
	global_load_lds_dwordx4 v210, s[56:57]
	s_add_u32 m0, s99, 0x1e000
	s_nop 0
	global_load_lds_dwordx4 v211, s[56:57]
	s_waitcnt vmcnt(6)
	s_barrier
	v_mfma_f32_16x16x32_bf16 v[16:19], v[128:131], v[180:183], v[16:19]
	v_mfma_f32_16x16x32_bf16 v[16:19], v[132:135], v[184:187], v[16:19]
	v_mfma_f32_16x16x32_bf16 v[20:23], v[128:131], v[188:191], v[20:23]
	v_mfma_f32_16x16x32_bf16 v[20:23], v[132:135], v[192:195], v[20:23]
	v_mfma_f32_16x16x32_bf16 v[24:27], v[136:139], v[180:183], v[24:27]
	v_mfma_f32_16x16x32_bf16 v[24:27], v[140:143], v[184:187], v[24:27]
	v_mfma_f32_16x16x32_bf16 v[28:31], v[136:139], v[188:191], v[28:31]
	v_mfma_f32_16x16x32_bf16 v[28:31], v[140:143], v[192:195], v[28:31]
	v_mfma_f32_16x16x32_bf16 v[0:3], v[144:147], v[180:183], v[0:3]
	v_mfma_f32_16x16x32_bf16 v[0:3], v[148:151], v[184:187], v[0:3]
	v_mfma_f32_16x16x32_bf16 v[4:7], v[144:147], v[188:191], v[4:7]
	v_mfma_f32_16x16x32_bf16 v[4:7], v[148:151], v[192:195], v[4:7]
	v_mfma_f32_16x16x32_bf16 v[8:11], v[152:155], v[180:183], v[8:11]
	v_mfma_f32_16x16x32_bf16 v[8:11], v[156:159], v[184:187], v[8:11]
	v_mfma_f32_16x16x32_bf16 v[12:15], v[152:155], v[188:191], v[12:15]
	v_mfma_f32_16x16x32_bf16 v[12:15], v[156:159], v[192:195], v[12:15]
	s_barrier
	s_sub_u32 s101, s101, 1
	s_cmp_lg_u32 s101, 0
	s_cbranch_scc1 .Lg8_p6g_loop
	ds_read_b128 v[160:163], v197 offset:0
	ds_read_b128 v[164:167], v199 offset:0
	ds_read_b128 v[172:175], v197 offset:2048
	ds_read_b128 v[176:179], v199 offset:2048
	ds_read_b128 v[128:131], v168 offset:0
	ds_read_b128 v[132:135], v171 offset:0
	ds_read_b128 v[136:139], v168 offset:2048
	ds_read_b128 v[140:143], v171 offset:2048
	ds_read_b128 v[144:147], v168 offset:4096
	ds_read_b128 v[148:151], v171 offset:4096
	ds_read_b128 v[152:155], v168 offset:6144
	ds_read_b128 v[156:159], v171 offset:6144
	s_add_u32 m0, s99, 0x14000
	s_nop 0
	global_load_lds_dwordx4 v203, s[58:59]
	s_add_u32 m0, s99, 0x16000
	s_nop 0
	global_load_lds_dwordx4 v204, s[58:59]
	s_barrier
	s_waitcnt lgkmcnt(0)
	v_mfma_f32_16x16x32_bf16 v[112:115], v[128:131], v[160:163], v[112:115]
	v_mfma_f32_16x16x32_bf16 v[112:115], v[132:135], v[164:167], v[112:115]
	v_mfma_f32_16x16x32_bf16 v[116:119], v[128:131], v[172:175], v[116:119]
	v_mfma_f32_16x16x32_bf16 v[116:119], v[132:135], v[176:179], v[116:119]
	v_mfma_f32_16x16x32_bf16 v[120:123], v[136:139], v[160:163], v[120:123]
	v_mfma_f32_16x16x32_bf16 v[120:123], v[140:143], v[164:167], v[120:123]
	v_mfma_f32_16x16x32_bf16 v[124:127], v[136:139], v[172:175], v[124:127]
	v_mfma_f32_16x16x32_bf16 v[124:127], v[140:143], v[176:179], v[124:127]
	v_mfma_f32_16x16x32_bf16 v[96:99], v[144:147], v[160:163], v[96:99]
	v_mfma_f32_16x16x32_bf16 v[96:99], v[148:151], v[164:167], v[96:99]
	v_mfma_f32_16x16x32_bf16 v[100:103], v[144:147], v[172:175], v[100:103]
	v_mfma_f32_16x16x32_bf16 v[100:103], v[148:151], v[176:179], v[100:103]
	v_mfma_f32_16x16x32_bf16 v[104:107], v[152:155], v[160:163], v[104:107]
	v_mfma_f32_16x16x32_bf16 v[104:107], v[156:159], v[164:167], v[104:107]
	v_mfma_f32_16x16x32_bf16 v[108:111], v[152:155], v[172:175], v[108:111]
	v_mfma_f32_16x16x32_bf16 v[108:111], v[156:159], v[176:179], v[108:111]
	s_barrier
	ds_read_b128 v[180:183], v197 offset:16384
	ds_read_b128 v[184:187], v199 offset:16384
	ds_read_b128 v[188:191], v197 offset:18432
	ds_read_b128 v[192:195], v199 offset:18432
	s_barrier
	s_waitcnt lgkmcnt(0)
	v_mfma_f32_16x16x32_bf16 v[48:51], v[128:131], v[180:183], v[48:51]
	v_mfma_f32_16x16x32_bf16 v[48:51], v[132:135], v[184:187], v[48:51]
	v_mfma_f32_16x16x32_bf16 v[52:55], v[128:131], v[188:191], v[52:55]
	v_mfma_f32_16x16x32_bf16 v[52:55], v[132:135], v[192:195], v[52:55]
	v_mfma_f32_16x16x32_bf16 v[56:59], v[136:139], v[180:183], v[56:59]
	v_mfma_f32_16x16x32_bf16 v[56:59], v[140:143], v[184:187], v[56:59]
	v_mfma_f32_16x16x32_bf16 v[60:63], v[136:139], v[188:191], v[60:63]
	v_mfma_f32_16x16x32_bf16 v[60:63], v[140:143], v[192:195], v[60:63]
	v_mfma_f32_16x16x32_bf16 v[32:35], v[144:147], v[180:183], v[32:35]
	v_mfma_f32_16x16x32_bf16 v[32:35], v[148:151], v[184:187], v[32:35]
	v_mfma_f32_16x16x32_bf16 v[36:39], v[144:147], v[188:191], v[36:39]
	v_mfma_f32_16x16x32_bf16 v[36:39], v[148:151], v[192:195], v[36:39]
	v_mfma_f32_16x16x32_bf16 v[40:43], v[152:155], v[180:183], v[40:43]
	v_mfma_f32_16x16x32_bf16 v[40:43], v[156:159], v[184:187], v[40:43]
	v_mfma_f32_16x16x32_bf16 v[44:47], v[152:155], v[188:191], v[44:47]
	v_mfma_f32_16x16x32_bf16 v[44:47], v[156:159], v[192:195], v[44:47]
	s_barrier
	ds_read_b128 v[128:131], v168 offset:16384
	ds_read_b128 v[132:135], v171 offset:16384
	ds_read_b128 v[136:139], v168 offset:18432
	ds_read_b128 v[140:143], v171 offset:18432
	ds_read_b128 v[144:147], v168 offset:20480
	ds_read_b128 v[148:151], v171 offset:20480
	ds_read_b128 v[152:155], v168 offset:22528
	ds_read_b128 v[156:159], v171 offset:22528
	s_waitcnt vmcnt(4)
	s_barrier
	s_waitcnt lgkmcnt(0)
	v_mfma_f32_16x16x32_bf16 v[80:83], v[128:131], v[160:163], v[80:83]
	v_mfma_f32_16x16x32_bf16 v[80:83], v[132:135], v[164:167], v[80:83]
	v_mfma_f32_16x16x32_bf16 v[84:87], v[128:131], v[172:175], v[84:87]
	v_mfma_f32_16x16x32_bf16 v[84:87], v[132:135], v[176:179], v[84:87]
	v_mfma_f32_16x16x32_bf16 v[88:91], v[136:139], v[160:163], v[88:91]
	v_mfma_f32_16x16x32_bf16 v[88:91], v[140:143], v[164:167], v[88:91]
	v_mfma_f32_16x16x32_bf16 v[92:95], v[136:139], v[172:175], v[92:95]
	v_mfma_f32_16x16x32_bf16 v[92:95], v[140:143], v[176:179], v[92:95]
	v_mfma_f32_16x16x32_bf16 v[64:67], v[144:147], v[160:163], v[64:67]
	v_mfma_f32_16x16x32_bf16 v[64:67], v[148:151], v[164:167], v[64:67]
	v_mfma_f32_16x16x32_bf16 v[68:71], v[144:147], v[172:175], v[68:71]
	v_mfma_f32_16x16x32_bf16 v[68:71], v[148:151], v[176:179], v[68:71]
	v_mfma_f32_16x16x32_bf16 v[72:75], v[152:155], v[160:163], v[72:75]
	v_mfma_f32_16x16x32_bf16 v[72:75], v[156:159], v[164:167], v[72:75]
	v_mfma_f32_16x16x32_bf16 v[76:79], v[152:155], v[172:175], v[76:79]
	v_mfma_f32_16x16x32_bf16 v[76:79], v[156:159], v[176:179], v[76:79]
	v_mfma_f32_16x16x32_bf16 v[16:19], v[128:131], v[180:183], v[16:19]
	v_mfma_f32_16x16x32_bf16 v[16:19], v[132:135], v[184:187], v[16:19]
	v_mfma_f32_16x16x32_bf16 v[20:23], v[128:131], v[188:191], v[20:23]
	v_mfma_f32_16x16x32_bf16 v[20:23], v[132:135], v[192:195], v[20:23]
	v_mfma_f32_16x16x32_bf16 v[24:27], v[136:139], v[180:183], v[24:27]
	v_mfma_f32_16x16x32_bf16 v[24:27], v[140:143], v[184:187], v[24:27]
	v_mfma_f32_16x16x32_bf16 v[28:31], v[136:139], v[188:191], v[28:31]
	v_mfma_f32_16x16x32_bf16 v[28:31], v[140:143], v[192:195], v[28:31]
	v_mfma_f32_16x16x32_bf16 v[0:3], v[144:147], v[180:183], v[0:3]
	v_mfma_f32_16x16x32_bf16 v[0:3], v[148:151], v[184:187], v[0:3]
	v_mfma_f32_16x16x32_bf16 v[4:7], v[144:147], v[188:191], v[4:7]
	v_mfma_f32_16x16x32_bf16 v[4:7], v[148:151], v[192:195], v[4:7]
	v_mfma_f32_16x16x32_bf16 v[8:11], v[152:155], v[180:183], v[8:11]
	v_mfma_f32_16x16x32_bf16 v[8:11], v[156:159], v[184:187], v[8:11]
	v_mfma_f32_16x16x32_bf16 v[12:15], v[152:155], v[188:191], v[12:15]
	v_mfma_f32_16x16x32_bf16 v[12:15], v[156:159], v[192:195], v[12:15]
	s_barrier
	ds_read_b128 v[160:163], v198 offset:0
	ds_read_b128 v[164:167], v200 offset:0
	ds_read_b128 v[172:175], v198 offset:2048
	ds_read_b128 v[176:179], v200 offset:2048
	ds_read_b128 v[128:131], v170 offset:0
	ds_read_b128 v[132:135], v196 offset:0
	ds_read_b128 v[136:139], v170 offset:2048
	ds_read_b128 v[140:143], v196 offset:2048
	ds_read_b128 v[144:147], v170 offset:4096
	ds_read_b128 v[148:151], v196 offset:4096
	ds_read_b128 v[152:155], v170 offset:6144
	ds_read_b128 v[156:159], v196 offset:6144
	s_waitcnt vmcnt(2)
	s_barrier
	s_waitcnt lgkmcnt(0)
	v_mfma_f32_16x16x32_bf16 v[112:115], v[128:131], v[160:163], v[112:115]
	v_mfma_f32_16x16x32_bf16 v[112:115], v[132:135], v[164:167], v[112:115]
	v_mfma_f32_16x16x32_bf16 v[116:119], v[128:131], v[172:175], v[116:119]
	v_mfma_f32_16x16x32_bf16 v[116:119], v[132:135], v[176:179], v[116:119]
	v_mfma_f32_16x16x32_bf16 v[120:123], v[136:139], v[160:163], v[120:123]
	v_mfma_f32_16x16x32_bf16 v[120:123], v[140:143], v[164:167], v[120:123]
	v_mfma_f32_16x16x32_bf16 v[124:127], v[136:139], v[172:175], v[124:127]
	v_mfma_f32_16x16x32_bf16 v[124:127], v[140:143], v[176:179], v[124:127]
	v_mfma_f32_16x16x32_bf16 v[96:99], v[144:147], v[160:163], v[96:99]
	v_mfma_f32_16x16x32_bf16 v[96:99], v[148:151], v[164:167], v[96:99]
	v_mfma_f32_16x16x32_bf16 v[100:103], v[144:147], v[172:175], v[100:103]
	v_mfma_f32_16x16x32_bf16 v[100:103], v[148:151], v[176:179], v[100:103]
	v_mfma_f32_16x16x32_bf16 v[104:107], v[152:155], v[160:163], v[104:107]
	v_mfma_f32_16x16x32_bf16 v[104:107], v[156:159], v[164:167], v[104:107]
	v_mfma_f32_16x16x32_bf16 v[108:111], v[152:155], v[172:175], v[108:111]
	v_mfma_f32_16x16x32_bf16 v[108:111], v[156:159], v[176:179], v[108:111]
	s_barrier
	ds_read_b128 v[180:183], v198 offset:16384
	ds_read_b128 v[184:187], v200 offset:16384
	ds_read_b128 v[188:191], v198 offset:18432
	ds_read_b128 v[192:195], v200 offset:18432
	s_waitcnt vmcnt(0)
	s_barrier
	s_waitcnt lgkmcnt(0)
	v_mfma_f32_16x16x32_bf16 v[48:51], v[128:131], v[180:183], v[48:51]
	v_mfma_f32_16x16x32_bf16 v[48:51], v[132:135], v[184:187], v[48:51]
	v_mfma_f32_16x16x32_bf16 v[52:55], v[128:131], v[188:191], v[52:55]
	v_mfma_f32_16x16x32_bf16 v[52:55], v[132:135], v[192:195], v[52:55]
	v_mfma_f32_16x16x32_bf16 v[56:59], v[136:139], v[180:183], v[56:59]
	v_mfma_f32_16x16x32_bf16 v[56:59], v[140:143], v[184:187], v[56:59]
	v_mfma_f32_16x16x32_bf16 v[60:63], v[136:139], v[188:191], v[60:63]
	v_mfma_f32_16x16x32_bf16 v[60:63], v[140:143], v[192:195], v[60:63]
	v_mfma_f32_16x16x32_bf16 v[32:35], v[144:147], v[180:183], v[32:35]
	v_mfma_f32_16x16x32_bf16 v[32:35], v[148:151], v[184:187], v[32:35]
	v_mfma_f32_16x16x32_bf16 v[36:39], v[144:147], v[188:191], v[36:39]
	v_mfma_f32_16x16x32_bf16 v[36:39], v[148:151], v[192:195], v[36:39]
	v_mfma_f32_16x16x32_bf16 v[40:43], v[152:155], v[180:183], v[40:43]
	v_mfma_f32_16x16x32_bf16 v[40:43], v[156:159], v[184:187], v[40:43]
	v_mfma_f32_16x16x32_bf16 v[44:47], v[152:155], v[188:191], v[44:47]
	v_mfma_f32_16x16x32_bf16 v[44:47], v[156:159], v[192:195], v[44:47]
	s_barrier
	ds_read_b128 v[128:131], v170 offset:16384
	ds_read_b128 v[132:135], v196 offset:16384
	ds_read_b128 v[136:139], v170 offset:18432
	ds_read_b128 v[140:143], v196 offset:18432
	ds_read_b128 v[144:147], v170 offset:20480
	ds_read_b128 v[148:151], v196 offset:20480
	ds_read_b128 v[152:155], v170 offset:22528
	ds_read_b128 v[156:159], v196 offset:22528
	s_barrier
	s_waitcnt lgkmcnt(0)
	v_mfma_f32_16x16x32_bf16 v[80:83], v[128:131], v[160:163], v[80:83]
	v_mfma_f32_16x16x32_bf16 v[80:83], v[132:135], v[164:167], v[80:83]
	v_mfma_f32_16x16x32_bf16 v[84:87], v[128:131], v[172:175], v[84:87]
	v_mfma_f32_16x16x32_bf16 v[84:87], v[132:135], v[176:179], v[84:87]
	v_mfma_f32_16x16x32_bf16 v[88:91], v[136:139], v[160:163], v[88:91]
	v_mfma_f32_16x16x32_bf16 v[88:91], v[140:143], v[164:167], v[88:91]
	v_mfma_f32_16x16x32_bf16 v[92:95], v[136:139], v[172:175], v[92:95]
	v_mfma_f32_16x16x32_bf16 v[92:95], v[140:143], v[176:179], v[92:95]
	v_mfma_f32_16x16x32_bf16 v[64:67], v[144:147], v[160:163], v[64:67]
	v_mfma_f32_16x16x32_bf16 v[64:67], v[148:151], v[164:167], v[64:67]
	v_mfma_f32_16x16x32_bf16 v[68:71], v[144:147], v[172:175], v[68:71]
	v_mfma_f32_16x16x32_bf16 v[68:71], v[148:151], v[176:179], v[68:71]
	v_mfma_f32_16x16x32_bf16 v[72:75], v[152:155], v[160:163], v[72:75]
	v_mfma_f32_16x16x32_bf16 v[72:75], v[156:159], v[164:167], v[72:75]
	v_mfma_f32_16x16x32_bf16 v[76:79], v[152:155], v[172:175], v[76:79]
	v_mfma_f32_16x16x32_bf16 v[76:79], v[156:159], v[176:179], v[76:79]
	v_mfma_f32_16x16x32_bf16 v[16:19], v[128:131], v[180:183], v[16:19]
	v_mfma_f32_16x16x32_bf16 v[16:19], v[132:135], v[184:187], v[16:19]
	v_mfma_f32_16x16x32_bf16 v[20:23], v[128:131], v[188:191], v[20:23]
	v_mfma_f32_16x16x32_bf16 v[20:23], v[132:135], v[192:195], v[20:23]
	v_mfma_f32_16x16x32_bf16 v[24:27], v[136:139], v[180:183], v[24:27]
	v_mfma_f32_16x16x32_bf16 v[24:27], v[140:143], v[184:187], v[24:27]
	v_mfma_f32_16x16x32_bf16 v[28:31], v[136:139], v[188:191], v[28:31]
	v_mfma_f32_16x16x32_bf16 v[28:31], v[140:143], v[192:195], v[28:31]
	v_mfma_f32_16x16x32_bf16 v[0:3], v[144:147], v[180:183], v[0:3]
	v_mfma_f32_16x16x32_bf16 v[0:3], v[148:151], v[184:187], v[0:3]
	v_mfma_f32_16x16x32_bf16 v[4:7], v[144:147], v[188:191], v[4:7]
	v_mfma_f32_16x16x32_bf16 v[4:7], v[148:151], v[192:195], v[4:7]
	v_mfma_f32_16x16x32_bf16 v[8:11], v[152:155], v[180:183], v[8:11]
	v_mfma_f32_16x16x32_bf16 v[8:11], v[156:159], v[184:187], v[8:11]
	v_mfma_f32_16x16x32_bf16 v[12:15], v[152:155], v[188:191], v[12:15]
	v_mfma_f32_16x16x32_bf16 v[12:15], v[156:159], v[192:195], v[12:15]
	s_barrier
	s_cmp_lg_u32 s100, 0
	s_cbranch_scc1 .Lg8_p6g_gb1
	s_barrier

.Lg8_p6h_loop:
	ds_read_b128 v[160:163], v197 offset:0
	ds_read_b128 v[164:167], v199 offset:0
	ds_read_b128 v[172:175], v197 offset:2048
	ds_read_b128 v[176:179], v199 offset:2048
	ds_read_b128 v[128:131], v168 offset:0
	ds_read_b128 v[132:135], v171 offset:0
	ds_read_b128 v[136:139], v168 offset:2048
	ds_read_b128 v[140:143], v171 offset:2048
	ds_read_b128 v[144:147], v168 offset:4096
	ds_read_b128 v[148:151], v171 offset:4096
	ds_read_b128 v[152:155], v168 offset:6144
	ds_read_b128 v[156:159], v171 offset:6144
	s_add_u32 m0, s99, 0x14000
	s_nop 0
	global_load_lds_dwordx4 v203, s[56:57]
	s_add_u32 m0, s99, 0x16000
	s_nop 0
	global_load_lds_dwordx4 v204, s[56:57]
	s_waitcnt lgkmcnt(8)
	s_barrier
	s_waitcnt lgkmcnt(0)
	v_mfma_f32_16x16x32_bf16 v[0:3], v[128:131], v[160:163], v[0:3]
	v_mfma_f32_16x16x32_bf16 v[0:3], v[132:135], v[164:167], v[0:3]
	v_mfma_f32_16x16x32_bf16 v[4:7], v[128:131], v[172:175], v[4:7]
	v_mfma_f32_16x16x32_bf16 v[4:7], v[132:135], v[176:179], v[4:7]
	v_mfma_f32_16x16x32_bf16 v[8:11], v[136:139], v[160:163], v[8:11]
	v_mfma_f32_16x16x32_bf16 v[8:11], v[140:143], v[164:167], v[8:11]
	v_mfma_f32_16x16x32_bf16 v[12:15], v[136:139], v[172:175], v[12:15]
	v_mfma_f32_16x16x32_bf16 v[12:15], v[140:143], v[176:179], v[12:15]
	v_mfma_f32_16x16x32_bf16 v[112:115], v[144:147], v[160:163], v[112:115]
	v_mfma_f32_16x16x32_bf16 v[112:115], v[148:151], v[164:167], v[112:115]
	v_mfma_f32_16x16x32_bf16 v[116:119], v[144:147], v[172:175], v[116:119]
	v_mfma_f32_16x16x32_bf16 v[116:119], v[148:151], v[176:179], v[116:119]
	v_mfma_f32_16x16x32_bf16 v[120:123], v[152:155], v[160:163], v[120:123]
	v_mfma_f32_16x16x32_bf16 v[120:123], v[156:159], v[164:167], v[120:123]
	v_mfma_f32_16x16x32_bf16 v[124:127], v[152:155], v[172:175], v[124:127]
	v_mfma_f32_16x16x32_bf16 v[124:127], v[156:159], v[176:179], v[124:127]
	s_barrier
	ds_read_b128 v[180:183], v197 offset:16384
	ds_read_b128 v[184:187], v199 offset:16384
	ds_read_b128 v[188:191], v197 offset:18432
	ds_read_b128 v[192:195], v199 offset:18432
	s_add_u32 s54, s54, 0x80
	s_addc_u32 s55, s55, 0
	s_add_u32 m0, s99, 0x8000
	s_nop 0
	global_load_lds_dwordx4 v205, s[54:55]
	s_add_u32 m0, s99, 0xa000
	s_nop 0
	global_load_lds_dwordx4 v206, s[54:55]
	s_barrier
	s_waitcnt lgkmcnt(0)
	v_mfma_f32_16x16x32_bf16 v[64:67], v[128:131], v[180:183], v[64:67]
	v_mfma_f32_16x16x32_bf16 v[64:67], v[132:135], v[184:187], v[64:67]
	v_mfma_f32_16x16x32_bf16 v[68:71], v[128:131], v[188:191], v[68:71]
	v_mfma_f32_16x16x32_bf16 v[68:71], v[132:135], v[192:195], v[68:71]
	v_mfma_f32_16x16x32_bf16 v[72:75], v[136:139], v[180:183], v[72:75]
	v_mfma_f32_16x16x32_bf16 v[72:75], v[140:143], v[184:187], v[72:75]
	v_mfma_f32_16x16x32_bf16 v[76:79], v[136:139], v[188:191], v[76:79]
	v_mfma_f32_16x16x32_bf16 v[76:79], v[140:143], v[192:195], v[76:79]
	v_mfma_f32_16x16x32_bf16 v[48:51], v[144:147], v[180:183], v[48:51]
	v_mfma_f32_16x16x32_bf16 v[48:51], v[148:151], v[184:187], v[48:51]
	v_mfma_f32_16x16x32_bf16 v[52:55], v[144:147], v[188:191], v[52:55]
	v_mfma_f32_16x16x32_bf16 v[52:55], v[148:151], v[192:195], v[52:55]
	v_mfma_f32_16x16x32_bf16 v[56:59], v[152:155], v[180:183], v[56:59]
	v_mfma_f32_16x16x32_bf16 v[56:59], v[156:159], v[184:187], v[56:59]
	v_mfma_f32_16x16x32_bf16 v[60:63], v[152:155], v[188:191], v[60:63]
	v_mfma_f32_16x16x32_bf16 v[60:63], v[156:159], v[192:195], v[60:63]
	s_barrier
	ds_read_b128 v[128:131], v168 offset:16384
	ds_read_b128 v[132:135], v171 offset:16384
	ds_read_b128 v[136:139], v168 offset:18432
	ds_read_b128 v[140:143], v171 offset:18432
	ds_read_b128 v[144:147], v168 offset:20480
	ds_read_b128 v[148:151], v171 offset:20480
	ds_read_b128 v[152:155], v168 offset:22528
	ds_read_b128 v[156:159], v171 offset:22528
	s_add_u32 s56, s56, 0x80
	s_addc_u32 s57, s57, 0
	s_add_u32 m0, s99, 0x0
	s_nop 0
	global_load_lds_dwordx4 v201, s[56:57]
	s_add_u32 m0, s99, 0x2000
	s_nop 0
	global_load_lds_dwordx4 v202, s[56:57]
	s_barrier
	s_waitcnt lgkmcnt(0)
	v_mfma_f32_16x16x32_bf16 v[96:99], v[128:131], v[160:163], v[96:99]
	v_mfma_f32_16x16x32_bf16 v[96:99], v[132:135], v[164:167], v[96:99]
	v_mfma_f32_16x16x32_bf16 v[100:103], v[128:131], v[172:175], v[100:103]
	v_mfma_f32_16x16x32_bf16 v[100:103], v[132:135], v[176:179], v[100:103]
	v_mfma_f32_16x16x32_bf16 v[104:107], v[136:139], v[160:163], v[104:107]
	v_mfma_f32_16x16x32_bf16 v[104:107], v[140:143], v[164:167], v[104:107]
	v_mfma_f32_16x16x32_bf16 v[108:111], v[136:139], v[172:175], v[108:111]
	v_mfma_f32_16x16x32_bf16 v[108:111], v[140:143], v[176:179], v[108:111]
	v_mfma_f32_16x16x32_bf16 v[80:83], v[144:147], v[160:163], v[80:83]
	v_mfma_f32_16x16x32_bf16 v[80:83], v[148:151], v[164:167], v[80:83]
	v_mfma_f32_16x16x32_bf16 v[84:87], v[144:147], v[172:175], v[84:87]
	v_mfma_f32_16x16x32_bf16 v[84:87], v[148:151], v[176:179], v[84:87]
	v_mfma_f32_16x16x32_bf16 v[88:91], v[152:155], v[160:163], v[88:91]
	v_mfma_f32_16x16x32_bf16 v[88:91], v[156:159], v[164:167], v[88:91]
	v_mfma_f32_16x16x32_bf16 v[92:95], v[152:155], v[172:175], v[92:95]
	v_mfma_f32_16x16x32_bf16 v[92:95], v[156:159], v[176:179], v[92:95]
	s_barrier
	s_add_u32 m0, s99, 0xc000
	s_nop 0
	global_load_lds_dwordx4 v210, s[54:55]
	s_add_u32 m0, s99, 0xe000
	s_nop 0
	global_load_lds_dwordx4 v211, s[54:55]
	s_waitcnt vmcnt(6)
	s_barrier
	v_mfma_f32_16x16x32_bf16 v[32:35], v[128:131], v[180:183], v[32:35]
	v_mfma_f32_16x16x32_bf16 v[32:35], v[132:135], v[184:187], v[32:35]
	v_mfma_f32_16x16x32_bf16 v[36:39], v[128:131], v[188:191], v[36:39]
	v_mfma_f32_16x16x32_bf16 v[36:39], v[132:135], v[192:195], v[36:39]
	v_mfma_f32_16x16x32_bf16 v[40:43], v[136:139], v[180:183], v[40:43]
	v_mfma_f32_16x16x32_bf16 v[40:43], v[140:143], v[184:187], v[40:43]
	v_mfma_f32_16x16x32_bf16 v[44:47], v[136:139], v[188:191], v[44:47]
	v_mfma_f32_16x16x32_bf16 v[44:47], v[140:143], v[192:195], v[44:47]
	v_mfma_f32_16x16x32_bf16 v[16:19], v[144:147], v[180:183], v[16:19]
	v_mfma_f32_16x16x32_bf16 v[16:19], v[148:151], v[184:187], v[16:19]
	v_mfma_f32_16x16x32_bf16 v[20:23], v[144:147], v[188:191], v[20:23]
	v_mfma_f32_16x16x32_bf16 v[20:23], v[148:151], v[192:195], v[20:23]
	v_mfma_f32_16x16x32_bf16 v[24:27], v[152:155], v[180:183], v[24:27]
	v_mfma_f32_16x16x32_bf16 v[24:27], v[156:159], v[184:187], v[24:27]
	v_mfma_f32_16x16x32_bf16 v[28:31], v[152:155], v[188:191], v[28:31]
	v_mfma_f32_16x16x32_bf16 v[28:31], v[156:159], v[192:195], v[28:31]
	s_barrier
	ds_read_b128 v[160:163], v198 offset:0
	ds_read_b128 v[164:167], v200 offset:0
	ds_read_b128 v[172:175], v198 offset:2048
	ds_read_b128 v[176:179], v200 offset:2048
	ds_read_b128 v[128:131], v170 offset:0
	ds_read_b128 v[132:135], v196 offset:0
	ds_read_b128 v[136:139], v170 offset:2048
	ds_read_b128 v[140:143], v196 offset:2048
	ds_read_b128 v[144:147], v170 offset:4096
	ds_read_b128 v[148:151], v196 offset:4096
	ds_read_b128 v[152:155], v170 offset:6144
	ds_read_b128 v[156:159], v196 offset:6144
	s_add_u32 m0, s99, 0x4000
	s_nop 0
	global_load_lds_dwordx4 v203, s[56:57]
	s_add_u32 m0, s99, 0x6000
	s_nop 0
	global_load_lds_dwordx4 v204, s[56:57]
	s_waitcnt lgkmcnt(8)
	s_barrier
	s_waitcnt lgkmcnt(0)
	v_mfma_f32_16x16x32_bf16 v[0:3], v[128:131], v[160:163], v[0:3]
	v_mfma_f32_16x16x32_bf16 v[0:3], v[132:135], v[164:167], v[0:3]
	v_mfma_f32_16x16x32_bf16 v[4:7], v[128:131], v[172:175], v[4:7]
	v_mfma_f32_16x16x32_bf16 v[4:7], v[132:135], v[176:179], v[4:7]
	v_mfma_f32_16x16x32_bf16 v[8:11], v[136:139], v[160:163], v[8:11]
	v_mfma_f32_16x16x32_bf16 v[8:11], v[140:143], v[164:167], v[8:11]
	v_mfma_f32_16x16x32_bf16 v[12:15], v[136:139], v[172:175], v[12:15]
	v_mfma_f32_16x16x32_bf16 v[12:15], v[140:143], v[176:179], v[12:15]
	v_mfma_f32_16x16x32_bf16 v[112:115], v[144:147], v[160:163], v[112:115]
	v_mfma_f32_16x16x32_bf16 v[112:115], v[148:151], v[164:167], v[112:115]
	v_mfma_f32_16x16x32_bf16 v[116:119], v[144:147], v[172:175], v[116:119]
	v_mfma_f32_16x16x32_bf16 v[116:119], v[148:151], v[176:179], v[116:119]
	v_mfma_f32_16x16x32_bf16 v[120:123], v[152:155], v[160:163], v[120:123]
	v_mfma_f32_16x16x32_bf16 v[120:123], v[156:159], v[164:167], v[120:123]
	v_mfma_f32_16x16x32_bf16 v[124:127], v[152:155], v[172:175], v[124:127]
	v_mfma_f32_16x16x32_bf16 v[124:127], v[156:159], v[176:179], v[124:127]
	s_barrier
	ds_read_b128 v[180:183], v198 offset:16384
	ds_read_b128 v[184:187], v200 offset:16384
	ds_read_b128 v[188:191], v198 offset:18432
	ds_read_b128 v[192:195], v200 offset:18432
	s_add_u32 s54, s54, 0x80
	s_addc_u32 s55, s55, 0
	s_add_u32 m0, s99, 0x18000
	s_nop 0
	global_load_lds_dwordx4 v205, s[54:55]
	s_add_u32 m0, s99, 0x1a000
	s_nop 0
	global_load_lds_dwordx4 v206, s[54:55]
	s_barrier
	s_waitcnt lgkmcnt(0)
	v_mfma_f32_16x16x32_bf16 v[64:67], v[128:131], v[180:183], v[64:67]
	v_mfma_f32_16x16x32_bf16 v[64:67], v[132:135], v[184:187], v[64:67]
	v_mfma_f32_16x16x32_bf16 v[68:71], v[128:131], v[188:191], v[68:71]
	v_mfma_f32_16x16x32_bf16 v[68:71], v[132:135], v[192:195], v[68:71]
	v_mfma_f32_16x16x32_bf16 v[72:75], v[136:139], v[180:183], v[72:75]
	v_mfma_f32_16x16x32_bf16 v[72:75], v[140:143], v[184:187], v[72:75]
	v_mfma_f32_16x16x32_bf16 v[76:79], v[136:139], v[188:191], v[76:79]
	v_mfma_f32_16x16x32_bf16 v[76:79], v[140:143], v[192:195], v[76:79]
	v_mfma_f32_16x16x32_bf16 v[48:51], v[144:147], v[180:183], v[48:51]
	v_mfma_f32_16x16x32_bf16 v[48:51], v[148:151], v[184:187], v[48:51]
	v_mfma_f32_16x16x32_bf16 v[52:55], v[144:147], v[188:191], v[52:55]
	v_mfma_f32_16x16x32_bf16 v[52:55], v[148:151], v[192:195], v[52:55]
	v_mfma_f32_16x16x32_bf16 v[56:59], v[152:155], v[180:183], v[56:59]
	v_mfma_f32_16x16x32_bf16 v[56:59], v[156:159], v[184:187], v[56:59]
	v_mfma_f32_16x16x32_bf16 v[60:63], v[152:155], v[188:191], v[60:63]
	v_mfma_f32_16x16x32_bf16 v[60:63], v[156:159], v[192:195], v[60:63]
	s_barrier
	ds_read_b128 v[128:131], v170 offset:16384
	ds_read_b128 v[132:135], v196 offset:16384
	ds_read_b128 v[136:139], v170 offset:18432
	ds_read_b128 v[140:143], v196 offset:18432
	ds_read_b128 v[144:147], v170 offset:20480
	ds_read_b128 v[148:151], v196 offset:20480
	ds_read_b128 v[152:155], v170 offset:22528
	ds_read_b128 v[156:159], v196 offset:22528
	s_add_u32 s56, s56, 0x80
	s_addc_u32 s57, s57, 0
	s_add_u32 m0, s99, 0x10000
	s_nop 0
	global_load_lds_dwordx4 v201, s[56:57]
	s_add_u32 m0, s99, 0x12000
	s_nop 0
	global_load_lds_dwordx4 v202, s[56:57]
	s_barrier
	s_waitcnt lgkmcnt(0)
	v_mfma_f32_16x16x32_bf16 v[96:99], v[128:131], v[160:163], v[96:99]
	v_mfma_f32_16x16x32_bf16 v[96:99], v[132:135], v[164:167], v[96:99]
	v_mfma_f32_16x16x32_bf16 v[100:103], v[128:131], v[172:175], v[100:103]
	v_mfma_f32_16x16x32_bf16 v[100:103], v[132:135], v[176:179], v[100:103]
	v_mfma_f32_16x16x32_bf16 v[104:107], v[136:139], v[160:163], v[104:107]
	v_mfma_f32_16x16x32_bf16 v[104:107], v[140:143], v[164:167], v[104:107]
	v_mfma_f32_16x16x32_bf16 v[108:111], v[136:139], v[172:175], v[108:111]
	v_mfma_f32_16x16x32_bf16 v[108:111], v[140:143], v[176:179], v[108:111]
	v_mfma_f32_16x16x32_bf16 v[80:83], v[144:147], v[160:163], v[80:83]
	v_mfma_f32_16x16x32_bf16 v[80:83], v[148:151], v[164:167], v[80:83]
	v_mfma_f32_16x16x32_bf16 v[84:87], v[144:147], v[172:175], v[84:87]
	v_mfma_f32_16x16x32_bf16 v[84:87], v[148:151], v[176:179], v[84:87]
	v_mfma_f32_16x16x32_bf16 v[88:91], v[152:155], v[160:163], v[88:91]
	v_mfma_f32_16x16x32_bf16 v[88:91], v[156:159], v[164:167], v[88:91]
	v_mfma_f32_16x16x32_bf16 v[92:95], v[152:155], v[172:175], v[92:95]
	v_mfma_f32_16x16x32_bf16 v[92:95], v[156:159], v[176:179], v[92:95]
	s_barrier
	s_add_u32 m0, s99, 0x1c000
	s_nop 0
	global_load_lds_dwordx4 v210, s[54:55]
	s_add_u32 m0, s99, 0x1e000
	s_nop 0
	global_load_lds_dwordx4 v211, s[54:55]
	s_waitcnt vmcnt(6)
	s_barrier
	v_mfma_f32_16x16x32_bf16 v[32:35], v[128:131], v[180:183], v[32:35]
	v_mfma_f32_16x16x32_bf16 v[32:35], v[132:135], v[184:187], v[32:35]
	v_mfma_f32_16x16x32_bf16 v[36:39], v[128:131], v[188:191], v[36:39]
	v_mfma_f32_16x16x32_bf16 v[36:39], v[132:135], v[192:195], v[36:39]
	v_mfma_f32_16x16x32_bf16 v[40:43], v[136:139], v[180:183], v[40:43]
	v_mfma_f32_16x16x32_bf16 v[40:43], v[140:143], v[184:187], v[40:43]
	v_mfma_f32_16x16x32_bf16 v[44:47], v[136:139], v[188:191], v[44:47]
	v_mfma_f32_16x16x32_bf16 v[44:47], v[140:143], v[192:195], v[44:47]
	v_mfma_f32_16x16x32_bf16 v[16:19], v[144:147], v[180:183], v[16:19]
	v_mfma_f32_16x16x32_bf16 v[16:19], v[148:151], v[184:187], v[16:19]
	v_mfma_f32_16x16x32_bf16 v[20:23], v[144:147], v[188:191], v[20:23]
	v_mfma_f32_16x16x32_bf16 v[20:23], v[148:151], v[192:195], v[20:23]
	v_mfma_f32_16x16x32_bf16 v[24:27], v[152:155], v[180:183], v[24:27]
	v_mfma_f32_16x16x32_bf16 v[24:27], v[156:159], v[184:187], v[24:27]
	v_mfma_f32_16x16x32_bf16 v[28:31], v[152:155], v[188:191], v[28:31]
	v_mfma_f32_16x16x32_bf16 v[28:31], v[156:159], v[192:195], v[28:31]
	s_barrier
	s_sub_u32 s101, s101, 1
	s_cmp_lg_u32 s101, 0
	s_cbranch_scc1 .Lg8_p6h_loop
	ds_read_b128 v[160:163], v197 offset:0
	ds_read_b128 v[164:167], v199 offset:0
	ds_read_b128 v[172:175], v197 offset:2048
	ds_read_b128 v[176:179], v199 offset:2048
	ds_read_b128 v[128:131], v168 offset:0
	ds_read_b128 v[132:135], v171 offset:0
	ds_read_b128 v[136:139], v168 offset:2048
	ds_read_b128 v[140:143], v171 offset:2048
	ds_read_b128 v[144:147], v168 offset:4096
	ds_read_b128 v[148:151], v171 offset:4096
	ds_read_b128 v[152:155], v168 offset:6144
	ds_read_b128 v[156:159], v171 offset:6144
	s_add_u32 m0, s99, 0x14000
	s_nop 0
	global_load_lds_dwordx4 v203, s[56:57]
	s_add_u32 m0, s99, 0x16000
	s_nop 0
	global_load_lds_dwordx4 v204, s[56:57]
	s_barrier
	s_waitcnt lgkmcnt(0)
	v_mfma_f32_16x16x32_bf16 v[0:3], v[128:131], v[160:163], v[0:3]
	v_mfma_f32_16x16x32_bf16 v[0:3], v[132:135], v[164:167], v[0:3]
	v_mfma_f32_16x16x32_bf16 v[4:7], v[128:131], v[172:175], v[4:7]
	v_mfma_f32_16x16x32_bf16 v[4:7], v[132:135], v[176:179], v[4:7]
	v_mfma_f32_16x16x32_bf16 v[8:11], v[136:139], v[160:163], v[8:11]
	v_mfma_f32_16x16x32_bf16 v[8:11], v[140:143], v[164:167], v[8:11]
	v_mfma_f32_16x16x32_bf16 v[12:15], v[136:139], v[172:175], v[12:15]
	v_mfma_f32_16x16x32_bf16 v[12:15], v[140:143], v[176:179], v[12:15]
	v_mfma_f32_16x16x32_bf16 v[112:115], v[144:147], v[160:163], v[112:115]
	v_mfma_f32_16x16x32_bf16 v[112:115], v[148:151], v[164:167], v[112:115]
	v_mfma_f32_16x16x32_bf16 v[116:119], v[144:147], v[172:175], v[116:119]
	v_mfma_f32_16x16x32_bf16 v[116:119], v[148:151], v[176:179], v[116:119]
	v_mfma_f32_16x16x32_bf16 v[120:123], v[152:155], v[160:163], v[120:123]
	v_mfma_f32_16x16x32_bf16 v[120:123], v[156:159], v[164:167], v[120:123]
	v_mfma_f32_16x16x32_bf16 v[124:127], v[152:155], v[172:175], v[124:127]
	v_mfma_f32_16x16x32_bf16 v[124:127], v[156:159], v[176:179], v[124:127]
	s_barrier
	ds_read_b128 v[180:183], v197 offset:16384
	ds_read_b128 v[184:187], v199 offset:16384
	ds_read_b128 v[188:191], v197 offset:18432
	ds_read_b128 v[192:195], v199 offset:18432
	s_barrier
	s_waitcnt lgkmcnt(0)
	v_mfma_f32_16x16x32_bf16 v[64:67], v[128:131], v[180:183], v[64:67]
	v_mfma_f32_16x16x32_bf16 v[64:67], v[132:135], v[184:187], v[64:67]
	v_mfma_f32_16x16x32_bf16 v[68:71], v[128:131], v[188:191], v[68:71]
	v_mfma_f32_16x16x32_bf16 v[68:71], v[132:135], v[192:195], v[68:71]
	v_mfma_f32_16x16x32_bf16 v[72:75], v[136:139], v[180:183], v[72:75]
	v_mfma_f32_16x16x32_bf16 v[72:75], v[140:143], v[184:187], v[72:75]
	v_mfma_f32_16x16x32_bf16 v[76:79], v[136:139], v[188:191], v[76:79]
	v_mfma_f32_16x16x32_bf16 v[76:79], v[140:143], v[192:195], v[76:79]
	v_mfma_f32_16x16x32_bf16 v[48:51], v[144:147], v[180:183], v[48:51]
	v_mfma_f32_16x16x32_bf16 v[48:51], v[148:151], v[184:187], v[48:51]
	v_mfma_f32_16x16x32_bf16 v[52:55], v[144:147], v[188:191], v[52:55]
	v_mfma_f32_16x16x32_bf16 v[52:55], v[148:151], v[192:195], v[52:55]
	v_mfma_f32_16x16x32_bf16 v[56:59], v[152:155], v[180:183], v[56:59]
	v_mfma_f32_16x16x32_bf16 v[56:59], v[156:159], v[184:187], v[56:59]
	v_mfma_f32_16x16x32_bf16 v[60:63], v[152:155], v[188:191], v[60:63]
	v_mfma_f32_16x16x32_bf16 v[60:63], v[156:159], v[192:195], v[60:63]
	s_barrier
	ds_read_b128 v[128:131], v168 offset:16384
	ds_read_b128 v[132:135], v171 offset:16384
	ds_read_b128 v[136:139], v168 offset:18432
	ds_read_b128 v[140:143], v171 offset:18432
	ds_read_b128 v[144:147], v168 offset:20480
	ds_read_b128 v[148:151], v171 offset:20480
	ds_read_b128 v[152:155], v168 offset:22528
	ds_read_b128 v[156:159], v171 offset:22528
	s_waitcnt vmcnt(4)
	s_barrier
	s_waitcnt lgkmcnt(0)
	v_mfma_f32_16x16x32_bf16 v[96:99], v[128:131], v[160:163], v[96:99]
	v_mfma_f32_16x16x32_bf16 v[96:99], v[132:135], v[164:167], v[96:99]
	v_mfma_f32_16x16x32_bf16 v[100:103], v[128:131], v[172:175], v[100:103]
	v_mfma_f32_16x16x32_bf16 v[100:103], v[132:135], v[176:179], v[100:103]
	v_mfma_f32_16x16x32_bf16 v[104:107], v[136:139], v[160:163], v[104:107]
	v_mfma_f32_16x16x32_bf16 v[104:107], v[140:143], v[164:167], v[104:107]
	v_mfma_f32_16x16x32_bf16 v[108:111], v[136:139], v[172:175], v[108:111]
	v_mfma_f32_16x16x32_bf16 v[108:111], v[140:143], v[176:179], v[108:111]
	v_mfma_f32_16x16x32_bf16 v[80:83], v[144:147], v[160:163], v[80:83]
	v_mfma_f32_16x16x32_bf16 v[80:83], v[148:151], v[164:167], v[80:83]
	v_mfma_f32_16x16x32_bf16 v[84:87], v[144:147], v[172:175], v[84:87]
	v_mfma_f32_16x16x32_bf16 v[84:87], v[148:151], v[176:179], v[84:87]
	v_mfma_f32_16x16x32_bf16 v[88:91], v[152:155], v[160:163], v[88:91]
	v_mfma_f32_16x16x32_bf16 v[88:91], v[156:159], v[164:167], v[88:91]
	v_mfma_f32_16x16x32_bf16 v[92:95], v[152:155], v[172:175], v[92:95]
	v_mfma_f32_16x16x32_bf16 v[92:95], v[156:159], v[176:179], v[92:95]
	v_mfma_f32_16x16x32_bf16 v[32:35], v[128:131], v[180:183], v[32:35]
	v_mfma_f32_16x16x32_bf16 v[32:35], v[132:135], v[184:187], v[32:35]
	v_mfma_f32_16x16x32_bf16 v[36:39], v[128:131], v[188:191], v[36:39]
	v_mfma_f32_16x16x32_bf16 v[36:39], v[132:135], v[192:195], v[36:39]
	v_mfma_f32_16x16x32_bf16 v[40:43], v[136:139], v[180:183], v[40:43]
	v_mfma_f32_16x16x32_bf16 v[40:43], v[140:143], v[184:187], v[40:43]
	v_mfma_f32_16x16x32_bf16 v[44:47], v[136:139], v[188:191], v[44:47]
	v_mfma_f32_16x16x32_bf16 v[44:47], v[140:143], v[192:195], v[44:47]
	v_mfma_f32_16x16x32_bf16 v[16:19], v[144:147], v[180:183], v[16:19]
	v_mfma_f32_16x16x32_bf16 v[16:19], v[148:151], v[184:187], v[16:19]
	v_mfma_f32_16x16x32_bf16 v[20:23], v[144:147], v[188:191], v[20:23]
	v_mfma_f32_16x16x32_bf16 v[20:23], v[148:151], v[192:195], v[20:23]
	v_mfma_f32_16x16x32_bf16 v[24:27], v[152:155], v[180:183], v[24:27]
	v_mfma_f32_16x16x32_bf16 v[24:27], v[156:159], v[184:187], v[24:27]
	v_mfma_f32_16x16x32_bf16 v[28:31], v[152:155], v[188:191], v[28:31]
	v_mfma_f32_16x16x32_bf16 v[28:31], v[156:159], v[192:195], v[28:31]
	s_barrier
	ds_read_b128 v[160:163], v198 offset:0
	ds_read_b128 v[164:167], v200 offset:0
	ds_read_b128 v[172:175], v198 offset:2048
	ds_read_b128 v[176:179], v200 offset:2048
	ds_read_b128 v[128:131], v170 offset:0
	ds_read_b128 v[132:135], v196 offset:0
	ds_read_b128 v[136:139], v170 offset:2048
	ds_read_b128 v[140:143], v196 offset:2048
	ds_read_b128 v[144:147], v170 offset:4096
	ds_read_b128 v[148:151], v196 offset:4096
	ds_read_b128 v[152:155], v170 offset:6144
	ds_read_b128 v[156:159], v196 offset:6144
	s_waitcnt vmcnt(2)
	s_barrier
	s_waitcnt lgkmcnt(0)
	v_mfma_f32_16x16x32_bf16 v[0:3], v[128:131], v[160:163], v[0:3]
	v_mfma_f32_16x16x32_bf16 v[0:3], v[132:135], v[164:167], v[0:3]
	v_mfma_f32_16x16x32_bf16 v[4:7], v[128:131], v[172:175], v[4:7]
	v_mfma_f32_16x16x32_bf16 v[4:7], v[132:135], v[176:179], v[4:7]
	v_mfma_f32_16x16x32_bf16 v[8:11], v[136:139], v[160:163], v[8:11]
	v_mfma_f32_16x16x32_bf16 v[8:11], v[140:143], v[164:167], v[8:11]
	v_mfma_f32_16x16x32_bf16 v[12:15], v[136:139], v[172:175], v[12:15]
	v_mfma_f32_16x16x32_bf16 v[12:15], v[140:143], v[176:179], v[12:15]
	v_mfma_f32_16x16x32_bf16 v[112:115], v[144:147], v[160:163], v[112:115]
	v_mfma_f32_16x16x32_bf16 v[112:115], v[148:151], v[164:167], v[112:115]
	v_mfma_f32_16x16x32_bf16 v[116:119], v[144:147], v[172:175], v[116:119]
	v_mfma_f32_16x16x32_bf16 v[116:119], v[148:151], v[176:179], v[116:119]
	v_mfma_f32_16x16x32_bf16 v[120:123], v[152:155], v[160:163], v[120:123]
	v_mfma_f32_16x16x32_bf16 v[120:123], v[156:159], v[164:167], v[120:123]
	v_mfma_f32_16x16x32_bf16 v[124:127], v[152:155], v[172:175], v[124:127]
	v_mfma_f32_16x16x32_bf16 v[124:127], v[156:159], v[176:179], v[124:127]
	s_barrier
	ds_read_b128 v[180:183], v198 offset:16384
	ds_read_b128 v[184:187], v200 offset:16384
	ds_read_b128 v[188:191], v198 offset:18432
	ds_read_b128 v[192:195], v200 offset:18432
	s_waitcnt vmcnt(0)
	s_barrier
	s_waitcnt lgkmcnt(0)
	v_mfma_f32_16x16x32_bf16 v[64:67], v[128:131], v[180:183], v[64:67]
	v_mfma_f32_16x16x32_bf16 v[64:67], v[132:135], v[184:187], v[64:67]
	v_mfma_f32_16x16x32_bf16 v[68:71], v[128:131], v[188:191], v[68:71]
	v_mfma_f32_16x16x32_bf16 v[68:71], v[132:135], v[192:195], v[68:71]
	v_mfma_f32_16x16x32_bf16 v[72:75], v[136:139], v[180:183], v[72:75]
	v_mfma_f32_16x16x32_bf16 v[72:75], v[140:143], v[184:187], v[72:75]
	v_mfma_f32_16x16x32_bf16 v[76:79], v[136:139], v[188:191], v[76:79]
	v_mfma_f32_16x16x32_bf16 v[76:79], v[140:143], v[192:195], v[76:79]
	v_mfma_f32_16x16x32_bf16 v[48:51], v[144:147], v[180:183], v[48:51]
	v_mfma_f32_16x16x32_bf16 v[48:51], v[148:151], v[184:187], v[48:51]
	v_mfma_f32_16x16x32_bf16 v[52:55], v[144:147], v[188:191], v[52:55]
	v_mfma_f32_16x16x32_bf16 v[52:55], v[148:151], v[192:195], v[52:55]
	v_mfma_f32_16x16x32_bf16 v[56:59], v[152:155], v[180:183], v[56:59]
	v_mfma_f32_16x16x32_bf16 v[56:59], v[156:159], v[184:187], v[56:59]
	v_mfma_f32_16x16x32_bf16 v[60:63], v[152:155], v[188:191], v[60:63]
	v_mfma_f32_16x16x32_bf16 v[60:63], v[156:159], v[192:195], v[60:63]
	s_barrier
	ds_read_b128 v[128:131], v170 offset:16384
	ds_read_b128 v[132:135], v196 offset:16384
	ds_read_b128 v[136:139], v170 offset:18432
	ds_read_b128 v[140:143], v196 offset:18432
	ds_read_b128 v[144:147], v170 offset:20480
	ds_read_b128 v[148:151], v196 offset:20480
	ds_read_b128 v[152:155], v170 offset:22528
	ds_read_b128 v[156:159], v196 offset:22528
	s_barrier
	s_waitcnt lgkmcnt(0)
	v_mfma_f32_16x16x32_bf16 v[96:99], v[128:131], v[160:163], v[96:99]
	v_mfma_f32_16x16x32_bf16 v[96:99], v[132:135], v[164:167], v[96:99]
	v_mfma_f32_16x16x32_bf16 v[100:103], v[128:131], v[172:175], v[100:103]
	v_mfma_f32_16x16x32_bf16 v[100:103], v[132:135], v[176:179], v[100:103]
	v_mfma_f32_16x16x32_bf16 v[104:107], v[136:139], v[160:163], v[104:107]
	v_mfma_f32_16x16x32_bf16 v[104:107], v[140:143], v[164:167], v[104:107]
	v_mfma_f32_16x16x32_bf16 v[108:111], v[136:139], v[172:175], v[108:111]
	v_mfma_f32_16x16x32_bf16 v[108:111], v[140:143], v[176:179], v[108:111]
	v_mfma_f32_16x16x32_bf16 v[80:83], v[144:147], v[160:163], v[80:83]
	v_mfma_f32_16x16x32_bf16 v[80:83], v[148:151], v[164:167], v[80:83]
	v_mfma_f32_16x16x32_bf16 v[84:87], v[144:147], v[172:175], v[84:87]
	v_mfma_f32_16x16x32_bf16 v[84:87], v[148:151], v[176:179], v[84:87]
	v_mfma_f32_16x16x32_bf16 v[88:91], v[152:155], v[160:163], v[88:91]
	v_mfma_f32_16x16x32_bf16 v[88:91], v[156:159], v[164:167], v[88:91]
	v_mfma_f32_16x16x32_bf16 v[92:95], v[152:155], v[172:175], v[92:95]
	v_mfma_f32_16x16x32_bf16 v[92:95], v[156:159], v[176:179], v[92:95]
	v_mfma_f32_16x16x32_bf16 v[32:35], v[128:131], v[180:183], v[32:35]
	v_mfma_f32_16x16x32_bf16 v[32:35], v[132:135], v[184:187], v[32:35]
	v_mfma_f32_16x16x32_bf16 v[36:39], v[128:131], v[188:191], v[36:39]
	v_mfma_f32_16x16x32_bf16 v[36:39], v[132:135], v[192:195], v[36:39]
	v_mfma_f32_16x16x32_bf16 v[40:43], v[136:139], v[180:183], v[40:43]
	v_mfma_f32_16x16x32_bf16 v[40:43], v[140:143], v[184:187], v[40:43]
	v_mfma_f32_16x16x32_bf16 v[44:47], v[136:139], v[188:191], v[44:47]
	v_mfma_f32_16x16x32_bf16 v[44:47], v[140:143], v[192:195], v[44:47]
	v_mfma_f32_16x16x32_bf16 v[16:19], v[144:147], v[180:183], v[16:19]
	v_mfma_f32_16x16x32_bf16 v[16:19], v[148:151], v[184:187], v[16:19]
	v_mfma_f32_16x16x32_bf16 v[20:23], v[144:147], v[188:191], v[20:23]
	v_mfma_f32_16x16x32_bf16 v[20:23], v[148:151], v[192:195], v[20:23]
	v_mfma_f32_16x16x32_bf16 v[24:27], v[152:155], v[180:183], v[24:27]
	v_mfma_f32_16x16x32_bf16 v[24:27], v[156:159], v[184:187], v[24:27]
	v_mfma_f32_16x16x32_bf16 v[28:31], v[152:155], v[188:191], v[28:31]
	v_mfma_f32_16x16x32_bf16 v[28:31], v[156:159], v[192:195], v[28:31]
	s_barrier
	s_cmp_lg_u32 s100, 0
	s_cbranch_scc1 .Lg8_p6h_gb1
	s_barrier

.Lg8_p7_loop:
	ds_read_b128 v[160:163], v197 offset:0
	ds_read_b128 v[164:167], v199 offset:0
	ds_read_b128 v[172:175], v197 offset:2048
	ds_read_b128 v[176:179], v199 offset:2048
	ds_read_b128 v[128:131], v168 offset:0
	ds_read_b128 v[132:135], v171 offset:0
	ds_read_b128 v[136:139], v168 offset:2048
	ds_read_b128 v[140:143], v171 offset:2048
	ds_read_b128 v[144:147], v168 offset:4096
	ds_read_b128 v[148:151], v171 offset:4096
	ds_read_b128 v[152:155], v168 offset:6144
	ds_read_b128 v[156:159], v171 offset:6144
	s_add_u32 m0, s99, 0x14000
	s_nop 0
	global_load_lds_dwordx4 v203, s[72:73]
	s_add_u32 m0, s99, 0x16000
	s_nop 0
	global_load_lds_dwordx4 v204, s[72:73]
	s_waitcnt lgkmcnt(8)
	s_barrier
	s_waitcnt lgkmcnt(0)
	v_mfma_f32_16x16x32_bf16 v[112:115], v[128:131], v[160:163], v[112:115]
	v_mfma_f32_16x16x32_bf16 v[112:115], v[132:135], v[164:167], v[112:115]
	v_mfma_f32_16x16x32_bf16 v[116:119], v[128:131], v[172:175], v[116:119]
	v_mfma_f32_16x16x32_bf16 v[116:119], v[132:135], v[176:179], v[116:119]
	v_mfma_f32_16x16x32_bf16 v[120:123], v[136:139], v[160:163], v[120:123]
	v_mfma_f32_16x16x32_bf16 v[120:123], v[140:143], v[164:167], v[120:123]
	v_mfma_f32_16x16x32_bf16 v[124:127], v[136:139], v[172:175], v[124:127]
	v_mfma_f32_16x16x32_bf16 v[124:127], v[140:143], v[176:179], v[124:127]
	v_mfma_f32_16x16x32_bf16 v[96:99], v[144:147], v[160:163], v[96:99]
	v_mfma_f32_16x16x32_bf16 v[96:99], v[148:151], v[164:167], v[96:99]
	v_mfma_f32_16x16x32_bf16 v[100:103], v[144:147], v[172:175], v[100:103]
	v_mfma_f32_16x16x32_bf16 v[100:103], v[148:151], v[176:179], v[100:103]
	v_mfma_f32_16x16x32_bf16 v[104:107], v[152:155], v[160:163], v[104:107]
	v_mfma_f32_16x16x32_bf16 v[104:107], v[156:159], v[164:167], v[104:107]
	v_mfma_f32_16x16x32_bf16 v[108:111], v[152:155], v[172:175], v[108:111]
	v_mfma_f32_16x16x32_bf16 v[108:111], v[156:159], v[176:179], v[108:111]
	s_barrier
	ds_read_b128 v[180:183], v197 offset:16384
	ds_read_b128 v[184:187], v199 offset:16384
	ds_read_b128 v[188:191], v197 offset:18432
	ds_read_b128 v[192:195], v199 offset:18432
	s_add_u32 s70, s70, 0x80
	s_addc_u32 s71, s71, 0
	s_add_u32 m0, s99, 0x8000
	s_nop 0
	global_load_lds_dwordx4 v205, s[70:71]
	s_add_u32 m0, s99, 0xa000
	s_nop 0
	global_load_lds_dwordx4 v206, s[70:71]
	s_barrier
	s_waitcnt lgkmcnt(0)
	v_mfma_f32_16x16x32_bf16 v[48:51], v[128:131], v[180:183], v[48:51]
	v_mfma_f32_16x16x32_bf16 v[48:51], v[132:135], v[184:187], v[48:51]
	v_mfma_f32_16x16x32_bf16 v[52:55], v[128:131], v[188:191], v[52:55]
	v_mfma_f32_16x16x32_bf16 v[52:55], v[132:135], v[192:195], v[52:55]
	v_mfma_f32_16x16x32_bf16 v[56:59], v[136:139], v[180:183], v[56:59]
	v_mfma_f32_16x16x32_bf16 v[56:59], v[140:143], v[184:187], v[56:59]
	v_mfma_f32_16x16x32_bf16 v[60:63], v[136:139], v[188:191], v[60:63]
	v_mfma_f32_16x16x32_bf16 v[60:63], v[140:143], v[192:195], v[60:63]
	v_mfma_f32_16x16x32_bf16 v[32:35], v[144:147], v[180:183], v[32:35]
	v_mfma_f32_16x16x32_bf16 v[32:35], v[148:151], v[184:187], v[32:35]
	v_mfma_f32_16x16x32_bf16 v[36:39], v[144:147], v[188:191], v[36:39]
	v_mfma_f32_16x16x32_bf16 v[36:39], v[148:151], v[192:195], v[36:39]
	v_mfma_f32_16x16x32_bf16 v[40:43], v[152:155], v[180:183], v[40:43]
	v_mfma_f32_16x16x32_bf16 v[40:43], v[156:159], v[184:187], v[40:43]
	v_mfma_f32_16x16x32_bf16 v[44:47], v[152:155], v[188:191], v[44:47]
	v_mfma_f32_16x16x32_bf16 v[44:47], v[156:159], v[192:195], v[44:47]
	s_barrier
	ds_read_b128 v[128:131], v168 offset:16384
	ds_read_b128 v[132:135], v171 offset:16384
	ds_read_b128 v[136:139], v168 offset:18432
	ds_read_b128 v[140:143], v171 offset:18432
	ds_read_b128 v[144:147], v168 offset:20480
	ds_read_b128 v[148:151], v171 offset:20480
	ds_read_b128 v[152:155], v168 offset:22528
	ds_read_b128 v[156:159], v171 offset:22528
	s_add_u32 s72, s72, 0x80
	s_addc_u32 s73, s73, 0
	s_add_u32 m0, s99, 0x0
	s_nop 0
	global_load_lds_dwordx4 v201, s[72:73]
	s_add_u32 m0, s99, 0x2000
	s_nop 0
	global_load_lds_dwordx4 v202, s[72:73]
	s_barrier
	s_waitcnt lgkmcnt(0)
	v_mfma_f32_16x16x32_bf16 v[80:83], v[128:131], v[160:163], v[80:83]
	v_mfma_f32_16x16x32_bf16 v[80:83], v[132:135], v[164:167], v[80:83]
	v_mfma_f32_16x16x32_bf16 v[84:87], v[128:131], v[172:175], v[84:87]
	v_mfma_f32_16x16x32_bf16 v[84:87], v[132:135], v[176:179], v[84:87]
	v_mfma_f32_16x16x32_bf16 v[88:91], v[136:139], v[160:163], v[88:91]
	v_mfma_f32_16x16x32_bf16 v[88:91], v[140:143], v[164:167], v[88:91]
	v_mfma_f32_16x16x32_bf16 v[92:95], v[136:139], v[172:175], v[92:95]
	v_mfma_f32_16x16x32_bf16 v[92:95], v[140:143], v[176:179], v[92:95]
	v_mfma_f32_16x16x32_bf16 v[64:67], v[144:147], v[160:163], v[64:67]
	v_mfma_f32_16x16x32_bf16 v[64:67], v[148:151], v[164:167], v[64:67]
	v_mfma_f32_16x16x32_bf16 v[68:71], v[144:147], v[172:175], v[68:71]
	v_mfma_f32_16x16x32_bf16 v[68:71], v[148:151], v[176:179], v[68:71]
	v_mfma_f32_16x16x32_bf16 v[72:75], v[152:155], v[160:163], v[72:75]
	v_mfma_f32_16x16x32_bf16 v[72:75], v[156:159], v[164:167], v[72:75]
	v_mfma_f32_16x16x32_bf16 v[76:79], v[152:155], v[172:175], v[76:79]
	v_mfma_f32_16x16x32_bf16 v[76:79], v[156:159], v[176:179], v[76:79]
	s_barrier
	s_add_u32 m0, s99, 0xc000
	s_nop 0
	global_load_lds_dwordx4 v210, s[70:71]
	s_add_u32 m0, s99, 0xe000
	s_nop 0
	global_load_lds_dwordx4 v211, s[70:71]
	s_waitcnt vmcnt(6)
	s_barrier
	v_mfma_f32_16x16x32_bf16 v[16:19], v[128:131], v[180:183], v[16:19]
	v_mfma_f32_16x16x32_bf16 v[16:19], v[132:135], v[184:187], v[16:19]
	v_mfma_f32_16x16x32_bf16 v[20:23], v[128:131], v[188:191], v[20:23]
	v_mfma_f32_16x16x32_bf16 v[20:23], v[132:135], v[192:195], v[20:23]
	v_mfma_f32_16x16x32_bf16 v[24:27], v[136:139], v[180:183], v[24:27]
	v_mfma_f32_16x16x32_bf16 v[24:27], v[140:143], v[184:187], v[24:27]
	v_mfma_f32_16x16x32_bf16 v[28:31], v[136:139], v[188:191], v[28:31]
	v_mfma_f32_16x16x32_bf16 v[28:31], v[140:143], v[192:195], v[28:31]
	v_mfma_f32_16x16x32_bf16 v[0:3], v[144:147], v[180:183], v[0:3]
	v_mfma_f32_16x16x32_bf16 v[0:3], v[148:151], v[184:187], v[0:3]
	v_mfma_f32_16x16x32_bf16 v[4:7], v[144:147], v[188:191], v[4:7]
	v_mfma_f32_16x16x32_bf16 v[4:7], v[148:151], v[192:195], v[4:7]
	v_mfma_f32_16x16x32_bf16 v[8:11], v[152:155], v[180:183], v[8:11]
	v_mfma_f32_16x16x32_bf16 v[8:11], v[156:159], v[184:187], v[8:11]
	v_mfma_f32_16x16x32_bf16 v[12:15], v[152:155], v[188:191], v[12:15]
	v_mfma_f32_16x16x32_bf16 v[12:15], v[156:159], v[192:195], v[12:15]
	s_barrier
	ds_read_b128 v[160:163], v198 offset:0
	ds_read_b128 v[164:167], v200 offset:0
	ds_read_b128 v[172:175], v198 offset:2048
	ds_read_b128 v[176:179], v200 offset:2048
	ds_read_b128 v[128:131], v170 offset:0
	ds_read_b128 v[132:135], v196 offset:0
	ds_read_b128 v[136:139], v170 offset:2048
	ds_read_b128 v[140:143], v196 offset:2048
	ds_read_b128 v[144:147], v170 offset:4096
	ds_read_b128 v[148:151], v196 offset:4096
	ds_read_b128 v[152:155], v170 offset:6144
	ds_read_b128 v[156:159], v196 offset:6144
	s_add_u32 m0, s99, 0x4000
	s_nop 0
	global_load_lds_dwordx4 v203, s[72:73]
	s_add_u32 m0, s99, 0x6000
	s_nop 0
	global_load_lds_dwordx4 v204, s[72:73]
	s_waitcnt lgkmcnt(8)
	s_barrier
	s_waitcnt lgkmcnt(0)
	v_mfma_f32_16x16x32_bf16 v[112:115], v[128:131], v[160:163], v[112:115]
	v_mfma_f32_16x16x32_bf16 v[112:115], v[132:135], v[164:167], v[112:115]
	v_mfma_f32_16x16x32_bf16 v[116:119], v[128:131], v[172:175], v[116:119]
	v_mfma_f32_16x16x32_bf16 v[116:119], v[132:135], v[176:179], v[116:119]
	v_mfma_f32_16x16x32_bf16 v[120:123], v[136:139], v[160:163], v[120:123]
	v_mfma_f32_16x16x32_bf16 v[120:123], v[140:143], v[164:167], v[120:123]
	v_mfma_f32_16x16x32_bf16 v[124:127], v[136:139], v[172:175], v[124:127]
	v_mfma_f32_16x16x32_bf16 v[124:127], v[140:143], v[176:179], v[124:127]
	v_mfma_f32_16x16x32_bf16 v[96:99], v[144:147], v[160:163], v[96:99]
	v_mfma_f32_16x16x32_bf16 v[96:99], v[148:151], v[164:167], v[96:99]
	v_mfma_f32_16x16x32_bf16 v[100:103], v[144:147], v[172:175], v[100:103]
	v_mfma_f32_16x16x32_bf16 v[100:103], v[148:151], v[176:179], v[100:103]
	v_mfma_f32_16x16x32_bf16 v[104:107], v[152:155], v[160:163], v[104:107]
	v_mfma_f32_16x16x32_bf16 v[104:107], v[156:159], v[164:167], v[104:107]
	v_mfma_f32_16x16x32_bf16 v[108:111], v[152:155], v[172:175], v[108:111]
	v_mfma_f32_16x16x32_bf16 v[108:111], v[156:159], v[176:179], v[108:111]
	s_barrier
	ds_read_b128 v[180:183], v198 offset:16384
	ds_read_b128 v[184:187], v200 offset:16384
	ds_read_b128 v[188:191], v198 offset:18432
	ds_read_b128 v[192:195], v200 offset:18432
	s_add_u32 s70, s70, 0x80
	s_addc_u32 s71, s71, 0
	s_add_u32 m0, s99, 0x18000
	s_nop 0
	global_load_lds_dwordx4 v205, s[70:71]
	s_add_u32 m0, s99, 0x1a000
	s_nop 0
	global_load_lds_dwordx4 v206, s[70:71]
	s_barrier
	s_waitcnt lgkmcnt(0)
	v_mfma_f32_16x16x32_bf16 v[48:51], v[128:131], v[180:183], v[48:51]
	v_mfma_f32_16x16x32_bf16 v[48:51], v[132:135], v[184:187], v[48:51]
	v_mfma_f32_16x16x32_bf16 v[52:55], v[128:131], v[188:191], v[52:55]
	v_mfma_f32_16x16x32_bf16 v[52:55], v[132:135], v[192:195], v[52:55]
	v_mfma_f32_16x16x32_bf16 v[56:59], v[136:139], v[180:183], v[56:59]
	v_mfma_f32_16x16x32_bf16 v[56:59], v[140:143], v[184:187], v[56:59]
	v_mfma_f32_16x16x32_bf16 v[60:63], v[136:139], v[188:191], v[60:63]
	v_mfma_f32_16x16x32_bf16 v[60:63], v[140:143], v[192:195], v[60:63]
	v_mfma_f32_16x16x32_bf16 v[32:35], v[144:147], v[180:183], v[32:35]
	v_mfma_f32_16x16x32_bf16 v[32:35], v[148:151], v[184:187], v[32:35]
	v_mfma_f32_16x16x32_bf16 v[36:39], v[144:147], v[188:191], v[36:39]
	v_mfma_f32_16x16x32_bf16 v[36:39], v[148:151], v[192:195], v[36:39]
	v_mfma_f32_16x16x32_bf16 v[40:43], v[152:155], v[180:183], v[40:43]
	v_mfma_f32_16x16x32_bf16 v[40:43], v[156:159], v[184:187], v[40:43]
	v_mfma_f32_16x16x32_bf16 v[44:47], v[152:155], v[188:191], v[44:47]
	v_mfma_f32_16x16x32_bf16 v[44:47], v[156:159], v[192:195], v[44:47]
	s_barrier
	ds_read_b128 v[128:131], v170 offset:16384
	ds_read_b128 v[132:135], v196 offset:16384
	ds_read_b128 v[136:139], v170 offset:18432
	ds_read_b128 v[140:143], v196 offset:18432
	ds_read_b128 v[144:147], v170 offset:20480
	ds_read_b128 v[148:151], v196 offset:20480
	ds_read_b128 v[152:155], v170 offset:22528
	ds_read_b128 v[156:159], v196 offset:22528
	s_add_u32 s72, s72, 0x80
	s_addc_u32 s73, s73, 0
	s_add_u32 m0, s99, 0x10000
	s_nop 0
	global_load_lds_dwordx4 v201, s[72:73]
	s_add_u32 m0, s99, 0x12000
	s_nop 0
	global_load_lds_dwordx4 v202, s[72:73]
	s_barrier
	s_waitcnt lgkmcnt(0)
	v_mfma_f32_16x16x32_bf16 v[80:83], v[128:131], v[160:163], v[80:83]
	v_mfma_f32_16x16x32_bf16 v[80:83], v[132:135], v[164:167], v[80:83]
	v_mfma_f32_16x16x32_bf16 v[84:87], v[128:131], v[172:175], v[84:87]
	v_mfma_f32_16x16x32_bf16 v[84:87], v[132:135], v[176:179], v[84:87]
	v_mfma_f32_16x16x32_bf16 v[88:91], v[136:139], v[160:163], v[88:91]
	v_mfma_f32_16x16x32_bf16 v[88:91], v[140:143], v[164:167], v[88:91]
	v_mfma_f32_16x16x32_bf16 v[92:95], v[136:139], v[172:175], v[92:95]
	v_mfma_f32_16x16x32_bf16 v[92:95], v[140:143], v[176:179], v[92:95]
	v_mfma_f32_16x16x32_bf16 v[64:67], v[144:147], v[160:163], v[64:67]
	v_mfma_f32_16x16x32_bf16 v[64:67], v[148:151], v[164:167], v[64:67]
	v_mfma_f32_16x16x32_bf16 v[68:71], v[144:147], v[172:175], v[68:71]
	v_mfma_f32_16x16x32_bf16 v[68:71], v[148:151], v[176:179], v[68:71]
	v_mfma_f32_16x16x32_bf16 v[72:75], v[152:155], v[160:163], v[72:75]
	v_mfma_f32_16x16x32_bf16 v[72:75], v[156:159], v[164:167], v[72:75]
	v_mfma_f32_16x16x32_bf16 v[76:79], v[152:155], v[172:175], v[76:79]
	v_mfma_f32_16x16x32_bf16 v[76:79], v[156:159], v[176:179], v[76:79]
	s_barrier
	s_add_u32 m0, s99, 0x1c000
	s_nop 0
	global_load_lds_dwordx4 v210, s[70:71]
	s_add_u32 m0, s99, 0x1e000
	s_nop 0
	global_load_lds_dwordx4 v211, s[70:71]
	s_waitcnt vmcnt(6)
	s_barrier
	v_mfma_f32_16x16x32_bf16 v[16:19], v[128:131], v[180:183], v[16:19]
	v_mfma_f32_16x16x32_bf16 v[16:19], v[132:135], v[184:187], v[16:19]
	v_mfma_f32_16x16x32_bf16 v[20:23], v[128:131], v[188:191], v[20:23]
	v_mfma_f32_16x16x32_bf16 v[20:23], v[132:135], v[192:195], v[20:23]
	v_mfma_f32_16x16x32_bf16 v[24:27], v[136:139], v[180:183], v[24:27]
	v_mfma_f32_16x16x32_bf16 v[24:27], v[140:143], v[184:187], v[24:27]
	v_mfma_f32_16x16x32_bf16 v[28:31], v[136:139], v[188:191], v[28:31]
	v_mfma_f32_16x16x32_bf16 v[28:31], v[140:143], v[192:195], v[28:31]
	v_mfma_f32_16x16x32_bf16 v[0:3], v[144:147], v[180:183], v[0:3]
	v_mfma_f32_16x16x32_bf16 v[0:3], v[148:151], v[184:187], v[0:3]
	v_mfma_f32_16x16x32_bf16 v[4:7], v[144:147], v[188:191], v[4:7]
	v_mfma_f32_16x16x32_bf16 v[4:7], v[148:151], v[192:195], v[4:7]
	v_mfma_f32_16x16x32_bf16 v[8:11], v[152:155], v[180:183], v[8:11]
	v_mfma_f32_16x16x32_bf16 v[8:11], v[156:159], v[184:187], v[8:11]
	v_mfma_f32_16x16x32_bf16 v[12:15], v[152:155], v[188:191], v[12:15]
	v_mfma_f32_16x16x32_bf16 v[12:15], v[156:159], v[192:195], v[12:15]
	s_barrier
	s_sub_u32 s101, s101, 1
	s_cmp_lg_u32 s101, 0
	s_cbranch_scc1 .Lg8_p7_loop
	ds_read_b128 v[160:163], v197 offset:0
	ds_read_b128 v[164:167], v199 offset:0
	ds_read_b128 v[172:175], v197 offset:2048
	ds_read_b128 v[176:179], v199 offset:2048
	ds_read_b128 v[128:131], v168 offset:0
	ds_read_b128 v[132:135], v171 offset:0
	ds_read_b128 v[136:139], v168 offset:2048
	ds_read_b128 v[140:143], v171 offset:2048
	ds_read_b128 v[144:147], v168 offset:4096
	ds_read_b128 v[148:151], v171 offset:4096
	ds_read_b128 v[152:155], v168 offset:6144
	ds_read_b128 v[156:159], v171 offset:6144
	s_add_u32 m0, s99, 0x14000
	s_nop 0
	global_load_lds_dwordx4 v203, s[72:73]
	s_add_u32 m0, s99, 0x16000
	s_nop 0
	global_load_lds_dwordx4 v204, s[72:73]
	s_barrier
	s_waitcnt lgkmcnt(0)
	v_mfma_f32_16x16x32_bf16 v[112:115], v[128:131], v[160:163], v[112:115]
	v_mfma_f32_16x16x32_bf16 v[112:115], v[132:135], v[164:167], v[112:115]
	v_mfma_f32_16x16x32_bf16 v[116:119], v[128:131], v[172:175], v[116:119]
	v_mfma_f32_16x16x32_bf16 v[116:119], v[132:135], v[176:179], v[116:119]
	v_mfma_f32_16x16x32_bf16 v[120:123], v[136:139], v[160:163], v[120:123]
	v_mfma_f32_16x16x32_bf16 v[120:123], v[140:143], v[164:167], v[120:123]
	v_mfma_f32_16x16x32_bf16 v[124:127], v[136:139], v[172:175], v[124:127]
	v_mfma_f32_16x16x32_bf16 v[124:127], v[140:143], v[176:179], v[124:127]
	v_mfma_f32_16x16x32_bf16 v[96:99], v[144:147], v[160:163], v[96:99]
	v_mfma_f32_16x16x32_bf16 v[96:99], v[148:151], v[164:167], v[96:99]
	v_mfma_f32_16x16x32_bf16 v[100:103], v[144:147], v[172:175], v[100:103]
	v_mfma_f32_16x16x32_bf16 v[100:103], v[148:151], v[176:179], v[100:103]
	v_mfma_f32_16x16x32_bf16 v[104:107], v[152:155], v[160:163], v[104:107]
	v_mfma_f32_16x16x32_bf16 v[104:107], v[156:159], v[164:167], v[104:107]
	v_mfma_f32_16x16x32_bf16 v[108:111], v[152:155], v[172:175], v[108:111]
	v_mfma_f32_16x16x32_bf16 v[108:111], v[156:159], v[176:179], v[108:111]
	s_barrier
	ds_read_b128 v[180:183], v197 offset:16384
	ds_read_b128 v[184:187], v199 offset:16384
	ds_read_b128 v[188:191], v197 offset:18432
	ds_read_b128 v[192:195], v199 offset:18432
	s_barrier
	s_waitcnt lgkmcnt(0)
	v_mfma_f32_16x16x32_bf16 v[48:51], v[128:131], v[180:183], v[48:51]
	v_mfma_f32_16x16x32_bf16 v[48:51], v[132:135], v[184:187], v[48:51]
	v_mfma_f32_16x16x32_bf16 v[52:55], v[128:131], v[188:191], v[52:55]
	v_mfma_f32_16x16x32_bf16 v[52:55], v[132:135], v[192:195], v[52:55]
	v_mfma_f32_16x16x32_bf16 v[56:59], v[136:139], v[180:183], v[56:59]
	v_mfma_f32_16x16x32_bf16 v[56:59], v[140:143], v[184:187], v[56:59]
	v_mfma_f32_16x16x32_bf16 v[60:63], v[136:139], v[188:191], v[60:63]
	v_mfma_f32_16x16x32_bf16 v[60:63], v[140:143], v[192:195], v[60:63]
	v_mfma_f32_16x16x32_bf16 v[32:35], v[144:147], v[180:183], v[32:35]
	v_mfma_f32_16x16x32_bf16 v[32:35], v[148:151], v[184:187], v[32:35]
	v_mfma_f32_16x16x32_bf16 v[36:39], v[144:147], v[188:191], v[36:39]
	v_mfma_f32_16x16x32_bf16 v[36:39], v[148:151], v[192:195], v[36:39]
	v_mfma_f32_16x16x32_bf16 v[40:43], v[152:155], v[180:183], v[40:43]
	v_mfma_f32_16x16x32_bf16 v[40:43], v[156:159], v[184:187], v[40:43]
	v_mfma_f32_16x16x32_bf16 v[44:47], v[152:155], v[188:191], v[44:47]
	v_mfma_f32_16x16x32_bf16 v[44:47], v[156:159], v[192:195], v[44:47]
	s_barrier
	ds_read_b128 v[128:131], v168 offset:16384
	ds_read_b128 v[132:135], v171 offset:16384
	ds_read_b128 v[136:139], v168 offset:18432
	ds_read_b128 v[140:143], v171 offset:18432
	ds_read_b128 v[144:147], v168 offset:20480
	ds_read_b128 v[148:151], v171 offset:20480
	ds_read_b128 v[152:155], v168 offset:22528
	ds_read_b128 v[156:159], v171 offset:22528
	s_waitcnt vmcnt(4)
	s_barrier
	s_waitcnt lgkmcnt(0)
	v_mfma_f32_16x16x32_bf16 v[80:83], v[128:131], v[160:163], v[80:83]
	v_mfma_f32_16x16x32_bf16 v[80:83], v[132:135], v[164:167], v[80:83]
	v_mfma_f32_16x16x32_bf16 v[84:87], v[128:131], v[172:175], v[84:87]
	v_mfma_f32_16x16x32_bf16 v[84:87], v[132:135], v[176:179], v[84:87]
	v_mfma_f32_16x16x32_bf16 v[88:91], v[136:139], v[160:163], v[88:91]
	v_mfma_f32_16x16x32_bf16 v[88:91], v[140:143], v[164:167], v[88:91]
	v_mfma_f32_16x16x32_bf16 v[92:95], v[136:139], v[172:175], v[92:95]
	v_mfma_f32_16x16x32_bf16 v[92:95], v[140:143], v[176:179], v[92:95]
	v_mfma_f32_16x16x32_bf16 v[64:67], v[144:147], v[160:163], v[64:67]
	v_mfma_f32_16x16x32_bf16 v[64:67], v[148:151], v[164:167], v[64:67]
	v_mfma_f32_16x16x32_bf16 v[68:71], v[144:147], v[172:175], v[68:71]
	v_mfma_f32_16x16x32_bf16 v[68:71], v[148:151], v[176:179], v[68:71]
	v_mfma_f32_16x16x32_bf16 v[72:75], v[152:155], v[160:163], v[72:75]
	v_mfma_f32_16x16x32_bf16 v[72:75], v[156:159], v[164:167], v[72:75]
	v_mfma_f32_16x16x32_bf16 v[76:79], v[152:155], v[172:175], v[76:79]
	v_mfma_f32_16x16x32_bf16 v[76:79], v[156:159], v[176:179], v[76:79]
	v_mfma_f32_16x16x32_bf16 v[16:19], v[128:131], v[180:183], v[16:19]
	v_mfma_f32_16x16x32_bf16 v[16:19], v[132:135], v[184:187], v[16:19]
	v_mfma_f32_16x16x32_bf16 v[20:23], v[128:131], v[188:191], v[20:23]
	v_mfma_f32_16x16x32_bf16 v[20:23], v[132:135], v[192:195], v[20:23]
	v_mfma_f32_16x16x32_bf16 v[24:27], v[136:139], v[180:183], v[24:27]
	v_mfma_f32_16x16x32_bf16 v[24:27], v[140:143], v[184:187], v[24:27]
	v_mfma_f32_16x16x32_bf16 v[28:31], v[136:139], v[188:191], v[28:31]
	v_mfma_f32_16x16x32_bf16 v[28:31], v[140:143], v[192:195], v[28:31]
	v_mfma_f32_16x16x32_bf16 v[0:3], v[144:147], v[180:183], v[0:3]
	v_mfma_f32_16x16x32_bf16 v[0:3], v[148:151], v[184:187], v[0:3]
	v_mfma_f32_16x16x32_bf16 v[4:7], v[144:147], v[188:191], v[4:7]
	v_mfma_f32_16x16x32_bf16 v[4:7], v[148:151], v[192:195], v[4:7]
	v_mfma_f32_16x16x32_bf16 v[8:11], v[152:155], v[180:183], v[8:11]
	v_mfma_f32_16x16x32_bf16 v[8:11], v[156:159], v[184:187], v[8:11]
	v_mfma_f32_16x16x32_bf16 v[12:15], v[152:155], v[188:191], v[12:15]
	v_mfma_f32_16x16x32_bf16 v[12:15], v[156:159], v[192:195], v[12:15]
	s_barrier
	ds_read_b128 v[160:163], v198 offset:0
	ds_read_b128 v[164:167], v200 offset:0
	ds_read_b128 v[172:175], v198 offset:2048
	ds_read_b128 v[176:179], v200 offset:2048
	ds_read_b128 v[128:131], v170 offset:0
	ds_read_b128 v[132:135], v196 offset:0
	ds_read_b128 v[136:139], v170 offset:2048
	ds_read_b128 v[140:143], v196 offset:2048
	ds_read_b128 v[144:147], v170 offset:4096
	ds_read_b128 v[148:151], v196 offset:4096
	ds_read_b128 v[152:155], v170 offset:6144
	ds_read_b128 v[156:159], v196 offset:6144
	s_waitcnt vmcnt(2)
	s_barrier
	s_waitcnt lgkmcnt(0)
	v_mfma_f32_16x16x32_bf16 v[112:115], v[128:131], v[160:163], v[112:115]
	v_mfma_f32_16x16x32_bf16 v[112:115], v[132:135], v[164:167], v[112:115]
	v_mfma_f32_16x16x32_bf16 v[116:119], v[128:131], v[172:175], v[116:119]
	v_mfma_f32_16x16x32_bf16 v[116:119], v[132:135], v[176:179], v[116:119]
	v_mfma_f32_16x16x32_bf16 v[120:123], v[136:139], v[160:163], v[120:123]
	v_mfma_f32_16x16x32_bf16 v[120:123], v[140:143], v[164:167], v[120:123]
	v_mfma_f32_16x16x32_bf16 v[124:127], v[136:139], v[172:175], v[124:127]
	v_mfma_f32_16x16x32_bf16 v[124:127], v[140:143], v[176:179], v[124:127]
	v_mfma_f32_16x16x32_bf16 v[96:99], v[144:147], v[160:163], v[96:99]
	v_mfma_f32_16x16x32_bf16 v[96:99], v[148:151], v[164:167], v[96:99]
	v_mfma_f32_16x16x32_bf16 v[100:103], v[144:147], v[172:175], v[100:103]
	v_mfma_f32_16x16x32_bf16 v[100:103], v[148:151], v[176:179], v[100:103]
	v_mfma_f32_16x16x32_bf16 v[104:107], v[152:155], v[160:163], v[104:107]
	v_mfma_f32_16x16x32_bf16 v[104:107], v[156:159], v[164:167], v[104:107]
	v_mfma_f32_16x16x32_bf16 v[108:111], v[152:155], v[172:175], v[108:111]
	v_mfma_f32_16x16x32_bf16 v[108:111], v[156:159], v[176:179], v[108:111]
	s_barrier
	ds_read_b128 v[180:183], v198 offset:16384
	ds_read_b128 v[184:187], v200 offset:16384
	ds_read_b128 v[188:191], v198 offset:18432
	ds_read_b128 v[192:195], v200 offset:18432
	s_waitcnt vmcnt(0)
	s_barrier
	s_waitcnt lgkmcnt(0)
	v_mfma_f32_16x16x32_bf16 v[48:51], v[128:131], v[180:183], v[48:51]
	v_mfma_f32_16x16x32_bf16 v[48:51], v[132:135], v[184:187], v[48:51]
	v_mfma_f32_16x16x32_bf16 v[52:55], v[128:131], v[188:191], v[52:55]
	v_mfma_f32_16x16x32_bf16 v[52:55], v[132:135], v[192:195], v[52:55]
	v_mfma_f32_16x16x32_bf16 v[56:59], v[136:139], v[180:183], v[56:59]
	v_mfma_f32_16x16x32_bf16 v[56:59], v[140:143], v[184:187], v[56:59]
	v_mfma_f32_16x16x32_bf16 v[60:63], v[136:139], v[188:191], v[60:63]
	v_mfma_f32_16x16x32_bf16 v[60:63], v[140:143], v[192:195], v[60:63]
	v_mfma_f32_16x16x32_bf16 v[32:35], v[144:147], v[180:183], v[32:35]
	v_mfma_f32_16x16x32_bf16 v[32:35], v[148:151], v[184:187], v[32:35]
	v_mfma_f32_16x16x32_bf16 v[36:39], v[144:147], v[188:191], v[36:39]
	v_mfma_f32_16x16x32_bf16 v[36:39], v[148:151], v[192:195], v[36:39]
	v_mfma_f32_16x16x32_bf16 v[40:43], v[152:155], v[180:183], v[40:43]
	v_mfma_f32_16x16x32_bf16 v[40:43], v[156:159], v[184:187], v[40:43]
	v_mfma_f32_16x16x32_bf16 v[44:47], v[152:155], v[188:191], v[44:47]
	v_mfma_f32_16x16x32_bf16 v[44:47], v[156:159], v[192:195], v[44:47]
	s_barrier
	ds_read_b128 v[128:131], v170 offset:16384
	ds_read_b128 v[132:135], v196 offset:16384
	ds_read_b128 v[136:139], v170 offset:18432
	ds_read_b128 v[140:143], v196 offset:18432
	ds_read_b128 v[144:147], v170 offset:20480
	ds_read_b128 v[148:151], v196 offset:20480
	ds_read_b128 v[152:155], v170 offset:22528
	ds_read_b128 v[156:159], v196 offset:22528
	s_barrier
	s_waitcnt lgkmcnt(0)
	v_mfma_f32_16x16x32_bf16 v[80:83], v[128:131], v[160:163], v[80:83]
	v_mfma_f32_16x16x32_bf16 v[80:83], v[132:135], v[164:167], v[80:83]
	v_mfma_f32_16x16x32_bf16 v[84:87], v[128:131], v[172:175], v[84:87]
	v_mfma_f32_16x16x32_bf16 v[84:87], v[132:135], v[176:179], v[84:87]
	v_mfma_f32_16x16x32_bf16 v[88:91], v[136:139], v[160:163], v[88:91]
	v_mfma_f32_16x16x32_bf16 v[88:91], v[140:143], v[164:167], v[88:91]
	v_mfma_f32_16x16x32_bf16 v[92:95], v[136:139], v[172:175], v[92:95]
	v_mfma_f32_16x16x32_bf16 v[92:95], v[140:143], v[176:179], v[92:95]
	v_mfma_f32_16x16x32_bf16 v[64:67], v[144:147], v[160:163], v[64:67]
	v_mfma_f32_16x16x32_bf16 v[64:67], v[148:151], v[164:167], v[64:67]
	v_mfma_f32_16x16x32_bf16 v[68:71], v[144:147], v[172:175], v[68:71]
	v_mfma_f32_16x16x32_bf16 v[68:71], v[148:151], v[176:179], v[68:71]
	v_mfma_f32_16x16x32_bf16 v[72:75], v[152:155], v[160:163], v[72:75]
	v_mfma_f32_16x16x32_bf16 v[72:75], v[156:159], v[164:167], v[72:75]
	v_mfma_f32_16x16x32_bf16 v[76:79], v[152:155], v[172:175], v[76:79]
	v_mfma_f32_16x16x32_bf16 v[76:79], v[156:159], v[176:179], v[76:79]
	v_mfma_f32_16x16x32_bf16 v[16:19], v[128:131], v[180:183], v[16:19]
	v_mfma_f32_16x16x32_bf16 v[16:19], v[132:135], v[184:187], v[16:19]
	v_mfma_f32_16x16x32_bf16 v[20:23], v[128:131], v[188:191], v[20:23]
	v_mfma_f32_16x16x32_bf16 v[20:23], v[132:135], v[192:195], v[20:23]
	v_mfma_f32_16x16x32_bf16 v[24:27], v[136:139], v[180:183], v[24:27]
	v_mfma_f32_16x16x32_bf16 v[24:27], v[140:143], v[184:187], v[24:27]
	v_mfma_f32_16x16x32_bf16 v[28:31], v[136:139], v[188:191], v[28:31]
	v_mfma_f32_16x16x32_bf16 v[28:31], v[140:143], v[192:195], v[28:31]
	v_mfma_f32_16x16x32_bf16 v[0:3], v[144:147], v[180:183], v[0:3]
	v_mfma_f32_16x16x32_bf16 v[0:3], v[148:151], v[184:187], v[0:3]
	v_mfma_f32_16x16x32_bf16 v[4:7], v[144:147], v[188:191], v[4:7]
	v_mfma_f32_16x16x32_bf16 v[4:7], v[148:151], v[192:195], v[4:7]
	v_mfma_f32_16x16x32_bf16 v[8:11], v[152:155], v[180:183], v[8:11]
	v_mfma_f32_16x16x32_bf16 v[8:11], v[156:159], v[184:187], v[8:11]
	v_mfma_f32_16x16x32_bf16 v[12:15], v[152:155], v[188:191], v[12:15]
	v_mfma_f32_16x16x32_bf16 v[12:15], v[156:159], v[192:195], v[12:15]
	s_barrier
	s_cmp_lg_u32 s100, 0
	s_cbranch_scc1 .Lg8_p7_gb1
	s_barrier

.Lg8_p9_loop:
	ds_read_b128 v[160:163], v197 offset:0
	ds_read_b128 v[164:167], v199 offset:0
	ds_read_b128 v[168:171], v197 offset:2048
	ds_read_b128 v[172:175], v199 offset:2048
	ds_read_b128 v[128:131], v184 offset:0
	ds_read_b128 v[132:135], v187 offset:0
	ds_read_b128 v[136:139], v184 offset:2048
	ds_read_b128 v[140:143], v187 offset:2048
	ds_read_b128 v[144:147], v184 offset:4096
	ds_read_b128 v[148:151], v187 offset:4096
	ds_read_b128 v[152:155], v184 offset:6144
	ds_read_b128 v[156:159], v187 offset:6144
	s_add_u32 m0, s99, 0x14000
	s_nop 0
	global_load_lds_dwordx4 v203, s[42:43]
	s_add_u32 m0, s99, 0x16000
	s_nop 0
	global_load_lds_dwordx4 v204, s[42:43]
	s_waitcnt lgkmcnt(8)
	s_barrier
	s_waitcnt lgkmcnt(0)
	v_mfma_f32_16x16x32_bf16 v[112:115], v[128:131], v[160:163], v[112:115]
	v_mfma_f32_16x16x32_bf16 v[112:115], v[132:135], v[164:167], v[112:115]
	v_mfma_f32_16x16x32_bf16 v[116:119], v[128:131], v[168:171], v[116:119]
	v_mfma_f32_16x16x32_bf16 v[116:119], v[132:135], v[172:175], v[116:119]
	v_mfma_f32_16x16x32_bf16 v[120:123], v[136:139], v[160:163], v[120:123]
	v_mfma_f32_16x16x32_bf16 v[120:123], v[140:143], v[164:167], v[120:123]
	v_mfma_f32_16x16x32_bf16 v[124:127], v[136:139], v[168:171], v[124:127]
	v_mfma_f32_16x16x32_bf16 v[124:127], v[140:143], v[172:175], v[124:127]
	v_mfma_f32_16x16x32_bf16 v[96:99], v[144:147], v[160:163], v[96:99]
	v_mfma_f32_16x16x32_bf16 v[96:99], v[148:151], v[164:167], v[96:99]
	v_mfma_f32_16x16x32_bf16 v[100:103], v[144:147], v[168:171], v[100:103]
	v_mfma_f32_16x16x32_bf16 v[100:103], v[148:151], v[172:175], v[100:103]
	v_mfma_f32_16x16x32_bf16 v[104:107], v[152:155], v[160:163], v[104:107]
	v_mfma_f32_16x16x32_bf16 v[104:107], v[156:159], v[164:167], v[104:107]
	v_mfma_f32_16x16x32_bf16 v[108:111], v[152:155], v[168:171], v[108:111]
	v_mfma_f32_16x16x32_bf16 v[108:111], v[156:159], v[172:175], v[108:111]
	s_barrier
	ds_read_b128 v[176:179], v197 offset:16384
	ds_read_b128 v[180:183], v199 offset:16384
	ds_read_b128 v[188:191], v197 offset:18432
	ds_read_b128 v[192:195], v199 offset:18432
	s_add_u32 s40, s40, 0x80
	s_addc_u32 s41, s41, 0
	s_add_u32 m0, s99, 0x8000
	s_nop 0
	global_load_lds_dwordx4 v205, s[40:41]
	s_add_u32 m0, s99, 0xa000
	s_nop 0
	global_load_lds_dwordx4 v206, s[40:41]
	s_barrier
	s_waitcnt lgkmcnt(0)
	v_mfma_f32_16x16x32_bf16 v[48:51], v[128:131], v[176:179], v[48:51]
	v_mfma_f32_16x16x32_bf16 v[48:51], v[132:135], v[180:183], v[48:51]
	v_mfma_f32_16x16x32_bf16 v[52:55], v[128:131], v[188:191], v[52:55]
	v_mfma_f32_16x16x32_bf16 v[52:55], v[132:135], v[192:195], v[52:55]
	v_mfma_f32_16x16x32_bf16 v[56:59], v[136:139], v[176:179], v[56:59]
	v_mfma_f32_16x16x32_bf16 v[56:59], v[140:143], v[180:183], v[56:59]
	v_mfma_f32_16x16x32_bf16 v[60:63], v[136:139], v[188:191], v[60:63]
	v_mfma_f32_16x16x32_bf16 v[60:63], v[140:143], v[192:195], v[60:63]
	v_mfma_f32_16x16x32_bf16 v[32:35], v[144:147], v[176:179], v[32:35]
	v_mfma_f32_16x16x32_bf16 v[32:35], v[148:151], v[180:183], v[32:35]
	v_mfma_f32_16x16x32_bf16 v[36:39], v[144:147], v[188:191], v[36:39]
	v_mfma_f32_16x16x32_bf16 v[36:39], v[148:151], v[192:195], v[36:39]
	v_mfma_f32_16x16x32_bf16 v[40:43], v[152:155], v[176:179], v[40:43]
	v_mfma_f32_16x16x32_bf16 v[40:43], v[156:159], v[180:183], v[40:43]
	v_mfma_f32_16x16x32_bf16 v[44:47], v[152:155], v[188:191], v[44:47]
	v_mfma_f32_16x16x32_bf16 v[44:47], v[156:159], v[192:195], v[44:47]
	s_barrier
	ds_read_b128 v[128:131], v184 offset:16384
	ds_read_b128 v[132:135], v187 offset:16384
	ds_read_b128 v[136:139], v184 offset:18432
	ds_read_b128 v[140:143], v187 offset:18432
	ds_read_b128 v[144:147], v184 offset:20480
	ds_read_b128 v[148:151], v187 offset:20480
	ds_read_b128 v[152:155], v184 offset:22528
	ds_read_b128 v[156:159], v187 offset:22528
	s_add_u32 s42, s42, 0x80
	s_addc_u32 s43, s43, 0
	s_add_u32 m0, s99, 0x0
	s_nop 0
	global_load_lds_dwordx4 v201, s[42:43]
	s_add_u32 m0, s99, 0x2000
	s_nop 0
	global_load_lds_dwordx4 v202, s[42:43]
	s_barrier
	s_waitcnt lgkmcnt(0)
	v_mfma_f32_16x16x32_bf16 v[64:67], v[128:131], v[160:163], v[64:67]
	v_mfma_f32_16x16x32_bf16 v[64:67], v[132:135], v[164:167], v[64:67]
	v_mfma_f32_16x16x32_bf16 v[68:71], v[128:131], v[168:171], v[68:71]
	v_mfma_f32_16x16x32_bf16 v[68:71], v[132:135], v[172:175], v[68:71]
	v_mfma_f32_16x16x32_bf16 v[72:75], v[136:139], v[160:163], v[72:75]
	v_mfma_f32_16x16x32_bf16 v[72:75], v[140:143], v[164:167], v[72:75]
	v_mfma_f32_16x16x32_bf16 v[76:79], v[136:139], v[168:171], v[76:79]
	v_mfma_f32_16x16x32_bf16 v[76:79], v[140:143], v[172:175], v[76:79]
	v_mfma_f32_16x16x32_bf16 v[80:83], v[144:147], v[160:163], v[80:83]
	v_mfma_f32_16x16x32_bf16 v[80:83], v[148:151], v[164:167], v[80:83]
	v_mfma_f32_16x16x32_bf16 v[84:87], v[144:147], v[168:171], v[84:87]
	v_mfma_f32_16x16x32_bf16 v[84:87], v[148:151], v[172:175], v[84:87]
	v_mfma_f32_16x16x32_bf16 v[88:91], v[152:155], v[160:163], v[88:91]
	v_mfma_f32_16x16x32_bf16 v[88:91], v[156:159], v[164:167], v[88:91]
	v_mfma_f32_16x16x32_bf16 v[92:95], v[152:155], v[168:171], v[92:95]
	v_mfma_f32_16x16x32_bf16 v[92:95], v[156:159], v[172:175], v[92:95]
	s_barrier
	s_add_u32 m0, s99, 0xc000
	s_nop 0
	global_load_lds_dwordx4 v210, s[40:41]
	s_add_u32 m0, s99, 0xe000
	s_nop 0
	global_load_lds_dwordx4 v211, s[40:41]
	s_waitcnt vmcnt(6)
	s_barrier
	v_mfma_f32_16x16x32_bf16 v[16:19], v[128:131], v[176:179], v[16:19]
	v_mfma_f32_16x16x32_bf16 v[16:19], v[132:135], v[180:183], v[16:19]
	v_mfma_f32_16x16x32_bf16 v[20:23], v[128:131], v[188:191], v[20:23]
	v_mfma_f32_16x16x32_bf16 v[20:23], v[132:135], v[192:195], v[20:23]
	v_mfma_f32_16x16x32_bf16 v[24:27], v[136:139], v[176:179], v[24:27]
	v_mfma_f32_16x16x32_bf16 v[24:27], v[140:143], v[180:183], v[24:27]
	v_mfma_f32_16x16x32_bf16 v[28:31], v[136:139], v[188:191], v[28:31]
	v_mfma_f32_16x16x32_bf16 v[28:31], v[140:143], v[192:195], v[28:31]
	v_mfma_f32_16x16x32_bf16 v[0:3], v[144:147], v[176:179], v[0:3]
	v_mfma_f32_16x16x32_bf16 v[0:3], v[148:151], v[180:183], v[0:3]
	v_mfma_f32_16x16x32_bf16 v[4:7], v[144:147], v[188:191], v[4:7]
	v_mfma_f32_16x16x32_bf16 v[4:7], v[148:151], v[192:195], v[4:7]
	v_mfma_f32_16x16x32_bf16 v[8:11], v[152:155], v[176:179], v[8:11]
	v_mfma_f32_16x16x32_bf16 v[8:11], v[156:159], v[180:183], v[8:11]
	v_mfma_f32_16x16x32_bf16 v[12:15], v[152:155], v[188:191], v[12:15]
	v_mfma_f32_16x16x32_bf16 v[12:15], v[156:159], v[192:195], v[12:15]
	s_barrier
	ds_read_b128 v[160:163], v198 offset:0
	ds_read_b128 v[164:167], v200 offset:0
	ds_read_b128 v[168:171], v198 offset:2048
	ds_read_b128 v[172:175], v200 offset:2048
	ds_read_b128 v[128:131], v186 offset:0
	ds_read_b128 v[132:135], v196 offset:0
	ds_read_b128 v[136:139], v186 offset:2048
	ds_read_b128 v[140:143], v196 offset:2048
	ds_read_b128 v[144:147], v186 offset:4096
	ds_read_b128 v[148:151], v196 offset:4096
	ds_read_b128 v[152:155], v186 offset:6144
	ds_read_b128 v[156:159], v196 offset:6144
	s_add_u32 m0, s99, 0x4000
	s_nop 0
	global_load_lds_dwordx4 v203, s[42:43]
	s_add_u32 m0, s99, 0x6000
	s_nop 0
	global_load_lds_dwordx4 v204, s[42:43]
	s_waitcnt lgkmcnt(8)
	s_barrier
	s_waitcnt lgkmcnt(0)
	v_mfma_f32_16x16x32_bf16 v[112:115], v[128:131], v[160:163], v[112:115]
	v_mfma_f32_16x16x32_bf16 v[112:115], v[132:135], v[164:167], v[112:115]
	v_mfma_f32_16x16x32_bf16 v[116:119], v[128:131], v[168:171], v[116:119]
	v_mfma_f32_16x16x32_bf16 v[116:119], v[132:135], v[172:175], v[116:119]
	v_mfma_f32_16x16x32_bf16 v[120:123], v[136:139], v[160:163], v[120:123]
	v_mfma_f32_16x16x32_bf16 v[120:123], v[140:143], v[164:167], v[120:123]
	v_mfma_f32_16x16x32_bf16 v[124:127], v[136:139], v[168:171], v[124:127]
	v_mfma_f32_16x16x32_bf16 v[124:127], v[140:143], v[172:175], v[124:127]
	v_mfma_f32_16x16x32_bf16 v[96:99], v[144:147], v[160:163], v[96:99]
	v_mfma_f32_16x16x32_bf16 v[96:99], v[148:151], v[164:167], v[96:99]
	v_mfma_f32_16x16x32_bf16 v[100:103], v[144:147], v[168:171], v[100:103]
	v_mfma_f32_16x16x32_bf16 v[100:103], v[148:151], v[172:175], v[100:103]
	v_mfma_f32_16x16x32_bf16 v[104:107], v[152:155], v[160:163], v[104:107]
	v_mfma_f32_16x16x32_bf16 v[104:107], v[156:159], v[164:167], v[104:107]
	v_mfma_f32_16x16x32_bf16 v[108:111], v[152:155], v[168:171], v[108:111]
	v_mfma_f32_16x16x32_bf16 v[108:111], v[156:159], v[172:175], v[108:111]
	s_barrier
	ds_read_b128 v[176:179], v198 offset:16384
	ds_read_b128 v[180:183], v200 offset:16384
	ds_read_b128 v[188:191], v198 offset:18432
	ds_read_b128 v[192:195], v200 offset:18432
	s_add_u32 s40, s40, 0x80
	s_addc_u32 s41, s41, 0
	s_add_u32 m0, s99, 0x18000
	s_nop 0
	global_load_lds_dwordx4 v205, s[40:41]
	s_add_u32 m0, s99, 0x1a000
	s_nop 0
	global_load_lds_dwordx4 v206, s[40:41]
	s_barrier
	s_waitcnt lgkmcnt(0)
	v_mfma_f32_16x16x32_bf16 v[48:51], v[128:131], v[176:179], v[48:51]
	v_mfma_f32_16x16x32_bf16 v[48:51], v[132:135], v[180:183], v[48:51]
	v_mfma_f32_16x16x32_bf16 v[52:55], v[128:131], v[188:191], v[52:55]
	v_mfma_f32_16x16x32_bf16 v[52:55], v[132:135], v[192:195], v[52:55]
	v_mfma_f32_16x16x32_bf16 v[56:59], v[136:139], v[176:179], v[56:59]
	v_mfma_f32_16x16x32_bf16 v[56:59], v[140:143], v[180:183], v[56:59]
	v_mfma_f32_16x16x32_bf16 v[60:63], v[136:139], v[188:191], v[60:63]
	v_mfma_f32_16x16x32_bf16 v[60:63], v[140:143], v[192:195], v[60:63]
	v_mfma_f32_16x16x32_bf16 v[32:35], v[144:147], v[176:179], v[32:35]
	v_mfma_f32_16x16x32_bf16 v[32:35], v[148:151], v[180:183], v[32:35]
	v_mfma_f32_16x16x32_bf16 v[36:39], v[144:147], v[188:191], v[36:39]
	v_mfma_f32_16x16x32_bf16 v[36:39], v[148:151], v[192:195], v[36:39]
	v_mfma_f32_16x16x32_bf16 v[40:43], v[152:155], v[176:179], v[40:43]
	v_mfma_f32_16x16x32_bf16 v[40:43], v[156:159], v[180:183], v[40:43]
	v_mfma_f32_16x16x32_bf16 v[44:47], v[152:155], v[188:191], v[44:47]
	v_mfma_f32_16x16x32_bf16 v[44:47], v[156:159], v[192:195], v[44:47]
	s_barrier
	ds_read_b128 v[128:131], v186 offset:16384
	ds_read_b128 v[132:135], v196 offset:16384
	ds_read_b128 v[136:139], v186 offset:18432
	ds_read_b128 v[140:143], v196 offset:18432
	ds_read_b128 v[144:147], v186 offset:20480
	ds_read_b128 v[148:151], v196 offset:20480
	ds_read_b128 v[152:155], v186 offset:22528
	ds_read_b128 v[156:159], v196 offset:22528
	s_add_u32 s42, s42, 0x80
	s_addc_u32 s43, s43, 0
	s_add_u32 m0, s99, 0x10000
	s_nop 0
	global_load_lds_dwordx4 v201, s[42:43]
	s_add_u32 m0, s99, 0x12000
	s_nop 0
	global_load_lds_dwordx4 v202, s[42:43]
	s_barrier
	s_waitcnt lgkmcnt(0)
	v_mfma_f32_16x16x32_bf16 v[64:67], v[128:131], v[160:163], v[64:67]
	v_mfma_f32_16x16x32_bf16 v[64:67], v[132:135], v[164:167], v[64:67]
	v_mfma_f32_16x16x32_bf16 v[68:71], v[128:131], v[168:171], v[68:71]
	v_mfma_f32_16x16x32_bf16 v[68:71], v[132:135], v[172:175], v[68:71]
	v_mfma_f32_16x16x32_bf16 v[72:75], v[136:139], v[160:163], v[72:75]
	v_mfma_f32_16x16x32_bf16 v[72:75], v[140:143], v[164:167], v[72:75]
	v_mfma_f32_16x16x32_bf16 v[76:79], v[136:139], v[168:171], v[76:79]
	v_mfma_f32_16x16x32_bf16 v[76:79], v[140:143], v[172:175], v[76:79]
	v_mfma_f32_16x16x32_bf16 v[80:83], v[144:147], v[160:163], v[80:83]
	v_mfma_f32_16x16x32_bf16 v[80:83], v[148:151], v[164:167], v[80:83]
	v_mfma_f32_16x16x32_bf16 v[84:87], v[144:147], v[168:171], v[84:87]
	v_mfma_f32_16x16x32_bf16 v[84:87], v[148:151], v[172:175], v[84:87]
	v_mfma_f32_16x16x32_bf16 v[88:91], v[152:155], v[160:163], v[88:91]
	v_mfma_f32_16x16x32_bf16 v[88:91], v[156:159], v[164:167], v[88:91]
	v_mfma_f32_16x16x32_bf16 v[92:95], v[152:155], v[168:171], v[92:95]
	v_mfma_f32_16x16x32_bf16 v[92:95], v[156:159], v[172:175], v[92:95]
	s_barrier
	s_add_u32 m0, s99, 0x1c000
	s_nop 0
	global_load_lds_dwordx4 v210, s[40:41]
	s_add_u32 m0, s99, 0x1e000
	s_nop 0
	global_load_lds_dwordx4 v211, s[40:41]
	s_waitcnt vmcnt(6)
	s_barrier
	v_mfma_f32_16x16x32_bf16 v[16:19], v[128:131], v[176:179], v[16:19]
	v_mfma_f32_16x16x32_bf16 v[16:19], v[132:135], v[180:183], v[16:19]
	v_mfma_f32_16x16x32_bf16 v[20:23], v[128:131], v[188:191], v[20:23]
	v_mfma_f32_16x16x32_bf16 v[20:23], v[132:135], v[192:195], v[20:23]
	v_mfma_f32_16x16x32_bf16 v[24:27], v[136:139], v[176:179], v[24:27]
	v_mfma_f32_16x16x32_bf16 v[24:27], v[140:143], v[180:183], v[24:27]
	v_mfma_f32_16x16x32_bf16 v[28:31], v[136:139], v[188:191], v[28:31]
	v_mfma_f32_16x16x32_bf16 v[28:31], v[140:143], v[192:195], v[28:31]
	v_mfma_f32_16x16x32_bf16 v[0:3], v[144:147], v[176:179], v[0:3]
	v_mfma_f32_16x16x32_bf16 v[0:3], v[148:151], v[180:183], v[0:3]
	v_mfma_f32_16x16x32_bf16 v[4:7], v[144:147], v[188:191], v[4:7]
	v_mfma_f32_16x16x32_bf16 v[4:7], v[148:151], v[192:195], v[4:7]
	v_mfma_f32_16x16x32_bf16 v[8:11], v[152:155], v[176:179], v[8:11]
	v_mfma_f32_16x16x32_bf16 v[8:11], v[156:159], v[180:183], v[8:11]
	v_mfma_f32_16x16x32_bf16 v[12:15], v[152:155], v[188:191], v[12:15]
	v_mfma_f32_16x16x32_bf16 v[12:15], v[156:159], v[192:195], v[12:15]
	s_barrier
	s_sub_u32 s101, s101, 1
	s_cmp_lg_u32 s101, 0
	s_cbranch_scc1 .Lg8_p9_loop
	ds_read_b128 v[160:163], v197 offset:0
	ds_read_b128 v[164:167], v199 offset:0
	ds_read_b128 v[168:171], v197 offset:2048
	ds_read_b128 v[172:175], v199 offset:2048
	ds_read_b128 v[128:131], v184 offset:0
	ds_read_b128 v[132:135], v187 offset:0
	ds_read_b128 v[136:139], v184 offset:2048
	ds_read_b128 v[140:143], v187 offset:2048
	ds_read_b128 v[144:147], v184 offset:4096
	ds_read_b128 v[148:151], v187 offset:4096
	ds_read_b128 v[152:155], v184 offset:6144
	ds_read_b128 v[156:159], v187 offset:6144
	s_add_u32 m0, s99, 0x14000
	s_nop 0
	global_load_lds_dwordx4 v203, s[42:43]
	s_add_u32 m0, s99, 0x16000
	s_nop 0
	global_load_lds_dwordx4 v204, s[42:43]
	s_barrier
	s_waitcnt lgkmcnt(0)
	v_mfma_f32_16x16x32_bf16 v[112:115], v[128:131], v[160:163], v[112:115]
	v_mfma_f32_16x16x32_bf16 v[112:115], v[132:135], v[164:167], v[112:115]
	v_mfma_f32_16x16x32_bf16 v[116:119], v[128:131], v[168:171], v[116:119]
	v_mfma_f32_16x16x32_bf16 v[116:119], v[132:135], v[172:175], v[116:119]
	v_mfma_f32_16x16x32_bf16 v[120:123], v[136:139], v[160:163], v[120:123]
	v_mfma_f32_16x16x32_bf16 v[120:123], v[140:143], v[164:167], v[120:123]
	v_mfma_f32_16x16x32_bf16 v[124:127], v[136:139], v[168:171], v[124:127]
	v_mfma_f32_16x16x32_bf16 v[124:127], v[140:143], v[172:175], v[124:127]
	v_mfma_f32_16x16x32_bf16 v[96:99], v[144:147], v[160:163], v[96:99]
	v_mfma_f32_16x16x32_bf16 v[96:99], v[148:151], v[164:167], v[96:99]
	v_mfma_f32_16x16x32_bf16 v[100:103], v[144:147], v[168:171], v[100:103]
	v_mfma_f32_16x16x32_bf16 v[100:103], v[148:151], v[172:175], v[100:103]
	v_mfma_f32_16x16x32_bf16 v[104:107], v[152:155], v[160:163], v[104:107]
	v_mfma_f32_16x16x32_bf16 v[104:107], v[156:159], v[164:167], v[104:107]
	v_mfma_f32_16x16x32_bf16 v[108:111], v[152:155], v[168:171], v[108:111]
	v_mfma_f32_16x16x32_bf16 v[108:111], v[156:159], v[172:175], v[108:111]
	s_barrier
	ds_read_b128 v[176:179], v197 offset:16384
	ds_read_b128 v[180:183], v199 offset:16384
	ds_read_b128 v[188:191], v197 offset:18432
	ds_read_b128 v[192:195], v199 offset:18432
	s_barrier
	s_waitcnt lgkmcnt(0)
	v_mfma_f32_16x16x32_bf16 v[48:51], v[128:131], v[176:179], v[48:51]
	v_mfma_f32_16x16x32_bf16 v[48:51], v[132:135], v[180:183], v[48:51]
	v_mfma_f32_16x16x32_bf16 v[52:55], v[128:131], v[188:191], v[52:55]
	v_mfma_f32_16x16x32_bf16 v[52:55], v[132:135], v[192:195], v[52:55]
	v_mfma_f32_16x16x32_bf16 v[56:59], v[136:139], v[176:179], v[56:59]
	v_mfma_f32_16x16x32_bf16 v[56:59], v[140:143], v[180:183], v[56:59]
	v_mfma_f32_16x16x32_bf16 v[60:63], v[136:139], v[188:191], v[60:63]
	v_mfma_f32_16x16x32_bf16 v[60:63], v[140:143], v[192:195], v[60:63]
	v_mfma_f32_16x16x32_bf16 v[32:35], v[144:147], v[176:179], v[32:35]
	v_mfma_f32_16x16x32_bf16 v[32:35], v[148:151], v[180:183], v[32:35]
	v_mfma_f32_16x16x32_bf16 v[36:39], v[144:147], v[188:191], v[36:39]
	v_mfma_f32_16x16x32_bf16 v[36:39], v[148:151], v[192:195], v[36:39]
	v_mfma_f32_16x16x32_bf16 v[40:43], v[152:155], v[176:179], v[40:43]
	v_mfma_f32_16x16x32_bf16 v[40:43], v[156:159], v[180:183], v[40:43]
	v_mfma_f32_16x16x32_bf16 v[44:47], v[152:155], v[188:191], v[44:47]
	v_mfma_f32_16x16x32_bf16 v[44:47], v[156:159], v[192:195], v[44:47]
	s_barrier
	ds_read_b128 v[128:131], v184 offset:16384
	ds_read_b128 v[132:135], v187 offset:16384
	ds_read_b128 v[136:139], v184 offset:18432
	ds_read_b128 v[140:143], v187 offset:18432
	ds_read_b128 v[144:147], v184 offset:20480
	ds_read_b128 v[148:151], v187 offset:20480
	ds_read_b128 v[152:155], v184 offset:22528
	ds_read_b128 v[156:159], v187 offset:22528
	s_waitcnt vmcnt(4)
	s_barrier
	s_waitcnt lgkmcnt(0)
	v_mfma_f32_16x16x32_bf16 v[64:67], v[128:131], v[160:163], v[64:67]
	v_mfma_f32_16x16x32_bf16 v[64:67], v[132:135], v[164:167], v[64:67]
	v_mfma_f32_16x16x32_bf16 v[68:71], v[128:131], v[168:171], v[68:71]
	v_mfma_f32_16x16x32_bf16 v[68:71], v[132:135], v[172:175], v[68:71]
	v_mfma_f32_16x16x32_bf16 v[72:75], v[136:139], v[160:163], v[72:75]
	v_mfma_f32_16x16x32_bf16 v[72:75], v[140:143], v[164:167], v[72:75]
	v_mfma_f32_16x16x32_bf16 v[76:79], v[136:139], v[168:171], v[76:79]
	v_mfma_f32_16x16x32_bf16 v[76:79], v[140:143], v[172:175], v[76:79]
	v_mfma_f32_16x16x32_bf16 v[80:83], v[144:147], v[160:163], v[80:83]
	v_mfma_f32_16x16x32_bf16 v[80:83], v[148:151], v[164:167], v[80:83]
	v_mfma_f32_16x16x32_bf16 v[84:87], v[144:147], v[168:171], v[84:87]
	v_mfma_f32_16x16x32_bf16 v[84:87], v[148:151], v[172:175], v[84:87]
	v_mfma_f32_16x16x32_bf16 v[88:91], v[152:155], v[160:163], v[88:91]
	v_mfma_f32_16x16x32_bf16 v[88:91], v[156:159], v[164:167], v[88:91]
	v_mfma_f32_16x16x32_bf16 v[92:95], v[152:155], v[168:171], v[92:95]
	v_mfma_f32_16x16x32_bf16 v[92:95], v[156:159], v[172:175], v[92:95]
	v_mfma_f32_16x16x32_bf16 v[16:19], v[128:131], v[176:179], v[16:19]
	v_mfma_f32_16x16x32_bf16 v[16:19], v[132:135], v[180:183], v[16:19]
	v_mfma_f32_16x16x32_bf16 v[20:23], v[128:131], v[188:191], v[20:23]
	v_mfma_f32_16x16x32_bf16 v[20:23], v[132:135], v[192:195], v[20:23]
	v_mfma_f32_16x16x32_bf16 v[24:27], v[136:139], v[176:179], v[24:27]
	v_mfma_f32_16x16x32_bf16 v[24:27], v[140:143], v[180:183], v[24:27]
	v_mfma_f32_16x16x32_bf16 v[28:31], v[136:139], v[188:191], v[28:31]
	v_mfma_f32_16x16x32_bf16 v[28:31], v[140:143], v[192:195], v[28:31]
	v_mfma_f32_16x16x32_bf16 v[0:3], v[144:147], v[176:179], v[0:3]
	v_mfma_f32_16x16x32_bf16 v[0:3], v[148:151], v[180:183], v[0:3]
	v_mfma_f32_16x16x32_bf16 v[4:7], v[144:147], v[188:191], v[4:7]
	v_mfma_f32_16x16x32_bf16 v[4:7], v[148:151], v[192:195], v[4:7]
	v_mfma_f32_16x16x32_bf16 v[8:11], v[152:155], v[176:179], v[8:11]
	v_mfma_f32_16x16x32_bf16 v[8:11], v[156:159], v[180:183], v[8:11]
	v_mfma_f32_16x16x32_bf16 v[12:15], v[152:155], v[188:191], v[12:15]
	v_mfma_f32_16x16x32_bf16 v[12:15], v[156:159], v[192:195], v[12:15]
	s_barrier
	ds_read_b128 v[160:163], v198 offset:0
	ds_read_b128 v[164:167], v200 offset:0
	ds_read_b128 v[168:171], v198 offset:2048
	ds_read_b128 v[172:175], v200 offset:2048
	ds_read_b128 v[128:131], v186 offset:0
	ds_read_b128 v[132:135], v196 offset:0
	ds_read_b128 v[136:139], v186 offset:2048
	ds_read_b128 v[140:143], v196 offset:2048
	ds_read_b128 v[144:147], v186 offset:4096
	ds_read_b128 v[148:151], v196 offset:4096
	ds_read_b128 v[152:155], v186 offset:6144
	ds_read_b128 v[156:159], v196 offset:6144
	s_waitcnt vmcnt(2)
	s_barrier
	s_waitcnt lgkmcnt(0)
	v_mfma_f32_16x16x32_bf16 v[112:115], v[128:131], v[160:163], v[112:115]
	v_mfma_f32_16x16x32_bf16 v[112:115], v[132:135], v[164:167], v[112:115]
	v_mfma_f32_16x16x32_bf16 v[116:119], v[128:131], v[168:171], v[116:119]
	v_mfma_f32_16x16x32_bf16 v[116:119], v[132:135], v[172:175], v[116:119]
	v_mfma_f32_16x16x32_bf16 v[120:123], v[136:139], v[160:163], v[120:123]
	v_mfma_f32_16x16x32_bf16 v[120:123], v[140:143], v[164:167], v[120:123]
	v_mfma_f32_16x16x32_bf16 v[124:127], v[136:139], v[168:171], v[124:127]
	v_mfma_f32_16x16x32_bf16 v[124:127], v[140:143], v[172:175], v[124:127]
	v_mfma_f32_16x16x32_bf16 v[96:99], v[144:147], v[160:163], v[96:99]
	v_mfma_f32_16x16x32_bf16 v[96:99], v[148:151], v[164:167], v[96:99]
	v_mfma_f32_16x16x32_bf16 v[100:103], v[144:147], v[168:171], v[100:103]
	v_mfma_f32_16x16x32_bf16 v[100:103], v[148:151], v[172:175], v[100:103]
	v_mfma_f32_16x16x32_bf16 v[104:107], v[152:155], v[160:163], v[104:107]
	v_mfma_f32_16x16x32_bf16 v[104:107], v[156:159], v[164:167], v[104:107]
	v_mfma_f32_16x16x32_bf16 v[108:111], v[152:155], v[168:171], v[108:111]
	v_mfma_f32_16x16x32_bf16 v[108:111], v[156:159], v[172:175], v[108:111]
	s_barrier
	ds_read_b128 v[176:179], v198 offset:16384
	ds_read_b128 v[180:183], v200 offset:16384
	ds_read_b128 v[188:191], v198 offset:18432
	ds_read_b128 v[192:195], v200 offset:18432
	s_waitcnt vmcnt(0)
	s_barrier
	s_waitcnt lgkmcnt(0)
	v_mfma_f32_16x16x32_bf16 v[48:51], v[128:131], v[176:179], v[48:51]
	v_mfma_f32_16x16x32_bf16 v[48:51], v[132:135], v[180:183], v[48:51]
	v_mfma_f32_16x16x32_bf16 v[52:55], v[128:131], v[188:191], v[52:55]
	v_mfma_f32_16x16x32_bf16 v[52:55], v[132:135], v[192:195], v[52:55]
	v_mfma_f32_16x16x32_bf16 v[56:59], v[136:139], v[176:179], v[56:59]
	v_mfma_f32_16x16x32_bf16 v[56:59], v[140:143], v[180:183], v[56:59]
	v_mfma_f32_16x16x32_bf16 v[60:63], v[136:139], v[188:191], v[60:63]
	v_mfma_f32_16x16x32_bf16 v[60:63], v[140:143], v[192:195], v[60:63]
	v_mfma_f32_16x16x32_bf16 v[32:35], v[144:147], v[176:179], v[32:35]
	v_mfma_f32_16x16x32_bf16 v[32:35], v[148:151], v[180:183], v[32:35]
	v_mfma_f32_16x16x32_bf16 v[36:39], v[144:147], v[188:191], v[36:39]
	v_mfma_f32_16x16x32_bf16 v[36:39], v[148:151], v[192:195], v[36:39]
	v_mfma_f32_16x16x32_bf16 v[40:43], v[152:155], v[176:179], v[40:43]
	v_mfma_f32_16x16x32_bf16 v[40:43], v[156:159], v[180:183], v[40:43]
	v_mfma_f32_16x16x32_bf16 v[44:47], v[152:155], v[188:191], v[44:47]
	v_mfma_f32_16x16x32_bf16 v[44:47], v[156:159], v[192:195], v[44:47]
	s_barrier
	ds_read_b128 v[128:131], v186 offset:16384
	ds_read_b128 v[132:135], v196 offset:16384
	ds_read_b128 v[136:139], v186 offset:18432
	ds_read_b128 v[140:143], v196 offset:18432
	ds_read_b128 v[144:147], v186 offset:20480
	ds_read_b128 v[148:151], v196 offset:20480
	ds_read_b128 v[152:155], v186 offset:22528
	ds_read_b128 v[156:159], v196 offset:22528
	s_barrier
	s_waitcnt lgkmcnt(0)
	v_mfma_f32_16x16x32_bf16 v[64:67], v[128:131], v[160:163], v[64:67]
	v_mfma_f32_16x16x32_bf16 v[64:67], v[132:135], v[164:167], v[64:67]
	v_mfma_f32_16x16x32_bf16 v[68:71], v[128:131], v[168:171], v[68:71]
	v_mfma_f32_16x16x32_bf16 v[68:71], v[132:135], v[172:175], v[68:71]
	v_mfma_f32_16x16x32_bf16 v[72:75], v[136:139], v[160:163], v[72:75]
	v_mfma_f32_16x16x32_bf16 v[72:75], v[140:143], v[164:167], v[72:75]
	v_mfma_f32_16x16x32_bf16 v[76:79], v[136:139], v[168:171], v[76:79]
	v_mfma_f32_16x16x32_bf16 v[76:79], v[140:143], v[172:175], v[76:79]
	v_mfma_f32_16x16x32_bf16 v[80:83], v[144:147], v[160:163], v[80:83]
	v_mfma_f32_16x16x32_bf16 v[80:83], v[148:151], v[164:167], v[80:83]
	v_mfma_f32_16x16x32_bf16 v[84:87], v[144:147], v[168:171], v[84:87]
	v_mfma_f32_16x16x32_bf16 v[84:87], v[148:151], v[172:175], v[84:87]
	v_mfma_f32_16x16x32_bf16 v[88:91], v[152:155], v[160:163], v[88:91]
	v_mfma_f32_16x16x32_bf16 v[88:91], v[156:159], v[164:167], v[88:91]
	v_mfma_f32_16x16x32_bf16 v[92:95], v[152:155], v[168:171], v[92:95]
	v_mfma_f32_16x16x32_bf16 v[92:95], v[156:159], v[172:175], v[92:95]
	v_mfma_f32_16x16x32_bf16 v[16:19], v[128:131], v[176:179], v[16:19]
	v_mfma_f32_16x16x32_bf16 v[16:19], v[132:135], v[180:183], v[16:19]
	v_mfma_f32_16x16x32_bf16 v[20:23], v[128:131], v[188:191], v[20:23]
	v_mfma_f32_16x16x32_bf16 v[20:23], v[132:135], v[192:195], v[20:23]
	v_mfma_f32_16x16x32_bf16 v[24:27], v[136:139], v[176:179], v[24:27]
	v_mfma_f32_16x16x32_bf16 v[24:27], v[140:143], v[180:183], v[24:27]
	v_mfma_f32_16x16x32_bf16 v[28:31], v[136:139], v[188:191], v[28:31]
	v_mfma_f32_16x16x32_bf16 v[28:31], v[140:143], v[192:195], v[28:31]
	v_mfma_f32_16x16x32_bf16 v[0:3], v[144:147], v[176:179], v[0:3]
	v_mfma_f32_16x16x32_bf16 v[0:3], v[148:151], v[180:183], v[0:3]
	v_mfma_f32_16x16x32_bf16 v[4:7], v[144:147], v[188:191], v[4:7]
	v_mfma_f32_16x16x32_bf16 v[4:7], v[148:151], v[192:195], v[4:7]
	v_mfma_f32_16x16x32_bf16 v[8:11], v[152:155], v[176:179], v[8:11]
	v_mfma_f32_16x16x32_bf16 v[8:11], v[156:159], v[180:183], v[8:11]
	v_mfma_f32_16x16x32_bf16 v[12:15], v[152:155], v[188:191], v[12:15]
	v_mfma_f32_16x16x32_bf16 v[12:15], v[156:159], v[192:195], v[12:15]
	s_barrier
	s_cmp_lg_u32 s100, 0
	s_cbranch_scc1 .Lg8_p9_gb1
	s_barrier
